# K-loop back-edge rotation (7.11 simple form): counter, pointer advance and exit test hoisted above the loop-closing barrier
# speedup vs baseline: 1.0009x; 1.0000x over previous
.Lprio_skip0:
.LBB0_165:
	ds_read_b128 v[148:151], v141
	ds_read_b128 v[152:155], v141 offset:1024
	ds_read_b128 v[156:159], v141 offset:2048
	ds_read_b128 v[160:163], v141 offset:3072
	ds_read_b128 v[164:167], v142
	ds_read_b128 v[168:171], v142 offset:1024
	ds_read_b128 v[172:175], v142 offset:2048
	ds_read_b128 v[176:179], v142 offset:3072
	s_add_u32 s14, s10, s12
	s_addc_u32 s15, s11, s13
	s_add_u32 s14, s14, 0x11200100
	s_addc_u32 s15, s15, 0
	s_add_u32 s47, s34, s12
	s_addc_u32 s50, s35, s13
	s_cmpk_eq_i32 s12, 0xf00
	s_cselect_b32 s17, s7, s15
	s_cselect_b32 s16, s6, s14
	s_cselect_b32 s15, s3, s50
	s_cselect_b32 s14, s2, s47
	s_mov_b32 m0, s37
	v_lshl_add_u64 v[212:213], v[136:137], 0, s[12:13]
	ds_read_b128 v[180:183], v143
	ds_read_b128 v[184:187], v143 offset:1024
	ds_read_b128 v[188:191], v143 offset:2048
	ds_read_b128 v[192:195], v143 offset:3072
	ds_read_b128 v[196:199], v143 offset:4096
	ds_read_b128 v[200:203], v143 offset:5120
	ds_read_b128 v[204:207], v143 offset:6144
	ds_read_b128 v[208:211], v143 offset:7168
	global_load_lds_dwordx4 v[212:213], off
	v_lshl_add_u64 v[212:213], v[138:139], 0, s[12:13]
	s_mov_b32 m0, s38
	s_nop 0
	global_load_lds_dwordx4 v[212:213], off
	s_waitcnt vmcnt(8)
	s_waitcnt lgkmcnt(0)
	s_barrier
	s_waitcnt lgkmcnt(0)
	v_mfma_f32_16x16x32_bf16 v[124:127], v[148:151], v[180:183], v[124:127]
	v_mfma_f32_16x16x32_bf16 v[120:123], v[156:159], v[180:183], v[120:123]
	v_mfma_f32_16x16x32_bf16 v[108:111], v[148:151], v[188:191], v[108:111]
	v_mfma_f32_16x16x32_bf16 v[104:107], v[156:159], v[188:191], v[104:107]
	v_mfma_f32_16x16x32_bf16 v[92:95], v[148:151], v[196:199], v[92:95]
	v_mfma_f32_16x16x32_bf16 v[88:91], v[156:159], v[196:199], v[88:91]
	v_mfma_f32_16x16x32_bf16 v[76:79], v[148:151], v[204:207], v[76:79]
	v_mfma_f32_16x16x32_bf16 v[72:75], v[156:159], v[204:207], v[72:75]
	v_mfma_f32_16x16x32_bf16 v[124:127], v[152:155], v[184:187], v[124:127]
	v_mfma_f32_16x16x32_bf16 v[120:123], v[160:163], v[184:187], v[120:123]
	v_mfma_f32_16x16x32_bf16 v[108:111], v[152:155], v[192:195], v[108:111]
	v_mfma_f32_16x16x32_bf16 v[104:107], v[160:163], v[192:195], v[104:107]
	v_mfma_f32_16x16x32_bf16 v[92:95], v[152:155], v[200:203], v[92:95]
	v_mfma_f32_16x16x32_bf16 v[88:91], v[160:163], v[200:203], v[88:91]
	v_mfma_f32_16x16x32_bf16 v[76:79], v[152:155], v[208:211], v[76:79]
	v_mfma_f32_16x16x32_bf16 v[72:75], v[160:163], v[208:211], v[72:75]
	v_mfma_f32_16x16x32_bf16 v[116:119], v[164:167], v[180:183], v[116:119]
	v_mfma_f32_16x16x32_bf16 v[112:115], v[172:175], v[180:183], v[112:115]
	v_mfma_f32_16x16x32_bf16 v[100:103], v[164:167], v[188:191], v[100:103]
	v_mfma_f32_16x16x32_bf16 v[96:99], v[172:175], v[188:191], v[96:99]
	v_mfma_f32_16x16x32_bf16 v[84:87], v[164:167], v[196:199], v[84:87]
	v_mfma_f32_16x16x32_bf16 v[80:83], v[172:175], v[196:199], v[80:83]
	v_mfma_f32_16x16x32_bf16 v[68:71], v[164:167], v[204:207], v[68:71]
	v_mfma_f32_16x16x32_bf16 v[64:67], v[172:175], v[204:207], v[64:67]
	v_mfma_f32_16x16x32_bf16 v[116:119], v[168:171], v[184:187], v[116:119]
	v_mfma_f32_16x16x32_bf16 v[112:115], v[176:179], v[184:187], v[112:115]
	v_mfma_f32_16x16x32_bf16 v[100:103], v[168:171], v[192:195], v[100:103]
	v_mfma_f32_16x16x32_bf16 v[96:99], v[176:179], v[192:195], v[96:99]
	v_mfma_f32_16x16x32_bf16 v[84:87], v[168:171], v[200:203], v[84:87]
	v_mfma_f32_16x16x32_bf16 v[80:83], v[176:179], v[200:203], v[80:83]
	v_mfma_f32_16x16x32_bf16 v[68:71], v[168:171], v[208:211], v[68:71]
	v_mfma_f32_16x16x32_bf16 v[64:67], v[176:179], v[208:211], v[64:67]
	s_barrier
	s_mov_b32 m0, s39
	v_lshl_add_u64 v[212:213], s[14:15], 0, v[130:131]
	s_add_u32 s50, s14, 0x80000
	ds_read_b128 v[180:183], v143 offset:16384
	ds_read_b128 v[184:187], v143 offset:17408
	ds_read_b128 v[188:191], v143 offset:18432
	ds_read_b128 v[192:195], v143 offset:19456
	ds_read_b128 v[196:199], v143 offset:20480
	ds_read_b128 v[200:203], v143 offset:21504
	ds_read_b128 v[204:207], v143 offset:22528
	ds_read_b128 v[208:211], v143 offset:23552
	global_load_lds_dwordx4 v[212:213], off
	v_lshl_add_u64 v[214:215], s[14:15], 0, v[134:135]
	s_mov_b32 m0, s40
	s_addc_u32 s51, s15, 0
	global_load_lds_dwordx4 v[214:215], off
	v_lshl_add_u64 v[216:217], s[50:51], 0, v[130:131]
	s_mov_b32 m0, s41
	v_lshl_add_u64 v[218:219], s[16:17], 0, v[132:133]
	global_load_lds_dwordx4 v[216:217], off
	v_lshl_add_u64 v[216:217], s[50:51], 0, v[134:135]
	s_mov_b32 m0, s42
	s_nop 0
	global_load_lds_dwordx4 v[216:217], off
	v_lshl_add_u64 v[216:217], s[16:17], 0, v[128:129]
	s_mov_b32 m0, s23
	s_nop 0
	global_load_lds_dwordx4 v[216:217], off
	s_mov_b32 m0, s27
	s_nop 0
	global_load_lds_dwordx4 v[218:219], off
	s_waitcnt vmcnt(8)
	s_waitcnt lgkmcnt(0)
	s_barrier
	s_waitcnt lgkmcnt(0)
	v_mfma_f32_16x16x32_bf16 v[60:63], v[148:151], v[180:183], v[60:63]
	v_mfma_f32_16x16x32_bf16 v[56:59], v[156:159], v[180:183], v[56:59]
	v_mfma_f32_16x16x32_bf16 v[44:47], v[148:151], v[188:191], v[44:47]
	v_mfma_f32_16x16x32_bf16 v[40:43], v[156:159], v[188:191], v[40:43]
	v_mfma_f32_16x16x32_bf16 v[28:31], v[148:151], v[196:199], v[28:31]
	v_mfma_f32_16x16x32_bf16 v[24:27], v[156:159], v[196:199], v[24:27]
	v_mfma_f32_16x16x32_bf16 v[12:15], v[148:151], v[204:207], v[12:15]
	v_mfma_f32_16x16x32_bf16 v[8:11], v[156:159], v[204:207], v[8:11]
	v_mfma_f32_16x16x32_bf16 v[60:63], v[152:155], v[184:187], v[60:63]
	v_mfma_f32_16x16x32_bf16 v[56:59], v[160:163], v[184:187], v[56:59]
	v_mfma_f32_16x16x32_bf16 v[44:47], v[152:155], v[192:195], v[44:47]
	v_mfma_f32_16x16x32_bf16 v[40:43], v[160:163], v[192:195], v[40:43]
	v_mfma_f32_16x16x32_bf16 v[28:31], v[152:155], v[200:203], v[28:31]
	v_mfma_f32_16x16x32_bf16 v[24:27], v[160:163], v[200:203], v[24:27]
	v_mfma_f32_16x16x32_bf16 v[12:15], v[152:155], v[208:211], v[12:15]
	v_mfma_f32_16x16x32_bf16 v[8:11], v[160:163], v[208:211], v[8:11]
	v_mfma_f32_16x16x32_bf16 v[52:55], v[164:167], v[180:183], v[52:55]
	v_mfma_f32_16x16x32_bf16 v[48:51], v[172:175], v[180:183], v[48:51]
	v_mfma_f32_16x16x32_bf16 v[36:39], v[164:167], v[188:191], v[36:39]
	v_mfma_f32_16x16x32_bf16 v[32:35], v[172:175], v[188:191], v[32:35]
	v_mfma_f32_16x16x32_bf16 v[20:23], v[164:167], v[196:199], v[20:23]
	v_mfma_f32_16x16x32_bf16 v[16:19], v[172:175], v[196:199], v[16:19]
	v_mfma_f32_16x16x32_bf16 v[4:7], v[164:167], v[204:207], v[4:7]
	v_mfma_f32_16x16x32_bf16 v[0:3], v[172:175], v[204:207], v[0:3]
	v_mfma_f32_16x16x32_bf16 v[52:55], v[168:171], v[184:187], v[52:55]
	v_mfma_f32_16x16x32_bf16 v[48:51], v[176:179], v[184:187], v[48:51]
	v_mfma_f32_16x16x32_bf16 v[36:39], v[168:171], v[192:195], v[36:39]
	v_mfma_f32_16x16x32_bf16 v[32:35], v[176:179], v[192:195], v[32:35]
	v_mfma_f32_16x16x32_bf16 v[20:23], v[168:171], v[200:203], v[20:23]
	v_mfma_f32_16x16x32_bf16 v[16:19], v[176:179], v[200:203], v[16:19]
	v_mfma_f32_16x16x32_bf16 v[4:7], v[168:171], v[208:211], v[4:7]
	v_mfma_f32_16x16x32_bf16 v[0:3], v[176:179], v[208:211], v[0:3]
	s_barrier
	ds_read_b128 v[148:151], v145
	ds_read_b128 v[152:155], v145 offset:1024
	ds_read_b128 v[156:159], v145 offset:2048
	ds_read_b128 v[160:163], v145 offset:3072
	ds_read_b128 v[164:167], v146
	ds_read_b128 v[168:171], v146 offset:1024
	ds_read_b128 v[172:175], v146 offset:2048
	ds_read_b128 v[176:179], v146 offset:3072
	s_add_u32 s16, s16, 0x80000
	s_addc_u32 s17, s17, 0
	s_mov_b32 m0, s28
	v_lshl_add_u64 v[220:221], s[16:17], 0, v[128:129]
	ds_read_b128 v[180:183], v143 offset:32768
	ds_read_b128 v[184:187], v143 offset:33792
	ds_read_b128 v[188:191], v143 offset:34816
	ds_read_b128 v[192:195], v143 offset:35840
	ds_read_b128 v[196:199], v143 offset:36864
	ds_read_b128 v[200:203], v143 offset:37888
	ds_read_b128 v[204:207], v143 offset:38912
	ds_read_b128 v[208:211], v143 offset:39936
	global_load_lds_dwordx4 v[220:221], off
	v_lshl_add_u64 v[220:221], s[16:17], 0, v[132:133]
	s_mov_b32 m0, s29
	s_nop 0
	global_load_lds_dwordx4 v[220:221], off
	s_waitcnt vmcnt(8)
	s_waitcnt lgkmcnt(0)
	s_barrier
	s_waitcnt lgkmcnt(0)
	v_mfma_f32_16x16x32_bf16 v[124:127], v[148:151], v[180:183], v[124:127]
	v_mfma_f32_16x16x32_bf16 v[120:123], v[156:159], v[180:183], v[120:123]
	v_mfma_f32_16x16x32_bf16 v[108:111], v[148:151], v[188:191], v[108:111]
	v_mfma_f32_16x16x32_bf16 v[104:107], v[156:159], v[188:191], v[104:107]
	v_mfma_f32_16x16x32_bf16 v[92:95], v[148:151], v[196:199], v[92:95]
	v_mfma_f32_16x16x32_bf16 v[88:91], v[156:159], v[196:199], v[88:91]
	v_mfma_f32_16x16x32_bf16 v[76:79], v[148:151], v[204:207], v[76:79]
	v_mfma_f32_16x16x32_bf16 v[72:75], v[156:159], v[204:207], v[72:75]
	v_mfma_f32_16x16x32_bf16 v[124:127], v[152:155], v[184:187], v[124:127]
	v_mfma_f32_16x16x32_bf16 v[120:123], v[160:163], v[184:187], v[120:123]
	v_mfma_f32_16x16x32_bf16 v[108:111], v[152:155], v[192:195], v[108:111]
	v_mfma_f32_16x16x32_bf16 v[104:107], v[160:163], v[192:195], v[104:107]
	v_mfma_f32_16x16x32_bf16 v[92:95], v[152:155], v[200:203], v[92:95]
	v_mfma_f32_16x16x32_bf16 v[88:91], v[160:163], v[200:203], v[88:91]
	v_mfma_f32_16x16x32_bf16 v[76:79], v[152:155], v[208:211], v[76:79]
	v_mfma_f32_16x16x32_bf16 v[72:75], v[160:163], v[208:211], v[72:75]
	v_mfma_f32_16x16x32_bf16 v[116:119], v[164:167], v[180:183], v[116:119]
	v_mfma_f32_16x16x32_bf16 v[112:115], v[172:175], v[180:183], v[112:115]
	v_mfma_f32_16x16x32_bf16 v[100:103], v[164:167], v[188:191], v[100:103]
	v_mfma_f32_16x16x32_bf16 v[96:99], v[172:175], v[188:191], v[96:99]
	v_mfma_f32_16x16x32_bf16 v[84:87], v[164:167], v[196:199], v[84:87]
	v_mfma_f32_16x16x32_bf16 v[80:83], v[172:175], v[196:199], v[80:83]
	v_mfma_f32_16x16x32_bf16 v[68:71], v[164:167], v[204:207], v[68:71]
	v_mfma_f32_16x16x32_bf16 v[64:67], v[172:175], v[204:207], v[64:67]
	v_mfma_f32_16x16x32_bf16 v[116:119], v[168:171], v[184:187], v[116:119]
	v_mfma_f32_16x16x32_bf16 v[112:115], v[176:179], v[184:187], v[112:115]
	v_mfma_f32_16x16x32_bf16 v[100:103], v[168:171], v[192:195], v[100:103]
	v_mfma_f32_16x16x32_bf16 v[96:99], v[176:179], v[192:195], v[96:99]
	v_mfma_f32_16x16x32_bf16 v[84:87], v[168:171], v[200:203], v[84:87]
	v_mfma_f32_16x16x32_bf16 v[80:83], v[176:179], v[200:203], v[80:83]
	v_mfma_f32_16x16x32_bf16 v[68:71], v[168:171], v[208:211], v[68:71]
	v_mfma_f32_16x16x32_bf16 v[64:67], v[176:179], v[208:211], v[64:67]
	s_barrier
	s_mov_b32 m0, s43
	v_lshl_add_u64 v[212:213], v[212:213], 0, s[8:9]
	s_add_u32 s14, s14, 0x80080
	ds_read_b128 v[180:183], v143 offset:49152
	ds_read_b128 v[184:187], v143 offset:50176
	ds_read_b128 v[188:191], v143 offset:51200
	ds_read_b128 v[192:195], v143 offset:52224
	ds_read_b128 v[196:199], v143 offset:53248
	ds_read_b128 v[200:203], v143 offset:54272
	ds_read_b128 v[204:207], v143 offset:55296
	ds_read_b128 v[208:211], v143 offset:56320
	global_load_lds_dwordx4 v[212:213], off
	v_lshl_add_u64 v[212:213], v[214:215], 0, s[8:9]
	s_mov_b32 m0, s44
	s_addc_u32 s15, s15, 0
	global_load_lds_dwordx4 v[212:213], off
	v_lshl_add_u64 v[212:213], s[14:15], 0, v[130:131]
	s_mov_b32 m0, s45
	s_nop 0
	global_load_lds_dwordx4 v[212:213], off
	v_lshl_add_u64 v[212:213], s[14:15], 0, v[134:135]
	s_mov_b32 m0, s46
	s_nop 0
	global_load_lds_dwordx4 v[212:213], off
	v_lshl_add_u64 v[212:213], v[216:217], 0, s[8:9]
	s_mov_b32 m0, s30
	s_nop 0
	global_load_lds_dwordx4 v[212:213], off
	v_lshl_add_u64 v[212:213], v[218:219], 0, s[8:9]
	s_mov_b32 m0, s31
	s_nop 0
	global_load_lds_dwordx4 v[212:213], off
	s_waitcnt vmcnt(8)
	s_waitcnt lgkmcnt(0)
	s_barrier
	s_waitcnt lgkmcnt(0)
	v_mfma_f32_16x16x32_bf16 v[60:63], v[148:151], v[180:183], v[60:63]
	v_mfma_f32_16x16x32_bf16 v[56:59], v[156:159], v[180:183], v[56:59]
	v_mfma_f32_16x16x32_bf16 v[44:47], v[148:151], v[188:191], v[44:47]
	v_mfma_f32_16x16x32_bf16 v[40:43], v[156:159], v[188:191], v[40:43]
	v_mfma_f32_16x16x32_bf16 v[28:31], v[148:151], v[196:199], v[28:31]
	v_mfma_f32_16x16x32_bf16 v[24:27], v[156:159], v[196:199], v[24:27]
	v_mfma_f32_16x16x32_bf16 v[12:15], v[148:151], v[204:207], v[12:15]
	v_mfma_f32_16x16x32_bf16 v[8:11], v[156:159], v[204:207], v[8:11]
	v_mfma_f32_16x16x32_bf16 v[60:63], v[152:155], v[184:187], v[60:63]
	v_mfma_f32_16x16x32_bf16 v[56:59], v[160:163], v[184:187], v[56:59]
	v_mfma_f32_16x16x32_bf16 v[44:47], v[152:155], v[192:195], v[44:47]
	v_mfma_f32_16x16x32_bf16 v[40:43], v[160:163], v[192:195], v[40:43]
	v_mfma_f32_16x16x32_bf16 v[28:31], v[152:155], v[200:203], v[28:31]
	v_mfma_f32_16x16x32_bf16 v[24:27], v[160:163], v[200:203], v[24:27]
	v_mfma_f32_16x16x32_bf16 v[12:15], v[152:155], v[208:211], v[12:15]
	v_mfma_f32_16x16x32_bf16 v[8:11], v[160:163], v[208:211], v[8:11]
	v_mfma_f32_16x16x32_bf16 v[52:55], v[164:167], v[180:183], v[52:55]
	v_mfma_f32_16x16x32_bf16 v[48:51], v[172:175], v[180:183], v[48:51]
	v_mfma_f32_16x16x32_bf16 v[36:39], v[164:167], v[188:191], v[36:39]
	v_mfma_f32_16x16x32_bf16 v[32:35], v[172:175], v[188:191], v[32:35]
	v_mfma_f32_16x16x32_bf16 v[20:23], v[164:167], v[196:199], v[20:23]
	v_mfma_f32_16x16x32_bf16 v[16:19], v[172:175], v[196:199], v[16:19]
	v_mfma_f32_16x16x32_bf16 v[4:7], v[164:167], v[204:207], v[4:7]
	v_mfma_f32_16x16x32_bf16 v[0:3], v[172:175], v[204:207], v[0:3]
	v_mfma_f32_16x16x32_bf16 v[52:55], v[168:171], v[184:187], v[52:55]
	v_mfma_f32_16x16x32_bf16 v[48:51], v[176:179], v[184:187], v[48:51]
	v_mfma_f32_16x16x32_bf16 v[36:39], v[168:171], v[192:195], v[36:39]
	v_mfma_f32_16x16x32_bf16 v[32:35], v[176:179], v[192:195], v[32:35]
	v_mfma_f32_16x16x32_bf16 v[20:23], v[168:171], v[200:203], v[20:23]
	v_mfma_f32_16x16x32_bf16 v[16:19], v[176:179], v[200:203], v[16:19]
	v_mfma_f32_16x16x32_bf16 v[4:7], v[168:171], v[208:211], v[4:7]
	v_mfma_f32_16x16x32_bf16 v[0:3], v[176:179], v[208:211], v[0:3]
	s_add_i32 s36, s36, 2
	s_add_u32 s12, s12, 0x100
	s_addc_u32 s13, s13, 0
	s_cmp_gt_u32 s36, 29
	s_barrier
	s_cbranch_scc0 .LBB0_165
	s_setprio 0
	s_cmpk_lt_u32 s33, 0x100
	s_cbranch_scc0 .LBB0_168
	s_barrier

.Lprio_skip1:
.LBB0_254:
	ds_read_b128 v[40:43], v176
	ds_read_b128 v[44:47], v176 offset:1024
	ds_read_b128 v[48:51], v176 offset:2048
	ds_read_b128 v[52:55], v176 offset:3072
	ds_read_b128 v[162:165], v177
	ds_read_b128 v[166:169], v177 offset:1024
	ds_read_b128 v[170:173], v177 offset:2048
	ds_read_b128 v[194:197], v177 offset:3072
	s_add_u32 s2, s0, 0xfff80080
	s_addc_u32 s3, s1, -1
	s_cmp_eq_u32 s77, 28
	s_cselect_b32 s47, s61, s3
	s_cselect_b32 s46, s72, s2
	s_cselect_b32 s3, s73, s76
	s_cselect_b32 s2, s74, s75
	v_lshl_add_u64 v[174:175], s[0:1], 0, v[156:157]
	s_add_i32 m0, s7, 0xc000
	ds_read_b128 v[198:201], v178
	ds_read_b128 v[202:205], v178 offset:1024
	ds_read_b128 v[206:209], v178 offset:2048
	ds_read_b128 v[210:213], v178 offset:3072
	ds_read_b128 v[214:217], v178 offset:4096
	ds_read_b128 v[218:221], v178 offset:5120
	ds_read_b128 v[222:225], v178 offset:6144
	ds_read_b128 v[226:229], v178 offset:7168
	global_load_lds_dwordx4 v[174:175], off
	v_lshl_add_u64 v[174:175], s[0:1], 0, v[160:161]
	s_add_i32 m0, s7, 0xe000
	s_nop 0
	global_load_lds_dwordx4 v[174:175], off
	s_waitcnt vmcnt(8)
	s_waitcnt lgkmcnt(0)
	s_barrier
	s_waitcnt lgkmcnt(0)
	v_mfma_f32_16x16x32_bf16 v[140:143], v[40:43], v[198:201], v[140:143]
	v_mfma_f32_16x16x32_bf16 v[136:139], v[48:51], v[198:201], v[136:139]
	v_mfma_f32_16x16x32_bf16 v[124:127], v[40:43], v[206:209], v[124:127]
	v_mfma_f32_16x16x32_bf16 v[120:123], v[48:51], v[206:209], v[120:123]
	v_mfma_f32_16x16x32_bf16 v[108:111], v[40:43], v[214:217], v[108:111]
	v_mfma_f32_16x16x32_bf16 v[104:107], v[48:51], v[214:217], v[104:107]
	v_mfma_f32_16x16x32_bf16 v[92:95], v[40:43], v[222:225], v[92:95]
	v_mfma_f32_16x16x32_bf16 v[88:91], v[48:51], v[222:225], v[88:91]
	v_mfma_f32_16x16x32_bf16 v[140:143], v[44:47], v[202:205], v[140:143]
	v_mfma_f32_16x16x32_bf16 v[136:139], v[52:55], v[202:205], v[136:139]
	v_mfma_f32_16x16x32_bf16 v[124:127], v[44:47], v[210:213], v[124:127]
	v_mfma_f32_16x16x32_bf16 v[120:123], v[52:55], v[210:213], v[120:123]
	v_mfma_f32_16x16x32_bf16 v[108:111], v[44:47], v[218:221], v[108:111]
	v_mfma_f32_16x16x32_bf16 v[104:107], v[52:55], v[218:221], v[104:107]
	v_mfma_f32_16x16x32_bf16 v[92:95], v[44:47], v[226:229], v[92:95]
	v_mfma_f32_16x16x32_bf16 v[88:91], v[52:55], v[226:229], v[88:91]
	v_mfma_f32_16x16x32_bf16 v[132:135], v[162:165], v[198:201], v[132:135]
	v_mfma_f32_16x16x32_bf16 v[128:131], v[170:173], v[198:201], v[128:131]
	v_mfma_f32_16x16x32_bf16 v[116:119], v[162:165], v[206:209], v[116:119]
	v_mfma_f32_16x16x32_bf16 v[112:115], v[170:173], v[206:209], v[112:115]
	v_mfma_f32_16x16x32_bf16 v[100:103], v[162:165], v[214:217], v[100:103]
	v_mfma_f32_16x16x32_bf16 v[96:99], v[170:173], v[214:217], v[96:99]
	v_mfma_f32_16x16x32_bf16 v[84:87], v[162:165], v[222:225], v[84:87]
	v_mfma_f32_16x16x32_bf16 v[80:83], v[170:173], v[222:225], v[80:83]
	v_mfma_f32_16x16x32_bf16 v[132:135], v[166:169], v[202:205], v[132:135]
	v_mfma_f32_16x16x32_bf16 v[128:131], v[194:197], v[202:205], v[128:131]
	v_mfma_f32_16x16x32_bf16 v[116:119], v[166:169], v[210:213], v[116:119]
	v_mfma_f32_16x16x32_bf16 v[112:115], v[194:197], v[210:213], v[112:115]
	v_mfma_f32_16x16x32_bf16 v[100:103], v[166:169], v[218:221], v[100:103]
	v_mfma_f32_16x16x32_bf16 v[96:99], v[194:197], v[218:221], v[96:99]
	v_mfma_f32_16x16x32_bf16 v[84:87], v[166:169], v[226:229], v[84:87]
	v_mfma_f32_16x16x32_bf16 v[80:83], v[194:197], v[226:229], v[80:83]
	s_barrier
	s_add_i32 s78, s56, s66
	v_lshl_add_u64 v[174:175], s[2:3], 0, v[150:151]
	s_mov_b32 m0, s78
	ds_read_b128 v[198:201], v178 offset:16384
	ds_read_b128 v[202:205], v178 offset:17408
	ds_read_b128 v[206:209], v178 offset:18432
	ds_read_b128 v[210:213], v178 offset:19456
	ds_read_b128 v[214:217], v178 offset:20480
	ds_read_b128 v[218:221], v178 offset:21504
	ds_read_b128 v[222:225], v178 offset:22528
	ds_read_b128 v[226:229], v178 offset:23552
	global_load_lds_dwordx4 v[174:175], off
	s_add_i32 m0, s78, 0x2000
	s_add_u32 s78, s2, 0x80000
	v_lshl_add_u64 v[182:183], s[2:3], 0, v[154:155]
	s_addc_u32 s79, s3, 0
	s_add_i32 s80, s57, s66
	global_load_lds_dwordx4 v[182:183], off
	v_lshl_add_u64 v[230:231], s[78:79], 0, v[150:151]
	s_mov_b32 m0, s80
	v_lshl_add_u64 v[232:233], s[46:47], 0, v[152:153]
	global_load_lds_dwordx4 v[230:231], off
	v_lshl_add_u64 v[230:231], s[78:79], 0, v[154:155]
	s_add_i32 m0, s80, 0x2000
	s_nop 0
	global_load_lds_dwordx4 v[230:231], off
	v_lshl_add_u64 v[230:231], s[46:47], 0, v[148:149]
	s_mov_b32 m0, s7
	s_nop 0
	global_load_lds_dwordx4 v[230:231], off
	s_mov_b32 m0, s39
	s_nop 0
	global_load_lds_dwordx4 v[232:233], off
	s_waitcnt vmcnt(8)
	s_waitcnt lgkmcnt(0)
	s_barrier
	s_waitcnt lgkmcnt(0)
	v_mfma_f32_16x16x32_bf16 v[76:79], v[40:43], v[198:201], v[76:79]
	v_mfma_f32_16x16x32_bf16 v[72:75], v[48:51], v[198:201], v[72:75]
	v_mfma_f32_16x16x32_bf16 v[60:63], v[40:43], v[206:209], v[60:63]
	v_mfma_f32_16x16x32_bf16 v[56:59], v[48:51], v[206:209], v[56:59]
	v_mfma_f32_16x16x32_bf16 v[28:31], v[40:43], v[214:217], v[28:31]
	v_mfma_f32_16x16x32_bf16 v[24:27], v[48:51], v[214:217], v[24:27]
	v_mfma_f32_16x16x32_bf16 v[12:15], v[40:43], v[222:225], v[12:15]
	v_mfma_f32_16x16x32_bf16 v[8:11], v[48:51], v[222:225], v[8:11]
	v_mfma_f32_16x16x32_bf16 v[76:79], v[44:47], v[202:205], v[76:79]
	v_mfma_f32_16x16x32_bf16 v[72:75], v[52:55], v[202:205], v[72:75]
	v_mfma_f32_16x16x32_bf16 v[60:63], v[44:47], v[210:213], v[60:63]
	v_mfma_f32_16x16x32_bf16 v[56:59], v[52:55], v[210:213], v[56:59]
	v_mfma_f32_16x16x32_bf16 v[28:31], v[44:47], v[218:221], v[28:31]
	v_mfma_f32_16x16x32_bf16 v[24:27], v[52:55], v[218:221], v[24:27]
	v_mfma_f32_16x16x32_bf16 v[12:15], v[44:47], v[226:229], v[12:15]
	v_mfma_f32_16x16x32_bf16 v[8:11], v[52:55], v[226:229], v[8:11]
	v_mfma_f32_16x16x32_bf16 v[36:39], v[162:165], v[206:209], v[36:39]
	v_mfma_f32_16x16x32_bf16 v[32:35], v[170:173], v[206:209], v[32:35]
	v_mfma_f32_16x16x32_bf16 v[20:23], v[162:165], v[214:217], v[20:23]
	v_mfma_f32_16x16x32_bf16 v[16:19], v[170:173], v[214:217], v[16:19]
	v_mfma_f32_16x16x32_bf16 v[4:7], v[162:165], v[222:225], v[4:7]
	v_mfma_f32_16x16x32_bf16 v[0:3], v[170:173], v[222:225], v[0:3]
	v_mfma_f32_16x16x32_bf16 v[40:43], v[162:165], v[198:201], v[68:71]
	v_mfma_f32_16x16x32_bf16 v[44:47], v[170:173], v[198:201], v[64:67]
	v_mfma_f32_16x16x32_bf16 v[36:39], v[166:169], v[210:213], v[36:39]
	v_mfma_f32_16x16x32_bf16 v[32:35], v[194:197], v[210:213], v[32:35]
	v_mfma_f32_16x16x32_bf16 v[20:23], v[166:169], v[218:221], v[20:23]
	v_mfma_f32_16x16x32_bf16 v[16:19], v[194:197], v[218:221], v[16:19]
	v_mfma_f32_16x16x32_bf16 v[4:7], v[166:169], v[226:229], v[4:7]
	v_mfma_f32_16x16x32_bf16 v[0:3], v[194:197], v[226:229], v[0:3]
	v_mfma_f32_16x16x32_bf16 v[40:43], v[166:169], v[202:205], v[40:43]
	v_mfma_f32_16x16x32_bf16 v[44:47], v[194:197], v[202:205], v[44:47]
	s_barrier
	ds_read_b128 v[48:51], v179
	ds_read_b128 v[52:55], v179 offset:1024
	ds_read_b128 v[64:67], v179 offset:2048
	ds_read_b128 v[68:71], v179 offset:3072
	ds_read_b128 v[162:165], v180
	ds_read_b128 v[166:169], v180 offset:1024
	ds_read_b128 v[170:173], v180 offset:2048
	ds_read_b128 v[194:197], v180 offset:3072
	s_add_u32 s46, s46, 0x80000
	s_addc_u32 s47, s47, 0
	s_mov_b32 m0, s41
	v_lshl_add_u64 v[234:235], s[46:47], 0, v[148:149]
	ds_read_b128 v[198:201], v178 offset:32768
	ds_read_b128 v[202:205], v178 offset:33792
	ds_read_b128 v[206:209], v178 offset:34816
	ds_read_b128 v[210:213], v178 offset:35840
	ds_read_b128 v[214:217], v178 offset:36864
	ds_read_b128 v[218:221], v178 offset:37888
	ds_read_b128 v[222:225], v178 offset:38912
	ds_read_b128 v[226:229], v178 offset:39936
	global_load_lds_dwordx4 v[234:235], off
	v_lshl_add_u64 v[234:235], s[46:47], 0, v[152:153]
	s_mov_b32 m0, s50
	s_nop 0
	global_load_lds_dwordx4 v[234:235], off
	s_waitcnt vmcnt(8)
	s_waitcnt lgkmcnt(0)
	s_barrier
	s_waitcnt lgkmcnt(0)
	v_mfma_f32_16x16x32_bf16 v[140:143], v[48:51], v[198:201], v[140:143]
	v_mfma_f32_16x16x32_bf16 v[136:139], v[64:67], v[198:201], v[136:139]
	v_mfma_f32_16x16x32_bf16 v[124:127], v[48:51], v[206:209], v[124:127]
	v_mfma_f32_16x16x32_bf16 v[120:123], v[64:67], v[206:209], v[120:123]
	v_mfma_f32_16x16x32_bf16 v[108:111], v[48:51], v[214:217], v[108:111]
	v_mfma_f32_16x16x32_bf16 v[104:107], v[64:67], v[214:217], v[104:107]
	v_mfma_f32_16x16x32_bf16 v[92:95], v[48:51], v[222:225], v[92:95]
	v_mfma_f32_16x16x32_bf16 v[88:91], v[64:67], v[222:225], v[88:91]
	v_mfma_f32_16x16x32_bf16 v[140:143], v[52:55], v[202:205], v[140:143]
	v_mfma_f32_16x16x32_bf16 v[136:139], v[68:71], v[202:205], v[136:139]
	v_mfma_f32_16x16x32_bf16 v[124:127], v[52:55], v[210:213], v[124:127]
	v_mfma_f32_16x16x32_bf16 v[120:123], v[68:71], v[210:213], v[120:123]
	v_mfma_f32_16x16x32_bf16 v[108:111], v[52:55], v[218:221], v[108:111]
	v_mfma_f32_16x16x32_bf16 v[104:107], v[68:71], v[218:221], v[104:107]
	v_mfma_f32_16x16x32_bf16 v[92:95], v[52:55], v[226:229], v[92:95]
	v_mfma_f32_16x16x32_bf16 v[88:91], v[68:71], v[226:229], v[88:91]
	v_mfma_f32_16x16x32_bf16 v[132:135], v[162:165], v[198:201], v[132:135]
	v_mfma_f32_16x16x32_bf16 v[128:131], v[170:173], v[198:201], v[128:131]
	v_mfma_f32_16x16x32_bf16 v[116:119], v[162:165], v[206:209], v[116:119]
	v_mfma_f32_16x16x32_bf16 v[112:115], v[170:173], v[206:209], v[112:115]
	v_mfma_f32_16x16x32_bf16 v[100:103], v[162:165], v[214:217], v[100:103]
	v_mfma_f32_16x16x32_bf16 v[96:99], v[170:173], v[214:217], v[96:99]
	v_mfma_f32_16x16x32_bf16 v[84:87], v[162:165], v[222:225], v[84:87]
	v_mfma_f32_16x16x32_bf16 v[80:83], v[170:173], v[222:225], v[80:83]
	v_mfma_f32_16x16x32_bf16 v[132:135], v[166:169], v[202:205], v[132:135]
	v_mfma_f32_16x16x32_bf16 v[128:131], v[194:197], v[202:205], v[128:131]
	v_mfma_f32_16x16x32_bf16 v[116:119], v[166:169], v[210:213], v[116:119]
	v_mfma_f32_16x16x32_bf16 v[112:115], v[194:197], v[210:213], v[112:115]
	v_mfma_f32_16x16x32_bf16 v[100:103], v[166:169], v[218:221], v[100:103]
	v_mfma_f32_16x16x32_bf16 v[96:99], v[194:197], v[218:221], v[96:99]
	v_mfma_f32_16x16x32_bf16 v[84:87], v[166:169], v[226:229], v[84:87]
	v_mfma_f32_16x16x32_bf16 v[80:83], v[194:197], v[226:229], v[80:83]
	s_barrier
	s_add_i32 s46, s58, s66
	v_lshl_add_u64 v[174:175], v[174:175], 0, s[14:15]
	s_mov_b32 m0, s46
	ds_read_b128 v[198:201], v178 offset:49152
	ds_read_b128 v[202:205], v178 offset:50176
	ds_read_b128 v[206:209], v178 offset:51200
	ds_read_b128 v[210:213], v178 offset:52224
	ds_read_b128 v[214:217], v178 offset:53248
	ds_read_b128 v[218:221], v178 offset:54272
	ds_read_b128 v[222:225], v178 offset:55296
	ds_read_b128 v[226:229], v178 offset:56320
	global_load_lds_dwordx4 v[174:175], off
	s_add_i32 m0, s46, 0x2000
	s_add_u32 s2, s2, 0x80080
	v_lshl_add_u64 v[174:175], v[182:183], 0, s[14:15]
	s_addc_u32 s3, s3, 0
	s_add_i32 s46, s59, s66
	global_load_lds_dwordx4 v[174:175], off
	v_lshl_add_u64 v[174:175], s[2:3], 0, v[150:151]
	s_mov_b32 m0, s46
	s_nop 0
	global_load_lds_dwordx4 v[174:175], off
	v_lshl_add_u64 v[174:175], s[2:3], 0, v[154:155]
	s_add_i32 m0, s46, 0x2000
	s_nop 0
	global_load_lds_dwordx4 v[174:175], off
	v_lshl_add_u64 v[174:175], v[230:231], 0, s[14:15]
	s_mov_b32 m0, s51
	s_nop 0
	global_load_lds_dwordx4 v[174:175], off
	v_lshl_add_u64 v[174:175], v[232:233], 0, s[14:15]
	s_mov_b32 m0, s52
	s_nop 0
	global_load_lds_dwordx4 v[174:175], off
	s_waitcnt vmcnt(8)
	s_waitcnt lgkmcnt(0)
	s_barrier
	s_waitcnt lgkmcnt(0)
	v_mfma_f32_16x16x32_bf16 v[76:79], v[48:51], v[198:201], v[76:79]
	v_mfma_f32_16x16x32_bf16 v[72:75], v[64:67], v[198:201], v[72:75]
	v_mfma_f32_16x16x32_bf16 v[60:63], v[48:51], v[206:209], v[60:63]
	v_mfma_f32_16x16x32_bf16 v[56:59], v[64:67], v[206:209], v[56:59]
	v_mfma_f32_16x16x32_bf16 v[28:31], v[48:51], v[214:217], v[28:31]
	v_mfma_f32_16x16x32_bf16 v[24:27], v[64:67], v[214:217], v[24:27]
	v_mfma_f32_16x16x32_bf16 v[12:15], v[48:51], v[222:225], v[12:15]
	v_mfma_f32_16x16x32_bf16 v[8:11], v[64:67], v[222:225], v[8:11]
	v_mfma_f32_16x16x32_bf16 v[76:79], v[52:55], v[202:205], v[76:79]
	v_mfma_f32_16x16x32_bf16 v[72:75], v[68:71], v[202:205], v[72:75]
	v_mfma_f32_16x16x32_bf16 v[60:63], v[52:55], v[210:213], v[60:63]
	v_mfma_f32_16x16x32_bf16 v[56:59], v[68:71], v[210:213], v[56:59]
	v_mfma_f32_16x16x32_bf16 v[28:31], v[52:55], v[218:221], v[28:31]
	v_mfma_f32_16x16x32_bf16 v[24:27], v[68:71], v[218:221], v[24:27]
	v_mfma_f32_16x16x32_bf16 v[12:15], v[52:55], v[226:229], v[12:15]
	v_mfma_f32_16x16x32_bf16 v[8:11], v[68:71], v[226:229], v[8:11]
	v_mfma_f32_16x16x32_bf16 v[40:43], v[162:165], v[198:201], v[40:43]
	v_mfma_f32_16x16x32_bf16 v[68:71], v[166:169], v[202:205], v[40:43]
	v_mfma_f32_16x16x32_bf16 v[40:43], v[170:173], v[198:201], v[44:47]
	v_mfma_f32_16x16x32_bf16 v[36:39], v[162:165], v[206:209], v[36:39]
	v_mfma_f32_16x16x32_bf16 v[32:35], v[170:173], v[206:209], v[32:35]
	v_mfma_f32_16x16x32_bf16 v[20:23], v[162:165], v[214:217], v[20:23]
	v_mfma_f32_16x16x32_bf16 v[16:19], v[170:173], v[214:217], v[16:19]
	v_mfma_f32_16x16x32_bf16 v[4:7], v[162:165], v[222:225], v[4:7]
	v_mfma_f32_16x16x32_bf16 v[0:3], v[170:173], v[222:225], v[0:3]
	v_mfma_f32_16x16x32_bf16 v[64:67], v[194:197], v[202:205], v[40:43]
	v_mfma_f32_16x16x32_bf16 v[36:39], v[166:169], v[210:213], v[36:39]
	v_mfma_f32_16x16x32_bf16 v[32:35], v[194:197], v[210:213], v[32:35]
	v_mfma_f32_16x16x32_bf16 v[20:23], v[166:169], v[218:221], v[20:23]
	v_mfma_f32_16x16x32_bf16 v[16:19], v[194:197], v[218:221], v[16:19]
	v_mfma_f32_16x16x32_bf16 v[4:7], v[166:169], v[226:229], v[4:7]
	v_mfma_f32_16x16x32_bf16 v[0:3], v[194:197], v[226:229], v[0:3]
	s_add_i32 s77, s77, 2
	s_add_u32 s0, s0, 0x100
	s_addc_u32 s1, s1, 0
	s_add_u32 s75, s75, 0x100
	s_addc_u32 s76, s76, 0
	s_cmp_gt_u32 s77, 29
	s_barrier
	s_cbranch_scc0 .LBB0_254
	s_setprio 0
	s_and_b64 vcc, exec, s[16:17]
	s_cbranch_vccz .LBB0_257
	s_barrier

.Lprio_skip2:
.LBB0_295:
	ds_read_b128 v[50:53], v44
	ds_read_b128 v[170:173], v44 offset:1024
	ds_read_b128 v[174:177], v44 offset:2048
	ds_read_b128 v[178:181], v44 offset:3072
	ds_read_b128 v[196:199], v45
	ds_read_b128 v[200:203], v45 offset:1024
	ds_read_b128 v[204:207], v45 offset:2048
	ds_read_b128 v[208:211], v45 offset:3072
	s_add_u32 s10, s6, s8
	s_addc_u32 s11, s7, s9
	s_add_u32 s10, s10, 0xf200100
	s_addc_u32 s11, s11, 0
	s_add_u32 s53, s21, s8
	s_addc_u32 s54, s22, s9
	s_cmpk_eq_i32 s8, 0xf00
	s_cselect_b32 s13, s35, s11
	s_cselect_b32 s12, s34, s10
	s_cselect_b32 s11, s1, s54
	s_cselect_b32 s10, s0, s53
	s_mov_b32 m0, s42
	v_lshl_add_u64 v[54:55], v[40:41], 0, s[8:9]
	ds_read_b128 v[212:215], v46
	ds_read_b128 v[216:219], v46 offset:1024
	ds_read_b128 v[220:223], v46 offset:2048
	ds_read_b128 v[224:227], v46 offset:3072
	ds_read_b128 v[228:231], v46 offset:4096
	ds_read_b128 v[232:235], v46 offset:5120
	ds_read_b128 v[236:239], v46 offset:6144
	ds_read_b128 v[240:243], v46 offset:7168
	global_load_lds_dwordx4 v[54:55], off
	v_lshl_add_u64 v[54:55], v[42:43], 0, s[8:9]
	s_mov_b32 m0, s43
	s_nop 0
	global_load_lds_dwordx4 v[54:55], off
	s_waitcnt vmcnt(8)
	s_waitcnt lgkmcnt(0)
	s_barrier
	s_waitcnt lgkmcnt(0)
	v_mfma_f32_16x16x32_bf16 v[140:143], v[50:53], v[212:215], v[140:143]
	v_mfma_f32_16x16x32_bf16 v[136:139], v[174:177], v[212:215], v[136:139]
	v_mfma_f32_16x16x32_bf16 v[124:127], v[50:53], v[220:223], v[124:127]
	v_mfma_f32_16x16x32_bf16 v[120:123], v[174:177], v[220:223], v[120:123]
	v_mfma_f32_16x16x32_bf16 v[108:111], v[50:53], v[228:231], v[108:111]
	v_mfma_f32_16x16x32_bf16 v[104:107], v[174:177], v[228:231], v[104:107]
	v_mfma_f32_16x16x32_bf16 v[92:95], v[50:53], v[236:239], v[92:95]
	v_mfma_f32_16x16x32_bf16 v[88:91], v[174:177], v[236:239], v[88:91]
	v_mfma_f32_16x16x32_bf16 v[140:143], v[170:173], v[216:219], v[140:143]
	v_mfma_f32_16x16x32_bf16 v[136:139], v[178:181], v[216:219], v[136:139]
	v_mfma_f32_16x16x32_bf16 v[124:127], v[170:173], v[224:227], v[124:127]
	v_mfma_f32_16x16x32_bf16 v[120:123], v[178:181], v[224:227], v[120:123]
	v_mfma_f32_16x16x32_bf16 v[108:111], v[170:173], v[232:235], v[108:111]
	v_mfma_f32_16x16x32_bf16 v[104:107], v[178:181], v[232:235], v[104:107]
	v_mfma_f32_16x16x32_bf16 v[92:95], v[170:173], v[240:243], v[92:95]
	v_mfma_f32_16x16x32_bf16 v[88:91], v[178:181], v[240:243], v[88:91]
	v_mfma_f32_16x16x32_bf16 v[132:135], v[196:199], v[212:215], v[132:135]
	v_mfma_f32_16x16x32_bf16 v[128:131], v[204:207], v[212:215], v[128:131]
	v_mfma_f32_16x16x32_bf16 v[116:119], v[196:199], v[220:223], v[116:119]
	v_mfma_f32_16x16x32_bf16 v[112:115], v[204:207], v[220:223], v[112:115]
	v_mfma_f32_16x16x32_bf16 v[100:103], v[196:199], v[228:231], v[100:103]
	v_mfma_f32_16x16x32_bf16 v[96:99], v[204:207], v[228:231], v[96:99]
	v_mfma_f32_16x16x32_bf16 v[84:87], v[196:199], v[236:239], v[84:87]
	v_mfma_f32_16x16x32_bf16 v[80:83], v[204:207], v[236:239], v[80:83]
	v_mfma_f32_16x16x32_bf16 v[132:135], v[200:203], v[216:219], v[132:135]
	v_mfma_f32_16x16x32_bf16 v[128:131], v[208:211], v[216:219], v[128:131]
	v_mfma_f32_16x16x32_bf16 v[116:119], v[200:203], v[224:227], v[116:119]
	v_mfma_f32_16x16x32_bf16 v[112:115], v[208:211], v[224:227], v[112:115]
	v_mfma_f32_16x16x32_bf16 v[100:103], v[200:203], v[232:235], v[100:103]
	v_mfma_f32_16x16x32_bf16 v[96:99], v[208:211], v[232:235], v[96:99]
	v_mfma_f32_16x16x32_bf16 v[84:87], v[200:203], v[240:243], v[84:87]
	v_mfma_f32_16x16x32_bf16 v[80:83], v[208:211], v[240:243], v[80:83]
	s_barrier
	s_mov_b32 m0, s44
	v_lshl_add_u64 v[182:183], s[10:11], 0, v[150:151]
	s_add_u32 s54, s10, 0x80000
	ds_read_b128 v[212:215], v46 offset:16384
	ds_read_b128 v[216:219], v46 offset:17408
	ds_read_b128 v[220:223], v46 offset:18432
	ds_read_b128 v[224:227], v46 offset:19456
	ds_read_b128 v[228:231], v46 offset:20480
	ds_read_b128 v[232:235], v46 offset:21504
	ds_read_b128 v[236:239], v46 offset:22528
	ds_read_b128 v[240:243], v46 offset:23552
	global_load_lds_dwordx4 v[182:183], off
	v_lshl_add_u64 v[244:245], s[10:11], 0, v[154:155]
	s_mov_b32 m0, s45
	s_addc_u32 s55, s11, 0
	global_load_lds_dwordx4 v[244:245], off
	v_lshl_add_u64 v[54:55], s[54:55], 0, v[150:151]
	s_mov_b32 m0, s46
	v_lshl_add_u64 v[246:247], s[12:13], 0, v[148:149]
	global_load_lds_dwordx4 v[54:55], off
	v_lshl_add_u64 v[54:55], s[54:55], 0, v[154:155]
	s_mov_b32 m0, s47
	v_lshl_add_u64 v[248:249], s[12:13], 0, v[152:153]
	global_load_lds_dwordx4 v[54:55], off
	s_mov_b32 m0, s14
	s_nop 0
	global_load_lds_dwordx4 v[246:247], off
	s_mov_b32 m0, s16
	s_nop 0
	global_load_lds_dwordx4 v[248:249], off
	s_waitcnt vmcnt(8)
	s_waitcnt lgkmcnt(0)
	s_barrier
	s_waitcnt lgkmcnt(0)
	v_mfma_f32_16x16x32_bf16 v[76:79], v[50:53], v[212:215], v[76:79]
	v_mfma_f32_16x16x32_bf16 v[72:75], v[174:177], v[212:215], v[72:75]
	v_mfma_f32_16x16x32_bf16 v[60:63], v[50:53], v[220:223], v[60:63]
	v_mfma_f32_16x16x32_bf16 v[54:57], v[174:177], v[220:223], v[56:59]
	v_mfma_f32_16x16x32_bf16 v[28:31], v[50:53], v[228:231], v[28:31]
	v_mfma_f32_16x16x32_bf16 v[24:27], v[174:177], v[228:231], v[24:27]
	v_mfma_f32_16x16x32_bf16 v[12:15], v[50:53], v[236:239], v[12:15]
	v_mfma_f32_16x16x32_bf16 v[8:11], v[174:177], v[236:239], v[8:11]
	v_mfma_f32_16x16x32_bf16 v[76:79], v[170:173], v[216:219], v[76:79]
	v_mfma_f32_16x16x32_bf16 v[72:75], v[178:181], v[216:219], v[72:75]
	v_mfma_f32_16x16x32_bf16 v[60:63], v[170:173], v[224:227], v[60:63]
	v_mfma_f32_16x16x32_bf16 v[54:57], v[178:181], v[224:227], v[54:57]
	v_mfma_f32_16x16x32_bf16 v[28:31], v[170:173], v[232:235], v[28:31]
	v_mfma_f32_16x16x32_bf16 v[24:27], v[178:181], v[232:235], v[24:27]
	v_mfma_f32_16x16x32_bf16 v[12:15], v[170:173], v[240:243], v[12:15]
	v_mfma_f32_16x16x32_bf16 v[8:11], v[178:181], v[240:243], v[8:11]
	v_mfma_f32_16x16x32_bf16 v[64:67], v[204:207], v[212:215], v[64:67]
	v_mfma_f32_16x16x32_bf16 v[36:39], v[196:199], v[220:223], v[36:39]
	v_mfma_f32_16x16x32_bf16 v[32:35], v[204:207], v[220:223], v[32:35]
	v_mfma_f32_16x16x32_bf16 v[20:23], v[196:199], v[228:231], v[20:23]
	v_mfma_f32_16x16x32_bf16 v[16:19], v[204:207], v[228:231], v[16:19]
	v_mfma_f32_16x16x32_bf16 v[4:7], v[196:199], v[236:239], v[4:7]
	v_mfma_f32_16x16x32_bf16 v[0:3], v[204:207], v[236:239], v[0:3]
	v_mfma_f32_16x16x32_bf16 v[50:53], v[196:199], v[212:215], v[68:71]
	v_mfma_f32_16x16x32_bf16 v[64:67], v[208:211], v[216:219], v[64:67]
	v_mfma_f32_16x16x32_bf16 v[36:39], v[200:203], v[224:227], v[36:39]
	v_mfma_f32_16x16x32_bf16 v[32:35], v[208:211], v[224:227], v[32:35]
	v_mfma_f32_16x16x32_bf16 v[20:23], v[200:203], v[232:235], v[20:23]
	v_mfma_f32_16x16x32_bf16 v[16:19], v[208:211], v[232:235], v[16:19]
	v_mfma_f32_16x16x32_bf16 v[4:7], v[200:203], v[240:243], v[4:7]
	v_mfma_f32_16x16x32_bf16 v[0:3], v[208:211], v[240:243], v[0:3]
	v_mfma_f32_16x16x32_bf16 v[50:53], v[200:203], v[216:219], v[50:53]
	s_barrier
	ds_read_b128 v[68:71], v47
	ds_read_b128 v[170:173], v47 offset:1024
	ds_read_b128 v[174:177], v47 offset:2048
	ds_read_b128 v[178:181], v47 offset:3072
	ds_read_b128 v[196:199], v48
	ds_read_b128 v[200:203], v48 offset:1024
	ds_read_b128 v[204:207], v48 offset:2048
	ds_read_b128 v[208:211], v48 offset:3072
	s_add_u32 s12, s12, 0x80000
	s_addc_u32 s13, s13, 0
	s_mov_b32 m0, s17
	v_lshl_add_u64 v[58:59], s[12:13], 0, v[148:149]
	ds_read_b128 v[212:215], v46 offset:32768
	ds_read_b128 v[216:219], v46 offset:33792
	ds_read_b128 v[220:223], v46 offset:34816
	ds_read_b128 v[224:227], v46 offset:35840
	ds_read_b128 v[228:231], v46 offset:36864
	ds_read_b128 v[232:235], v46 offset:37888
	ds_read_b128 v[236:239], v46 offset:38912
	ds_read_b128 v[240:243], v46 offset:39936
	global_load_lds_dwordx4 v[58:59], off
	v_lshl_add_u64 v[58:59], s[12:13], 0, v[152:153]
	s_mov_b32 m0, s18
	s_nop 0
	global_load_lds_dwordx4 v[58:59], off
	s_waitcnt vmcnt(8)
	s_waitcnt lgkmcnt(0)
	s_barrier
	s_waitcnt lgkmcnt(0)
	v_mfma_f32_16x16x32_bf16 v[140:143], v[68:71], v[212:215], v[140:143]
	v_mfma_f32_16x16x32_bf16 v[136:139], v[174:177], v[212:215], v[136:139]
	v_mfma_f32_16x16x32_bf16 v[124:127], v[68:71], v[220:223], v[124:127]
	v_mfma_f32_16x16x32_bf16 v[120:123], v[174:177], v[220:223], v[120:123]
	v_mfma_f32_16x16x32_bf16 v[108:111], v[68:71], v[228:231], v[108:111]
	v_mfma_f32_16x16x32_bf16 v[104:107], v[174:177], v[228:231], v[104:107]
	v_mfma_f32_16x16x32_bf16 v[92:95], v[68:71], v[236:239], v[92:95]
	v_mfma_f32_16x16x32_bf16 v[88:91], v[174:177], v[236:239], v[88:91]
	v_mfma_f32_16x16x32_bf16 v[140:143], v[170:173], v[216:219], v[140:143]
	v_mfma_f32_16x16x32_bf16 v[136:139], v[178:181], v[216:219], v[136:139]
	v_mfma_f32_16x16x32_bf16 v[124:127], v[170:173], v[224:227], v[124:127]
	v_mfma_f32_16x16x32_bf16 v[120:123], v[178:181], v[224:227], v[120:123]
	v_mfma_f32_16x16x32_bf16 v[108:111], v[170:173], v[232:235], v[108:111]
	v_mfma_f32_16x16x32_bf16 v[104:107], v[178:181], v[232:235], v[104:107]
	v_mfma_f32_16x16x32_bf16 v[92:95], v[170:173], v[240:243], v[92:95]
	v_mfma_f32_16x16x32_bf16 v[88:91], v[178:181], v[240:243], v[88:91]
	v_mfma_f32_16x16x32_bf16 v[132:135], v[196:199], v[212:215], v[132:135]
	v_mfma_f32_16x16x32_bf16 v[128:131], v[204:207], v[212:215], v[128:131]
	v_mfma_f32_16x16x32_bf16 v[116:119], v[196:199], v[220:223], v[116:119]
	v_mfma_f32_16x16x32_bf16 v[112:115], v[204:207], v[220:223], v[112:115]
	v_mfma_f32_16x16x32_bf16 v[100:103], v[196:199], v[228:231], v[100:103]
	v_mfma_f32_16x16x32_bf16 v[96:99], v[204:207], v[228:231], v[96:99]
	v_mfma_f32_16x16x32_bf16 v[84:87], v[196:199], v[236:239], v[84:87]
	v_mfma_f32_16x16x32_bf16 v[80:83], v[204:207], v[236:239], v[80:83]
	v_mfma_f32_16x16x32_bf16 v[132:135], v[200:203], v[216:219], v[132:135]
	v_mfma_f32_16x16x32_bf16 v[128:131], v[208:211], v[216:219], v[128:131]
	v_mfma_f32_16x16x32_bf16 v[116:119], v[200:203], v[224:227], v[116:119]
	v_mfma_f32_16x16x32_bf16 v[112:115], v[208:211], v[224:227], v[112:115]
	v_mfma_f32_16x16x32_bf16 v[100:103], v[200:203], v[232:235], v[100:103]
	v_mfma_f32_16x16x32_bf16 v[96:99], v[208:211], v[232:235], v[96:99]
	v_mfma_f32_16x16x32_bf16 v[84:87], v[200:203], v[240:243], v[84:87]
	v_mfma_f32_16x16x32_bf16 v[80:83], v[208:211], v[240:243], v[80:83]
	s_barrier
	s_mov_b32 m0, s49
	v_lshl_add_u64 v[58:59], v[182:183], 0, s[4:5]
	s_add_u32 s10, s10, 0x80080
	ds_read_b128 v[212:215], v46 offset:49152
	ds_read_b128 v[216:219], v46 offset:50176
	ds_read_b128 v[220:223], v46 offset:51200
	ds_read_b128 v[224:227], v46 offset:52224
	ds_read_b128 v[228:231], v46 offset:53248
	ds_read_b128 v[232:235], v46 offset:54272
	ds_read_b128 v[236:239], v46 offset:55296
	ds_read_b128 v[240:243], v46 offset:56320
	global_load_lds_dwordx4 v[58:59], off
	v_lshl_add_u64 v[58:59], v[244:245], 0, s[4:5]
	s_mov_b32 m0, s50
	s_addc_u32 s11, s11, 0
	global_load_lds_dwordx4 v[58:59], off
	v_lshl_add_u64 v[58:59], s[10:11], 0, v[150:151]
	s_mov_b32 m0, s51
	s_nop 0
	global_load_lds_dwordx4 v[58:59], off
	v_lshl_add_u64 v[58:59], s[10:11], 0, v[154:155]
	s_mov_b32 m0, s52
	s_nop 0
	global_load_lds_dwordx4 v[58:59], off
	v_lshl_add_u64 v[58:59], v[246:247], 0, s[4:5]
	s_mov_b32 m0, s19
	s_nop 0
	global_load_lds_dwordx4 v[58:59], off
	v_lshl_add_u64 v[58:59], v[248:249], 0, s[4:5]
	s_mov_b32 m0, s20
	s_nop 0
	global_load_lds_dwordx4 v[58:59], off
	s_waitcnt vmcnt(8)
	s_waitcnt lgkmcnt(0)
	s_barrier
	s_waitcnt lgkmcnt(0)
	v_mfma_f32_16x16x32_bf16 v[76:79], v[68:71], v[212:215], v[76:79]
	v_mfma_f32_16x16x32_bf16 v[72:75], v[174:177], v[212:215], v[72:75]
	v_mfma_f32_16x16x32_bf16 v[58:61], v[68:71], v[220:223], v[60:63]
	v_mfma_f32_16x16x32_bf16 v[54:57], v[174:177], v[220:223], v[54:57]
	v_mfma_f32_16x16x32_bf16 v[28:31], v[68:71], v[228:231], v[28:31]
	v_mfma_f32_16x16x32_bf16 v[24:27], v[174:177], v[228:231], v[24:27]
	v_mfma_f32_16x16x32_bf16 v[12:15], v[68:71], v[236:239], v[12:15]
	v_mfma_f32_16x16x32_bf16 v[8:11], v[174:177], v[236:239], v[8:11]
	v_mfma_f32_16x16x32_bf16 v[76:79], v[170:173], v[216:219], v[76:79]
	v_mfma_f32_16x16x32_bf16 v[72:75], v[178:181], v[216:219], v[72:75]
	v_mfma_f32_16x16x32_bf16 v[60:63], v[170:173], v[224:227], v[58:61]
	v_mfma_f32_16x16x32_bf16 v[56:59], v[178:181], v[224:227], v[54:57]
	v_mfma_f32_16x16x32_bf16 v[28:31], v[170:173], v[232:235], v[28:31]
	v_mfma_f32_16x16x32_bf16 v[24:27], v[178:181], v[232:235], v[24:27]
	v_mfma_f32_16x16x32_bf16 v[12:15], v[170:173], v[240:243], v[12:15]
	v_mfma_f32_16x16x32_bf16 v[8:11], v[178:181], v[240:243], v[8:11]
	v_mfma_f32_16x16x32_bf16 v[50:53], v[196:199], v[212:215], v[50:53]
	v_mfma_f32_16x16x32_bf16 v[68:71], v[200:203], v[216:219], v[50:53]
	v_mfma_f32_16x16x32_bf16 v[50:53], v[204:207], v[212:215], v[64:67]
	v_mfma_f32_16x16x32_bf16 v[36:39], v[196:199], v[220:223], v[36:39]
	v_mfma_f32_16x16x32_bf16 v[32:35], v[204:207], v[220:223], v[32:35]
	v_mfma_f32_16x16x32_bf16 v[20:23], v[196:199], v[228:231], v[20:23]
	v_mfma_f32_16x16x32_bf16 v[16:19], v[204:207], v[228:231], v[16:19]
	v_mfma_f32_16x16x32_bf16 v[4:7], v[196:199], v[236:239], v[4:7]
	v_mfma_f32_16x16x32_bf16 v[0:3], v[204:207], v[236:239], v[0:3]
	v_mfma_f32_16x16x32_bf16 v[64:67], v[208:211], v[216:219], v[50:53]
	v_mfma_f32_16x16x32_bf16 v[36:39], v[200:203], v[224:227], v[36:39]
	v_mfma_f32_16x16x32_bf16 v[32:35], v[208:211], v[224:227], v[32:35]
	v_mfma_f32_16x16x32_bf16 v[20:23], v[200:203], v[232:235], v[20:23]
	v_mfma_f32_16x16x32_bf16 v[16:19], v[208:211], v[232:235], v[16:19]
	v_mfma_f32_16x16x32_bf16 v[4:7], v[200:203], v[240:243], v[4:7]
	v_mfma_f32_16x16x32_bf16 v[0:3], v[208:211], v[240:243], v[0:3]
	s_add_i32 s23, s23, 2
	s_add_u32 s8, s8, 0x100
	s_addc_u32 s9, s9, 0
	s_cmp_gt_u32 s23, 29
	s_barrier
	s_cbranch_scc0 .LBB0_295
	s_setprio 0
	s_and_b64 vcc, exec, s[38:39]
	s_cbranch_vccz .LBB0_298
	s_barrier

.Lprio_skip3:
.LBB0_338:
	ds_read_b128 v[50:53], v44
	ds_read_b128 v[156:159], v44 offset:1024
	ds_read_b128 v[160:163], v44 offset:2048
	ds_read_b128 v[164:167], v44 offset:3072
	ds_read_b128 v[168:171], v45
	ds_read_b128 v[172:175], v45 offset:1024
	ds_read_b128 v[176:179], v45 offset:2048
	ds_read_b128 v[180:183], v45 offset:3072
	s_add_u32 s8, s2, s6
	s_addc_u32 s9, s3, s7
	s_add_u32 s8, s8, 0xf200100
	s_addc_u32 s9, s9, 0
	s_add_u32 s48, s19, s6
	s_addc_u32 s49, s20, s7
	s_cmpk_eq_i32 s6, 0xf00
	s_cselect_b32 s11, s35, s9
	s_cselect_b32 s10, s34, s8
	s_cselect_b32 s9, s1, s49
	s_cselect_b32 s8, s0, s48
	s_mov_b32 m0, s22
	v_lshl_add_u64 v[54:55], v[40:41], 0, s[6:7]
	ds_read_b128 v[186:189], v46
	ds_read_b128 v[190:193], v46 offset:1024
	ds_read_b128 v[194:197], v46 offset:2048
	ds_read_b128 v[198:201], v46 offset:3072
	ds_read_b128 v[202:205], v46 offset:4096
	ds_read_b128 v[206:209], v46 offset:5120
	ds_read_b128 v[210:213], v46 offset:6144
	ds_read_b128 v[214:217], v46 offset:7168
	global_load_lds_dwordx4 v[54:55], off
	v_lshl_add_u64 v[54:55], v[42:43], 0, s[6:7]
	s_mov_b32 m0, s23
	s_nop 0
	global_load_lds_dwordx4 v[54:55], off
	s_waitcnt vmcnt(8)
	s_waitcnt lgkmcnt(0)
	s_barrier
	s_waitcnt lgkmcnt(0)
	v_mfma_f32_16x16x32_bf16 v[140:143], v[50:53], v[186:189], v[140:143]
	v_mfma_f32_16x16x32_bf16 v[136:139], v[160:163], v[186:189], v[136:139]
	v_mfma_f32_16x16x32_bf16 v[124:127], v[50:53], v[194:197], v[124:127]
	v_mfma_f32_16x16x32_bf16 v[120:123], v[160:163], v[194:197], v[120:123]
	v_mfma_f32_16x16x32_bf16 v[108:111], v[50:53], v[202:205], v[108:111]
	v_mfma_f32_16x16x32_bf16 v[104:107], v[160:163], v[202:205], v[104:107]
	v_mfma_f32_16x16x32_bf16 v[92:95], v[50:53], v[210:213], v[92:95]
	v_mfma_f32_16x16x32_bf16 v[88:91], v[160:163], v[210:213], v[88:91]
	v_mfma_f32_16x16x32_bf16 v[140:143], v[156:159], v[190:193], v[140:143]
	v_mfma_f32_16x16x32_bf16 v[136:139], v[164:167], v[190:193], v[136:139]
	v_mfma_f32_16x16x32_bf16 v[124:127], v[156:159], v[198:201], v[124:127]
	v_mfma_f32_16x16x32_bf16 v[120:123], v[164:167], v[198:201], v[120:123]
	v_mfma_f32_16x16x32_bf16 v[108:111], v[156:159], v[206:209], v[108:111]
	v_mfma_f32_16x16x32_bf16 v[104:107], v[164:167], v[206:209], v[104:107]
	v_mfma_f32_16x16x32_bf16 v[92:95], v[156:159], v[214:217], v[92:95]
	v_mfma_f32_16x16x32_bf16 v[88:91], v[164:167], v[214:217], v[88:91]
	v_mfma_f32_16x16x32_bf16 v[132:135], v[168:171], v[186:189], v[132:135]
	v_mfma_f32_16x16x32_bf16 v[128:131], v[176:179], v[186:189], v[128:131]
	v_mfma_f32_16x16x32_bf16 v[116:119], v[168:171], v[194:197], v[116:119]
	v_mfma_f32_16x16x32_bf16 v[112:115], v[176:179], v[194:197], v[112:115]
	v_mfma_f32_16x16x32_bf16 v[100:103], v[168:171], v[202:205], v[100:103]
	v_mfma_f32_16x16x32_bf16 v[96:99], v[176:179], v[202:205], v[96:99]
	v_mfma_f32_16x16x32_bf16 v[84:87], v[168:171], v[210:213], v[84:87]
	v_mfma_f32_16x16x32_bf16 v[80:83], v[176:179], v[210:213], v[80:83]
	v_mfma_f32_16x16x32_bf16 v[132:135], v[172:175], v[190:193], v[132:135]
	v_mfma_f32_16x16x32_bf16 v[128:131], v[180:183], v[190:193], v[128:131]
	v_mfma_f32_16x16x32_bf16 v[116:119], v[172:175], v[198:201], v[116:119]
	v_mfma_f32_16x16x32_bf16 v[112:115], v[180:183], v[198:201], v[112:115]
	v_mfma_f32_16x16x32_bf16 v[100:103], v[172:175], v[206:209], v[100:103]
	v_mfma_f32_16x16x32_bf16 v[96:99], v[180:183], v[206:209], v[96:99]
	v_mfma_f32_16x16x32_bf16 v[84:87], v[172:175], v[214:217], v[84:87]
	v_mfma_f32_16x16x32_bf16 v[80:83], v[180:183], v[214:217], v[80:83]
	s_barrier
	s_mov_b32 m0, s40
	v_lshl_add_u64 v[218:219], s[8:9], 0, v[150:151]
	s_add_u32 s48, s8, 0x80000
	ds_read_b128 v[186:189], v46 offset:16384
	ds_read_b128 v[190:193], v46 offset:17408
	ds_read_b128 v[194:197], v46 offset:18432
	ds_read_b128 v[198:201], v46 offset:19456
	ds_read_b128 v[202:205], v46 offset:20480
	ds_read_b128 v[206:209], v46 offset:21504
	ds_read_b128 v[210:213], v46 offset:22528
	ds_read_b128 v[214:217], v46 offset:23552
	global_load_lds_dwordx4 v[218:219], off
	v_lshl_add_u64 v[220:221], s[8:9], 0, v[154:155]
	s_mov_b32 m0, s41
	s_addc_u32 s49, s9, 0
	global_load_lds_dwordx4 v[220:221], off
	v_lshl_add_u64 v[54:55], s[48:49], 0, v[150:151]
	s_mov_b32 m0, s42
	v_lshl_add_u64 v[222:223], s[10:11], 0, v[148:149]
	global_load_lds_dwordx4 v[54:55], off
	v_lshl_add_u64 v[54:55], s[48:49], 0, v[154:155]
	s_mov_b32 m0, s43
	v_lshl_add_u64 v[224:225], s[10:11], 0, v[152:153]
	global_load_lds_dwordx4 v[54:55], off
	s_mov_b32 m0, s12
	s_nop 0
	global_load_lds_dwordx4 v[222:223], off
	s_mov_b32 m0, s14
	s_nop 0
	global_load_lds_dwordx4 v[224:225], off
	s_waitcnt vmcnt(8)
	s_waitcnt lgkmcnt(0)
	s_barrier
	s_waitcnt lgkmcnt(0)
	v_mfma_f32_16x16x32_bf16 v[76:79], v[50:53], v[186:189], v[76:79]
	v_mfma_f32_16x16x32_bf16 v[72:75], v[160:163], v[186:189], v[72:75]
	v_mfma_f32_16x16x32_bf16 v[60:63], v[50:53], v[194:197], v[60:63]
	v_mfma_f32_16x16x32_bf16 v[54:57], v[160:163], v[194:197], v[56:59]
	v_mfma_f32_16x16x32_bf16 v[28:31], v[50:53], v[202:205], v[28:31]
	v_mfma_f32_16x16x32_bf16 v[24:27], v[160:163], v[202:205], v[24:27]
	v_mfma_f32_16x16x32_bf16 v[12:15], v[50:53], v[210:213], v[12:15]
	v_mfma_f32_16x16x32_bf16 v[8:11], v[160:163], v[210:213], v[8:11]
	v_mfma_f32_16x16x32_bf16 v[76:79], v[156:159], v[190:193], v[76:79]
	v_mfma_f32_16x16x32_bf16 v[72:75], v[164:167], v[190:193], v[72:75]
	v_mfma_f32_16x16x32_bf16 v[60:63], v[156:159], v[198:201], v[60:63]
	v_mfma_f32_16x16x32_bf16 v[54:57], v[164:167], v[198:201], v[54:57]
	v_mfma_f32_16x16x32_bf16 v[28:31], v[156:159], v[206:209], v[28:31]
	v_mfma_f32_16x16x32_bf16 v[24:27], v[164:167], v[206:209], v[24:27]
	v_mfma_f32_16x16x32_bf16 v[12:15], v[156:159], v[214:217], v[12:15]
	v_mfma_f32_16x16x32_bf16 v[8:11], v[164:167], v[214:217], v[8:11]
	v_mfma_f32_16x16x32_bf16 v[64:67], v[176:179], v[186:189], v[64:67]
	v_mfma_f32_16x16x32_bf16 v[36:39], v[168:171], v[194:197], v[36:39]
	v_mfma_f32_16x16x32_bf16 v[32:35], v[176:179], v[194:197], v[32:35]
	v_mfma_f32_16x16x32_bf16 v[20:23], v[168:171], v[202:205], v[20:23]
	v_mfma_f32_16x16x32_bf16 v[16:19], v[176:179], v[202:205], v[16:19]
	v_mfma_f32_16x16x32_bf16 v[4:7], v[168:171], v[210:213], v[4:7]
	v_mfma_f32_16x16x32_bf16 v[0:3], v[176:179], v[210:213], v[0:3]
	v_mfma_f32_16x16x32_bf16 v[50:53], v[168:171], v[186:189], v[68:71]
	v_mfma_f32_16x16x32_bf16 v[64:67], v[180:183], v[190:193], v[64:67]
	v_mfma_f32_16x16x32_bf16 v[36:39], v[172:175], v[198:201], v[36:39]
	v_mfma_f32_16x16x32_bf16 v[32:35], v[180:183], v[198:201], v[32:35]
	v_mfma_f32_16x16x32_bf16 v[20:23], v[172:175], v[206:209], v[20:23]
	v_mfma_f32_16x16x32_bf16 v[16:19], v[180:183], v[206:209], v[16:19]
	v_mfma_f32_16x16x32_bf16 v[4:7], v[172:175], v[214:217], v[4:7]
	v_mfma_f32_16x16x32_bf16 v[0:3], v[180:183], v[214:217], v[0:3]
	v_mfma_f32_16x16x32_bf16 v[50:53], v[172:175], v[190:193], v[50:53]
	s_barrier
	ds_read_b128 v[68:71], v47
	ds_read_b128 v[156:159], v47 offset:1024
	ds_read_b128 v[160:163], v47 offset:2048
	ds_read_b128 v[164:167], v47 offset:3072
	ds_read_b128 v[168:171], v48
	ds_read_b128 v[172:175], v48 offset:1024
	ds_read_b128 v[176:179], v48 offset:2048
	ds_read_b128 v[180:183], v48 offset:3072
	s_add_u32 s10, s10, 0x80000
	s_addc_u32 s11, s11, 0
	s_mov_b32 m0, s15
	v_lshl_add_u64 v[58:59], s[10:11], 0, v[148:149]
	ds_read_b128 v[186:189], v46 offset:32768
	ds_read_b128 v[190:193], v46 offset:33792
	ds_read_b128 v[194:197], v46 offset:34816
	ds_read_b128 v[198:201], v46 offset:35840
	ds_read_b128 v[202:205], v46 offset:36864
	ds_read_b128 v[206:209], v46 offset:37888
	ds_read_b128 v[210:213], v46 offset:38912
	ds_read_b128 v[214:217], v46 offset:39936
	global_load_lds_dwordx4 v[58:59], off
	v_lshl_add_u64 v[58:59], s[10:11], 0, v[152:153]
	s_mov_b32 m0, s16
	s_nop 0
	global_load_lds_dwordx4 v[58:59], off
	s_waitcnt vmcnt(8)
	s_waitcnt lgkmcnt(0)
	s_barrier
	s_waitcnt lgkmcnt(0)
	v_mfma_f32_16x16x32_bf16 v[140:143], v[68:71], v[186:189], v[140:143]
	v_mfma_f32_16x16x32_bf16 v[136:139], v[160:163], v[186:189], v[136:139]
	v_mfma_f32_16x16x32_bf16 v[124:127], v[68:71], v[194:197], v[124:127]
	v_mfma_f32_16x16x32_bf16 v[120:123], v[160:163], v[194:197], v[120:123]
	v_mfma_f32_16x16x32_bf16 v[108:111], v[68:71], v[202:205], v[108:111]
	v_mfma_f32_16x16x32_bf16 v[104:107], v[160:163], v[202:205], v[104:107]
	v_mfma_f32_16x16x32_bf16 v[92:95], v[68:71], v[210:213], v[92:95]
	v_mfma_f32_16x16x32_bf16 v[88:91], v[160:163], v[210:213], v[88:91]
	v_mfma_f32_16x16x32_bf16 v[140:143], v[156:159], v[190:193], v[140:143]
	v_mfma_f32_16x16x32_bf16 v[136:139], v[164:167], v[190:193], v[136:139]
	v_mfma_f32_16x16x32_bf16 v[124:127], v[156:159], v[198:201], v[124:127]
	v_mfma_f32_16x16x32_bf16 v[120:123], v[164:167], v[198:201], v[120:123]
	v_mfma_f32_16x16x32_bf16 v[108:111], v[156:159], v[206:209], v[108:111]
	v_mfma_f32_16x16x32_bf16 v[104:107], v[164:167], v[206:209], v[104:107]
	v_mfma_f32_16x16x32_bf16 v[92:95], v[156:159], v[214:217], v[92:95]
	v_mfma_f32_16x16x32_bf16 v[88:91], v[164:167], v[214:217], v[88:91]
	v_mfma_f32_16x16x32_bf16 v[132:135], v[168:171], v[186:189], v[132:135]
	v_mfma_f32_16x16x32_bf16 v[128:131], v[176:179], v[186:189], v[128:131]
	v_mfma_f32_16x16x32_bf16 v[116:119], v[168:171], v[194:197], v[116:119]
	v_mfma_f32_16x16x32_bf16 v[112:115], v[176:179], v[194:197], v[112:115]
	v_mfma_f32_16x16x32_bf16 v[100:103], v[168:171], v[202:205], v[100:103]
	v_mfma_f32_16x16x32_bf16 v[96:99], v[176:179], v[202:205], v[96:99]
	v_mfma_f32_16x16x32_bf16 v[84:87], v[168:171], v[210:213], v[84:87]
	v_mfma_f32_16x16x32_bf16 v[80:83], v[176:179], v[210:213], v[80:83]
	v_mfma_f32_16x16x32_bf16 v[132:135], v[172:175], v[190:193], v[132:135]
	v_mfma_f32_16x16x32_bf16 v[128:131], v[180:183], v[190:193], v[128:131]
	v_mfma_f32_16x16x32_bf16 v[116:119], v[172:175], v[198:201], v[116:119]
	v_mfma_f32_16x16x32_bf16 v[112:115], v[180:183], v[198:201], v[112:115]
	v_mfma_f32_16x16x32_bf16 v[100:103], v[172:175], v[206:209], v[100:103]
	v_mfma_f32_16x16x32_bf16 v[96:99], v[180:183], v[206:209], v[96:99]
	v_mfma_f32_16x16x32_bf16 v[84:87], v[172:175], v[214:217], v[84:87]
	v_mfma_f32_16x16x32_bf16 v[80:83], v[180:183], v[214:217], v[80:83]
	s_barrier
	s_mov_b32 m0, s44
	v_lshl_add_u64 v[58:59], v[218:219], 0, s[4:5]
	s_add_u32 s8, s8, 0x80080
	ds_read_b128 v[186:189], v46 offset:49152
	ds_read_b128 v[190:193], v46 offset:50176
	ds_read_b128 v[194:197], v46 offset:51200
	ds_read_b128 v[198:201], v46 offset:52224
	ds_read_b128 v[202:205], v46 offset:53248
	ds_read_b128 v[206:209], v46 offset:54272
	ds_read_b128 v[210:213], v46 offset:55296
	ds_read_b128 v[214:217], v46 offset:56320
	global_load_lds_dwordx4 v[58:59], off
	v_lshl_add_u64 v[58:59], v[220:221], 0, s[4:5]
	s_mov_b32 m0, s45
	s_addc_u32 s9, s9, 0
	global_load_lds_dwordx4 v[58:59], off
	v_lshl_add_u64 v[58:59], s[8:9], 0, v[150:151]
	s_mov_b32 m0, s46
	s_nop 0
	global_load_lds_dwordx4 v[58:59], off
	v_lshl_add_u64 v[58:59], s[8:9], 0, v[154:155]
	s_mov_b32 m0, s47
	s_nop 0
	global_load_lds_dwordx4 v[58:59], off
	v_lshl_add_u64 v[58:59], v[222:223], 0, s[4:5]
	s_mov_b32 m0, s17
	s_nop 0
	global_load_lds_dwordx4 v[58:59], off
	v_lshl_add_u64 v[58:59], v[224:225], 0, s[4:5]
	s_mov_b32 m0, s18
	s_nop 0
	global_load_lds_dwordx4 v[58:59], off
	s_waitcnt vmcnt(8)
	s_waitcnt lgkmcnt(0)
	s_barrier
	s_waitcnt lgkmcnt(0)
	v_mfma_f32_16x16x32_bf16 v[76:79], v[68:71], v[186:189], v[76:79]
	v_mfma_f32_16x16x32_bf16 v[72:75], v[160:163], v[186:189], v[72:75]
	v_mfma_f32_16x16x32_bf16 v[58:61], v[68:71], v[194:197], v[60:63]
	v_mfma_f32_16x16x32_bf16 v[54:57], v[160:163], v[194:197], v[54:57]
	v_mfma_f32_16x16x32_bf16 v[28:31], v[68:71], v[202:205], v[28:31]
	v_mfma_f32_16x16x32_bf16 v[24:27], v[160:163], v[202:205], v[24:27]
	v_mfma_f32_16x16x32_bf16 v[12:15], v[68:71], v[210:213], v[12:15]
	v_mfma_f32_16x16x32_bf16 v[8:11], v[160:163], v[210:213], v[8:11]
	v_mfma_f32_16x16x32_bf16 v[76:79], v[156:159], v[190:193], v[76:79]
	v_mfma_f32_16x16x32_bf16 v[72:75], v[164:167], v[190:193], v[72:75]
	v_mfma_f32_16x16x32_bf16 v[60:63], v[156:159], v[198:201], v[58:61]
	v_mfma_f32_16x16x32_bf16 v[56:59], v[164:167], v[198:201], v[54:57]
	v_mfma_f32_16x16x32_bf16 v[28:31], v[156:159], v[206:209], v[28:31]
	v_mfma_f32_16x16x32_bf16 v[24:27], v[164:167], v[206:209], v[24:27]
	v_mfma_f32_16x16x32_bf16 v[12:15], v[156:159], v[214:217], v[12:15]
	v_mfma_f32_16x16x32_bf16 v[8:11], v[164:167], v[214:217], v[8:11]
	v_mfma_f32_16x16x32_bf16 v[50:53], v[168:171], v[186:189], v[50:53]
	v_mfma_f32_16x16x32_bf16 v[68:71], v[172:175], v[190:193], v[50:53]
	v_mfma_f32_16x16x32_bf16 v[50:53], v[176:179], v[186:189], v[64:67]
	v_mfma_f32_16x16x32_bf16 v[36:39], v[168:171], v[194:197], v[36:39]
	v_mfma_f32_16x16x32_bf16 v[32:35], v[176:179], v[194:197], v[32:35]
	v_mfma_f32_16x16x32_bf16 v[20:23], v[168:171], v[202:205], v[20:23]
	v_mfma_f32_16x16x32_bf16 v[16:19], v[176:179], v[202:205], v[16:19]
	v_mfma_f32_16x16x32_bf16 v[4:7], v[168:171], v[210:213], v[4:7]
	v_mfma_f32_16x16x32_bf16 v[0:3], v[176:179], v[210:213], v[0:3]
	v_mfma_f32_16x16x32_bf16 v[64:67], v[180:183], v[190:193], v[50:53]
	v_mfma_f32_16x16x32_bf16 v[36:39], v[172:175], v[198:201], v[36:39]
	v_mfma_f32_16x16x32_bf16 v[32:35], v[180:183], v[198:201], v[32:35]
	v_mfma_f32_16x16x32_bf16 v[20:23], v[172:175], v[206:209], v[20:23]
	v_mfma_f32_16x16x32_bf16 v[16:19], v[180:183], v[206:209], v[16:19]
	v_mfma_f32_16x16x32_bf16 v[4:7], v[172:175], v[214:217], v[4:7]
	v_mfma_f32_16x16x32_bf16 v[0:3], v[180:183], v[214:217], v[0:3]
	s_add_i32 s21, s21, 2
	s_add_u32 s6, s6, 0x100
	s_addc_u32 s7, s7, 0
	s_cmp_lt_u32 s21, 30
	s_barrier
	s_cbranch_scc1 .LBB0_338
	s_setprio 0
	s_andn2_b64 vcc, exec, s[38:39]
	s_cbranch_vccnz .LBB0_341
	s_barrier

.Lprio_skip4:
.LBB0_655:
	ds_read_b128 v[120:123], v230
	ds_read_b128 v[132:135], v230 offset:1024
	ds_read_b128 v[136:139], v230 offset:2048
	ds_read_b128 v[140:143], v230 offset:3072
	ds_read_b128 v[144:147], v231
	ds_read_b128 v[148:151], v231 offset:1024
	ds_read_b128 v[152:155], v231 offset:2048
	ds_read_b128 v[156:159], v231 offset:3072
	s_add_u32 s28, s0, s2
	s_addc_u32 s29, s1, s3
	s_cmpk_eq_i32 s2, 0x1000
	s_cselect_b32 s30, 0, s2
	s_cselect_b32 s31, 0, s3
	s_cselect_b32 s28, s57, s28
	s_cselect_b32 s29, s7, s29
	s_add_u32 s30, s10, s30
	s_addc_u32 s31, s11, s31
	s_add_u32 s98, s2, s86
	s_addc_u32 s99, s3, s87
	s_add_i32 m0, s85, 0x8000
	v_lshl_add_u64 v[204:205], v[192:193], 0, s[98:99]
	ds_read_b128 v[160:163], v232
	ds_read_b128 v[164:167], v232 offset:1024
	ds_read_b128 v[168:171], v232 offset:2048
	ds_read_b128 v[172:175], v232 offset:3072
	ds_read_b128 v[176:179], v232 offset:4096
	ds_read_b128 v[180:183], v232 offset:5120
	ds_read_b128 v[196:199], v232 offset:6144
	ds_read_b128 v[200:203], v232 offset:7168
	global_load_lds_dwordx4 v[204:205], off
	s_add_u32 s98, s98, 0x20000
	s_addc_u32 s99, s99, 0
	s_add_i32 m0, s85, 0x9000
	v_lshl_add_u64 v[204:205], v[192:193], 0, s[98:99]
	global_load_lds_dwordx4 v[204:205], off
	s_add_u32 s98, s98, 0x20000
	s_addc_u32 s99, s99, 0
	s_add_i32 m0, s85, 0xa000
	v_lshl_add_u64 v[204:205], v[192:193], 0, s[98:99]
	global_load_lds_dwordx4 v[204:205], off
	s_add_u32 s98, s98, 0x20000
	s_addc_u32 s99, s99, 0
	s_add_i32 m0, s85, 0xb000
	v_lshl_add_u64 v[204:205], v[192:193], 0, s[98:99]
	global_load_lds_dwordx4 v[204:205], off
	s_waitcnt vmcnt(8)
	s_waitcnt lgkmcnt(0)
	s_barrier
	s_waitcnt lgkmcnt(0)
	v_mfma_f32_16x16x32_bf16 v[128:131], v[120:123], v[160:163], v[128:131]
	v_mfma_f32_16x16x32_bf16 v[124:127], v[136:139], v[160:163], v[124:127]
	v_mfma_f32_16x16x32_bf16 v[108:111], v[120:123], v[168:171], v[108:111]
	v_mfma_f32_16x16x32_bf16 v[104:107], v[136:139], v[168:171], v[104:107]
	v_mfma_f32_16x16x32_bf16 v[92:95], v[120:123], v[176:179], v[92:95]
	v_mfma_f32_16x16x32_bf16 v[88:91], v[136:139], v[176:179], v[88:91]
	v_mfma_f32_16x16x32_bf16 v[76:79], v[120:123], v[196:199], v[76:79]
	v_mfma_f32_16x16x32_bf16 v[72:75], v[136:139], v[196:199], v[72:75]
	v_mfma_f32_16x16x32_bf16 v[128:131], v[132:135], v[164:167], v[128:131]
	v_mfma_f32_16x16x32_bf16 v[124:127], v[140:143], v[164:167], v[124:127]
	v_mfma_f32_16x16x32_bf16 v[108:111], v[132:135], v[172:175], v[108:111]
	v_mfma_f32_16x16x32_bf16 v[104:107], v[140:143], v[172:175], v[104:107]
	v_mfma_f32_16x16x32_bf16 v[92:95], v[132:135], v[180:183], v[92:95]
	v_mfma_f32_16x16x32_bf16 v[88:91], v[140:143], v[180:183], v[88:91]
	v_mfma_f32_16x16x32_bf16 v[76:79], v[132:135], v[200:203], v[76:79]
	v_mfma_f32_16x16x32_bf16 v[72:75], v[140:143], v[200:203], v[72:75]
	v_mfma_f32_16x16x32_bf16 v[116:119], v[144:147], v[160:163], v[116:119]
	v_mfma_f32_16x16x32_bf16 v[112:115], v[152:155], v[160:163], v[112:115]
	v_mfma_f32_16x16x32_bf16 v[100:103], v[144:147], v[168:171], v[100:103]
	v_mfma_f32_16x16x32_bf16 v[96:99], v[152:155], v[168:171], v[96:99]
	v_mfma_f32_16x16x32_bf16 v[84:87], v[144:147], v[176:179], v[84:87]
	v_mfma_f32_16x16x32_bf16 v[80:83], v[152:155], v[176:179], v[80:83]
	v_mfma_f32_16x16x32_bf16 v[68:71], v[144:147], v[196:199], v[68:71]
	v_mfma_f32_16x16x32_bf16 v[64:67], v[152:155], v[196:199], v[64:67]
	v_mfma_f32_16x16x32_bf16 v[116:119], v[148:151], v[164:167], v[116:119]
	v_mfma_f32_16x16x32_bf16 v[112:115], v[156:159], v[164:167], v[112:115]
	v_mfma_f32_16x16x32_bf16 v[100:103], v[148:151], v[172:175], v[100:103]
	v_mfma_f32_16x16x32_bf16 v[96:99], v[156:159], v[172:175], v[96:99]
	v_mfma_f32_16x16x32_bf16 v[84:87], v[148:151], v[180:183], v[84:87]
	v_mfma_f32_16x16x32_bf16 v[80:83], v[156:159], v[180:183], v[80:83]
	v_mfma_f32_16x16x32_bf16 v[68:71], v[148:151], v[200:203], v[68:71]
	v_mfma_f32_16x16x32_bf16 v[64:67], v[156:159], v[200:203], v[64:67]
	s_barrier
	s_mov_b32 m0, s50
	v_lshl_add_u64 v[204:205], s[28:29], 0, v[188:189]
	s_add_u32 s60, s28, 0x80000
	ds_read_b128 v[160:163], v232 offset:16384
	ds_read_b128 v[164:167], v232 offset:17408
	ds_read_b128 v[168:171], v232 offset:18432
	ds_read_b128 v[172:175], v232 offset:19456
	ds_read_b128 v[176:179], v232 offset:20480
	ds_read_b128 v[180:183], v232 offset:21504
	ds_read_b128 v[196:199], v232 offset:22528
	ds_read_b128 v[200:203], v232 offset:23552
	global_load_lds_dwordx4 v[204:205], off
	v_lshl_add_u64 v[206:207], s[28:29], 0, v[184:185]
	s_mov_b32 m0, s51
	s_addc_u32 s61, s29, 0
	global_load_lds_dwordx4 v[206:207], off
	v_lshl_add_u64 v[208:209], s[60:61], 0, v[188:189]
	s_mov_b32 m0, s52
	global_load_lds_dwordx4 v[208:209], off
	v_lshl_add_u64 v[208:209], s[60:61], 0, v[184:185]
	s_mov_b32 m0, s53
	s_nop 0
	global_load_lds_dwordx4 v[208:209], off
	s_waitcnt vmcnt(8)
	s_waitcnt lgkmcnt(0)
	s_barrier
	s_waitcnt lgkmcnt(0)
	v_mfma_f32_16x16x32_bf16 v[60:63], v[120:123], v[160:163], v[60:63]
	v_mfma_f32_16x16x32_bf16 v[56:59], v[136:139], v[160:163], v[56:59]
	v_mfma_f32_16x16x32_bf16 v[44:47], v[120:123], v[168:171], v[44:47]
	v_mfma_f32_16x16x32_bf16 v[40:43], v[136:139], v[168:171], v[40:43]
	v_mfma_f32_16x16x32_bf16 v[28:31], v[120:123], v[176:179], v[28:31]
	v_mfma_f32_16x16x32_bf16 v[24:27], v[136:139], v[176:179], v[24:27]
	v_mfma_f32_16x16x32_bf16 v[12:15], v[120:123], v[196:199], v[12:15]
	v_mfma_f32_16x16x32_bf16 v[8:11], v[136:139], v[196:199], v[8:11]
	v_mfma_f32_16x16x32_bf16 v[60:63], v[132:135], v[164:167], v[60:63]
	v_mfma_f32_16x16x32_bf16 v[56:59], v[140:143], v[164:167], v[56:59]
	v_mfma_f32_16x16x32_bf16 v[44:47], v[132:135], v[172:175], v[44:47]
	v_mfma_f32_16x16x32_bf16 v[40:43], v[140:143], v[172:175], v[40:43]
	v_mfma_f32_16x16x32_bf16 v[28:31], v[132:135], v[180:183], v[28:31]
	v_mfma_f32_16x16x32_bf16 v[24:27], v[140:143], v[180:183], v[24:27]
	v_mfma_f32_16x16x32_bf16 v[12:15], v[132:135], v[200:203], v[12:15]
	v_mfma_f32_16x16x32_bf16 v[8:11], v[140:143], v[200:203], v[8:11]
	v_mfma_f32_16x16x32_bf16 v[52:55], v[144:147], v[160:163], v[52:55]
	v_mfma_f32_16x16x32_bf16 v[48:51], v[152:155], v[160:163], v[48:51]
	v_mfma_f32_16x16x32_bf16 v[36:39], v[144:147], v[168:171], v[36:39]
	v_mfma_f32_16x16x32_bf16 v[32:35], v[152:155], v[168:171], v[32:35]
	v_mfma_f32_16x16x32_bf16 v[20:23], v[144:147], v[176:179], v[20:23]
	v_mfma_f32_16x16x32_bf16 v[16:19], v[152:155], v[176:179], v[16:19]
	v_mfma_f32_16x16x32_bf16 v[4:7], v[144:147], v[196:199], v[4:7]
	v_mfma_f32_16x16x32_bf16 v[0:3], v[152:155], v[196:199], v[0:3]
	v_mfma_f32_16x16x32_bf16 v[52:55], v[148:151], v[164:167], v[52:55]
	v_mfma_f32_16x16x32_bf16 v[48:51], v[156:159], v[164:167], v[48:51]
	v_mfma_f32_16x16x32_bf16 v[36:39], v[148:151], v[172:175], v[36:39]
	v_mfma_f32_16x16x32_bf16 v[32:35], v[156:159], v[172:175], v[32:35]
	v_mfma_f32_16x16x32_bf16 v[20:23], v[148:151], v[180:183], v[20:23]
	v_mfma_f32_16x16x32_bf16 v[16:19], v[156:159], v[180:183], v[16:19]
	v_mfma_f32_16x16x32_bf16 v[4:7], v[148:151], v[200:203], v[4:7]
	v_mfma_f32_16x16x32_bf16 v[0:3], v[156:159], v[200:203], v[0:3]
	s_waitcnt vmcnt(4)
	s_barrier
	ds_read_b128 v[120:123], v234
	ds_read_b128 v[132:135], v234 offset:1024
	ds_read_b128 v[136:139], v234 offset:2048
	ds_read_b128 v[140:143], v234 offset:3072
	ds_read_b128 v[144:147], v235
	ds_read_b128 v[148:151], v235 offset:1024
	ds_read_b128 v[152:155], v235 offset:2048
	ds_read_b128 v[156:159], v235 offset:3072
	s_add_u32 s98, s30, s96
	s_addc_u32 s99, s31, s97
	s_add_i32 m0, s85, 0
	v_lshl_add_u64 v[212:213], s[98:99], 0, v[190:191]
	ds_read_b128 v[160:163], v232 offset:32768
	ds_read_b128 v[164:167], v232 offset:33792
	ds_read_b128 v[168:171], v232 offset:34816
	ds_read_b128 v[172:175], v232 offset:35840
	ds_read_b128 v[176:179], v232 offset:36864
	ds_read_b128 v[180:183], v232 offset:37888
	ds_read_b128 v[196:199], v232 offset:38912
	ds_read_b128 v[200:203], v232 offset:39936
	global_load_lds_dwordx4 v[212:213], off
	s_add_u32 s98, s98, 0x20000
	s_addc_u32 s99, s99, 0
	s_add_i32 m0, s85, 0x1000
	v_lshl_add_u64 v[212:213], s[98:99], 0, v[190:191]
	global_load_lds_dwordx4 v[212:213], off
	s_add_u32 s98, s98, 0x20000
	s_addc_u32 s99, s99, 0
	s_add_i32 m0, s85, 0x2000
	v_lshl_add_u64 v[212:213], s[98:99], 0, v[190:191]
	global_load_lds_dwordx4 v[212:213], off
	s_add_u32 s98, s98, 0x20000
	s_addc_u32 s99, s99, 0
	s_add_i32 m0, s85, 0x3000
	v_lshl_add_u64 v[212:213], s[98:99], 0, v[190:191]
	global_load_lds_dwordx4 v[212:213], off
	s_waitcnt vmcnt(8)
	s_waitcnt lgkmcnt(0)
	s_barrier
	s_waitcnt lgkmcnt(0)
	v_mfma_f32_16x16x32_bf16 v[128:131], v[120:123], v[160:163], v[128:131]
	v_mfma_f32_16x16x32_bf16 v[124:127], v[136:139], v[160:163], v[124:127]
	v_mfma_f32_16x16x32_bf16 v[108:111], v[120:123], v[168:171], v[108:111]
	v_mfma_f32_16x16x32_bf16 v[104:107], v[136:139], v[168:171], v[104:107]
	v_mfma_f32_16x16x32_bf16 v[92:95], v[120:123], v[176:179], v[92:95]
	v_mfma_f32_16x16x32_bf16 v[88:91], v[136:139], v[176:179], v[88:91]
	v_mfma_f32_16x16x32_bf16 v[76:79], v[120:123], v[196:199], v[76:79]
	v_mfma_f32_16x16x32_bf16 v[72:75], v[136:139], v[196:199], v[72:75]
	v_mfma_f32_16x16x32_bf16 v[128:131], v[132:135], v[164:167], v[128:131]
	v_mfma_f32_16x16x32_bf16 v[124:127], v[140:143], v[164:167], v[124:127]
	v_mfma_f32_16x16x32_bf16 v[108:111], v[132:135], v[172:175], v[108:111]
	v_mfma_f32_16x16x32_bf16 v[104:107], v[140:143], v[172:175], v[104:107]
	v_mfma_f32_16x16x32_bf16 v[92:95], v[132:135], v[180:183], v[92:95]
	v_mfma_f32_16x16x32_bf16 v[88:91], v[140:143], v[180:183], v[88:91]
	v_mfma_f32_16x16x32_bf16 v[76:79], v[132:135], v[200:203], v[76:79]
	v_mfma_f32_16x16x32_bf16 v[72:75], v[140:143], v[200:203], v[72:75]
	v_mfma_f32_16x16x32_bf16 v[116:119], v[144:147], v[160:163], v[116:119]
	v_mfma_f32_16x16x32_bf16 v[112:115], v[152:155], v[160:163], v[112:115]
	v_mfma_f32_16x16x32_bf16 v[100:103], v[144:147], v[168:171], v[100:103]
	v_mfma_f32_16x16x32_bf16 v[96:99], v[152:155], v[168:171], v[96:99]
	v_mfma_f32_16x16x32_bf16 v[84:87], v[144:147], v[176:179], v[84:87]
	v_mfma_f32_16x16x32_bf16 v[80:83], v[152:155], v[176:179], v[80:83]
	v_mfma_f32_16x16x32_bf16 v[68:71], v[144:147], v[196:199], v[68:71]
	v_mfma_f32_16x16x32_bf16 v[64:67], v[152:155], v[196:199], v[64:67]
	v_mfma_f32_16x16x32_bf16 v[116:119], v[148:151], v[164:167], v[116:119]
	v_mfma_f32_16x16x32_bf16 v[112:115], v[156:159], v[164:167], v[112:115]
	v_mfma_f32_16x16x32_bf16 v[100:103], v[148:151], v[172:175], v[100:103]
	v_mfma_f32_16x16x32_bf16 v[96:99], v[156:159], v[172:175], v[96:99]
	v_mfma_f32_16x16x32_bf16 v[84:87], v[148:151], v[180:183], v[84:87]
	v_mfma_f32_16x16x32_bf16 v[80:83], v[156:159], v[180:183], v[80:83]
	v_mfma_f32_16x16x32_bf16 v[68:71], v[148:151], v[200:203], v[68:71]
	v_mfma_f32_16x16x32_bf16 v[64:67], v[156:159], v[200:203], v[64:67]
	s_barrier
	s_mov_b32 m0, s55
	v_lshl_add_u64 v[204:205], v[204:205], 0, s[18:19]
	ds_read_b128 v[160:163], v232 offset:49152
	ds_read_b128 v[164:167], v232 offset:50176
	ds_read_b128 v[168:171], v232 offset:51200
	ds_read_b128 v[172:175], v232 offset:52224
	ds_read_b128 v[176:179], v232 offset:53248
	ds_read_b128 v[180:183], v232 offset:54272
	ds_read_b128 v[196:199], v232 offset:55296
	ds_read_b128 v[200:203], v232 offset:56320
	global_load_lds_dwordx4 v[204:205], off
	s_add_i32 m0, s55, 0x2000
	s_add_u32 s28, s28, 0x80080
	v_lshl_add_u64 v[204:205], v[206:207], 0, s[18:19]
	s_addc_u32 s29, s29, 0
	s_add_i32 s30, s54, s37
	global_load_lds_dwordx4 v[204:205], off
	v_lshl_add_u64 v[204:205], s[28:29], 0, v[188:189]
	s_mov_b32 m0, s30
	s_nop 0
	global_load_lds_dwordx4 v[204:205], off
	v_lshl_add_u64 v[204:205], s[28:29], 0, v[184:185]
	s_add_i32 m0, s30, 0x2000
	s_nop 0
	global_load_lds_dwordx4 v[204:205], off
	s_waitcnt vmcnt(8)
	s_waitcnt lgkmcnt(0)
	s_barrier
	s_waitcnt lgkmcnt(0)
	v_mfma_f32_16x16x32_bf16 v[60:63], v[120:123], v[160:163], v[60:63]
	v_mfma_f32_16x16x32_bf16 v[56:59], v[136:139], v[160:163], v[56:59]
	v_mfma_f32_16x16x32_bf16 v[44:47], v[120:123], v[168:171], v[44:47]
	v_mfma_f32_16x16x32_bf16 v[40:43], v[136:139], v[168:171], v[40:43]
	v_mfma_f32_16x16x32_bf16 v[28:31], v[120:123], v[176:179], v[28:31]
	v_mfma_f32_16x16x32_bf16 v[24:27], v[136:139], v[176:179], v[24:27]
	v_mfma_f32_16x16x32_bf16 v[12:15], v[120:123], v[196:199], v[12:15]
	v_mfma_f32_16x16x32_bf16 v[8:11], v[136:139], v[196:199], v[8:11]
	v_mfma_f32_16x16x32_bf16 v[60:63], v[132:135], v[164:167], v[60:63]
	v_mfma_f32_16x16x32_bf16 v[56:59], v[140:143], v[164:167], v[56:59]
	v_mfma_f32_16x16x32_bf16 v[44:47], v[132:135], v[172:175], v[44:47]
	v_mfma_f32_16x16x32_bf16 v[40:43], v[140:143], v[172:175], v[40:43]
	v_mfma_f32_16x16x32_bf16 v[28:31], v[132:135], v[180:183], v[28:31]
	v_mfma_f32_16x16x32_bf16 v[24:27], v[140:143], v[180:183], v[24:27]
	v_mfma_f32_16x16x32_bf16 v[12:15], v[132:135], v[200:203], v[12:15]
	v_mfma_f32_16x16x32_bf16 v[8:11], v[140:143], v[200:203], v[8:11]
	v_mfma_f32_16x16x32_bf16 v[52:55], v[144:147], v[160:163], v[52:55]
	v_mfma_f32_16x16x32_bf16 v[48:51], v[152:155], v[160:163], v[48:51]
	v_mfma_f32_16x16x32_bf16 v[36:39], v[144:147], v[168:171], v[36:39]
	v_mfma_f32_16x16x32_bf16 v[32:35], v[152:155], v[168:171], v[32:35]
	v_mfma_f32_16x16x32_bf16 v[20:23], v[144:147], v[176:179], v[20:23]
	v_mfma_f32_16x16x32_bf16 v[16:19], v[152:155], v[176:179], v[16:19]
	v_mfma_f32_16x16x32_bf16 v[4:7], v[144:147], v[196:199], v[4:7]
	v_mfma_f32_16x16x32_bf16 v[0:3], v[152:155], v[196:199], v[0:3]
	v_mfma_f32_16x16x32_bf16 v[52:55], v[148:151], v[164:167], v[52:55]
	v_mfma_f32_16x16x32_bf16 v[48:51], v[156:159], v[164:167], v[48:51]
	v_mfma_f32_16x16x32_bf16 v[36:39], v[148:151], v[172:175], v[36:39]
	v_mfma_f32_16x16x32_bf16 v[32:35], v[156:159], v[172:175], v[32:35]
	v_mfma_f32_16x16x32_bf16 v[20:23], v[148:151], v[180:183], v[20:23]
	v_mfma_f32_16x16x32_bf16 v[16:19], v[156:159], v[180:183], v[16:19]
	v_mfma_f32_16x16x32_bf16 v[4:7], v[148:151], v[200:203], v[4:7]
	v_mfma_f32_16x16x32_bf16 v[0:3], v[156:159], v[200:203], v[0:3]
	s_waitcnt vmcnt(4)
	s_add_i32 s58, s58, 2
	s_add_u32 s2, s2, 0x100
	s_addc_u32 s3, s3, 0
	s_cmp_gt_u32 s58, 29
	s_barrier
	s_cbranch_scc0 .LBB0_655
	s_setprio 0
	s_and_b64 vcc, exec, s[22:23]
	s_cbranch_vccz .LBB0_658
	s_barrier

.Lprio_skip5:
.LBB0_785:
	ds_read_b128 v[140:143], v148
	ds_read_b128 v[154:157], v148 offset:1024
	ds_read_b128 v[158:161], v148 offset:2048
	ds_read_b128 v[162:165], v148 offset:3072
	ds_read_b128 v[166:169], v149
	ds_read_b128 v[170:173], v149 offset:1024
	ds_read_b128 v[174:177], v149 offset:2048
	ds_read_b128 v[178:181], v149 offset:3072
	s_add_u32 s38, s36, 0xfff80080
	s_addc_u32 s39, s37, -1
	s_cmp_eq_u32 s75, 28
	s_cselect_b32 s41, s69, s39
	s_cselect_b32 s40, s70, s38
	s_cselect_b32 s39, s71, s74
	s_cselect_b32 s38, s72, s73
	s_sub_u32 s98, s36, 0x80000
	s_subb_u32 s99, s37, 0
	s_add_i32 m0, s85, 0x8000
	ds_read_b128 v[182:185], v150
	ds_read_b128 v[186:189], v150 offset:1024
	ds_read_b128 v[190:193], v150 offset:2048
	ds_read_b128 v[194:197], v150 offset:3072
	ds_read_b128 v[198:201], v150 offset:4096
	ds_read_b128 v[202:205], v150 offset:5120
	ds_read_b128 v[206:209], v150 offset:6144
	ds_read_b128 v[210:213], v150 offset:7168
	global_load_lds_dwordx4 v222, s[98:99]
	s_add_u32 s98, s98, 0x20000
	s_addc_u32 s99, s99, 0
	s_add_i32 m0, s85, 0x9000
	s_nop 0
	global_load_lds_dwordx4 v222, s[98:99]
	s_add_u32 s98, s98, 0x20000
	s_addc_u32 s99, s99, 0
	s_add_i32 m0, s85, 0xa000
	s_nop 0
	global_load_lds_dwordx4 v222, s[98:99]
	s_add_u32 s98, s98, 0x20000
	s_addc_u32 s99, s99, 0
	s_add_i32 m0, s85, 0xb000
	s_nop 0
	global_load_lds_dwordx4 v222, s[98:99]
	s_waitcnt vmcnt(8)
	s_waitcnt lgkmcnt(0)
	s_barrier
	s_waitcnt lgkmcnt(0)
	v_mfma_f32_16x16x32_bf16 v[124:127], v[140:143], v[182:185], v[124:127]
	v_mfma_f32_16x16x32_bf16 v[120:123], v[158:161], v[182:185], v[120:123]
	v_mfma_f32_16x16x32_bf16 v[112:115], v[140:143], v[190:193], v[112:115]
	v_mfma_f32_16x16x32_bf16 v[104:107], v[158:161], v[190:193], v[104:107]
	v_mfma_f32_16x16x32_bf16 v[96:99], v[140:143], v[198:201], v[96:99]
	v_mfma_f32_16x16x32_bf16 v[88:91], v[158:161], v[198:201], v[88:91]
	v_mfma_f32_16x16x32_bf16 v[80:83], v[140:143], v[206:209], v[80:83]
	v_mfma_f32_16x16x32_bf16 v[72:75], v[158:161], v[206:209], v[72:75]
	v_mfma_f32_16x16x32_bf16 v[124:127], v[154:157], v[186:189], v[124:127]
	v_mfma_f32_16x16x32_bf16 v[120:123], v[162:165], v[186:189], v[120:123]
	v_mfma_f32_16x16x32_bf16 v[112:115], v[154:157], v[194:197], v[112:115]
	v_mfma_f32_16x16x32_bf16 v[104:107], v[162:165], v[194:197], v[104:107]
	v_mfma_f32_16x16x32_bf16 v[96:99], v[154:157], v[202:205], v[96:99]
	v_mfma_f32_16x16x32_bf16 v[88:91], v[162:165], v[202:205], v[88:91]
	v_mfma_f32_16x16x32_bf16 v[80:83], v[154:157], v[210:213], v[80:83]
	v_mfma_f32_16x16x32_bf16 v[72:75], v[162:165], v[210:213], v[72:75]
	v_mfma_f32_16x16x32_bf16 v[116:119], v[166:169], v[182:185], v[116:119]
	v_mfma_f32_16x16x32_bf16 v[108:111], v[174:177], v[182:185], v[108:111]
	v_mfma_f32_16x16x32_bf16 v[100:103], v[166:169], v[190:193], v[100:103]
	v_mfma_f32_16x16x32_bf16 v[92:95], v[174:177], v[190:193], v[92:95]
	v_mfma_f32_16x16x32_bf16 v[84:87], v[166:169], v[198:201], v[84:87]
	v_mfma_f32_16x16x32_bf16 v[76:79], v[174:177], v[198:201], v[76:79]
	v_mfma_f32_16x16x32_bf16 v[68:71], v[166:169], v[206:209], v[68:71]
	v_mfma_f32_16x16x32_bf16 v[64:67], v[174:177], v[206:209], v[64:67]
	v_mfma_f32_16x16x32_bf16 v[116:119], v[170:173], v[186:189], v[116:119]
	v_mfma_f32_16x16x32_bf16 v[108:111], v[178:181], v[186:189], v[108:111]
	v_mfma_f32_16x16x32_bf16 v[100:103], v[170:173], v[194:197], v[100:103]
	v_mfma_f32_16x16x32_bf16 v[92:95], v[178:181], v[194:197], v[92:95]
	v_mfma_f32_16x16x32_bf16 v[84:87], v[170:173], v[202:205], v[84:87]
	v_mfma_f32_16x16x32_bf16 v[76:79], v[178:181], v[202:205], v[76:79]
	v_mfma_f32_16x16x32_bf16 v[68:71], v[170:173], v[210:213], v[68:71]
	v_mfma_f32_16x16x32_bf16 v[64:67], v[178:181], v[210:213], v[64:67]
	s_barrier
	s_add_i32 s76, s59, s5
	v_lshl_add_u64 v[144:145], s[38:39], 0, v[130:131]
	s_mov_b32 m0, s76
	ds_read_b128 v[182:185], v150 offset:16384
	ds_read_b128 v[186:189], v150 offset:17408
	ds_read_b128 v[190:193], v150 offset:18432
	ds_read_b128 v[194:197], v150 offset:19456
	ds_read_b128 v[198:201], v150 offset:20480
	ds_read_b128 v[202:205], v150 offset:21504
	ds_read_b128 v[206:209], v150 offset:22528
	ds_read_b128 v[210:213], v150 offset:23552
	global_load_lds_dwordx4 v[144:145], off
	s_add_i32 m0, s76, 0x2000
	s_add_u32 s76, s38, 0x80000
	v_lshl_add_u64 v[214:215], s[38:39], 0, v[134:135]
	s_addc_u32 s77, s39, 0
	s_add_i32 s78, s60, s5
	global_load_lds_dwordx4 v[214:215], off
	v_lshl_add_u64 v[216:217], s[76:77], 0, v[130:131]
	s_mov_b32 m0, s78
	global_load_lds_dwordx4 v[216:217], off
	v_lshl_add_u64 v[216:217], s[76:77], 0, v[134:135]
	s_add_i32 m0, s78, 0x2000
	s_nop 0
	global_load_lds_dwordx4 v[216:217], off
	s_waitcnt vmcnt(8)
	s_waitcnt lgkmcnt(0)
	s_barrier
	s_waitcnt lgkmcnt(0)
	v_mfma_f32_16x16x32_bf16 v[60:63], v[140:143], v[182:185], v[60:63]
	v_mfma_f32_16x16x32_bf16 v[56:59], v[158:161], v[182:185], v[56:59]
	v_mfma_f32_16x16x32_bf16 v[48:51], v[140:143], v[190:193], v[48:51]
	v_mfma_f32_16x16x32_bf16 v[40:43], v[158:161], v[190:193], v[40:43]
	v_mfma_f32_16x16x32_bf16 v[32:35], v[140:143], v[198:201], v[32:35]
	v_mfma_f32_16x16x32_bf16 v[24:27], v[158:161], v[198:201], v[24:27]
	v_mfma_f32_16x16x32_bf16 v[16:19], v[140:143], v[206:209], v[16:19]
	v_mfma_f32_16x16x32_bf16 v[8:11], v[158:161], v[206:209], v[8:11]
	v_mfma_f32_16x16x32_bf16 v[60:63], v[154:157], v[186:189], v[60:63]
	v_mfma_f32_16x16x32_bf16 v[56:59], v[162:165], v[186:189], v[56:59]
	v_mfma_f32_16x16x32_bf16 v[48:51], v[154:157], v[194:197], v[48:51]
	v_mfma_f32_16x16x32_bf16 v[40:43], v[162:165], v[194:197], v[40:43]
	v_mfma_f32_16x16x32_bf16 v[32:35], v[154:157], v[202:205], v[32:35]
	v_mfma_f32_16x16x32_bf16 v[24:27], v[162:165], v[202:205], v[24:27]
	v_mfma_f32_16x16x32_bf16 v[16:19], v[154:157], v[210:213], v[16:19]
	v_mfma_f32_16x16x32_bf16 v[8:11], v[162:165], v[210:213], v[8:11]
	v_mfma_f32_16x16x32_bf16 v[52:55], v[166:169], v[182:185], v[52:55]
	v_mfma_f32_16x16x32_bf16 v[44:47], v[174:177], v[182:185], v[44:47]
	v_mfma_f32_16x16x32_bf16 v[36:39], v[166:169], v[190:193], v[36:39]
	v_mfma_f32_16x16x32_bf16 v[28:31], v[174:177], v[190:193], v[28:31]
	v_mfma_f32_16x16x32_bf16 v[20:23], v[166:169], v[198:201], v[20:23]
	v_mfma_f32_16x16x32_bf16 v[12:15], v[174:177], v[198:201], v[12:15]
	v_mfma_f32_16x16x32_bf16 v[4:7], v[166:169], v[206:209], v[4:7]
	v_mfma_f32_16x16x32_bf16 v[0:3], v[174:177], v[206:209], v[0:3]
	v_mfma_f32_16x16x32_bf16 v[52:55], v[170:173], v[186:189], v[52:55]
	v_mfma_f32_16x16x32_bf16 v[44:47], v[178:181], v[186:189], v[44:47]
	v_mfma_f32_16x16x32_bf16 v[36:39], v[170:173], v[194:197], v[36:39]
	v_mfma_f32_16x16x32_bf16 v[28:31], v[178:181], v[194:197], v[28:31]
	v_mfma_f32_16x16x32_bf16 v[20:23], v[170:173], v[202:205], v[20:23]
	v_mfma_f32_16x16x32_bf16 v[12:15], v[178:181], v[202:205], v[12:15]
	v_mfma_f32_16x16x32_bf16 v[4:7], v[170:173], v[210:213], v[4:7]
	v_mfma_f32_16x16x32_bf16 v[0:3], v[178:181], v[210:213], v[0:3]
	s_waitcnt vmcnt(4)
	s_barrier
	ds_read_b128 v[140:143], v151
	ds_read_b128 v[154:157], v151 offset:1024
	ds_read_b128 v[158:161], v151 offset:2048
	ds_read_b128 v[162:165], v151 offset:3072
	ds_read_b128 v[166:169], v152
	ds_read_b128 v[170:173], v152 offset:1024
	ds_read_b128 v[174:177], v152 offset:2048
	ds_read_b128 v[178:181], v152 offset:3072
	s_mov_b32 s98, s40
	s_mov_b32 s99, s41
	s_add_i32 m0, s85, 0
	ds_read_b128 v[182:185], v150 offset:32768
	ds_read_b128 v[186:189], v150 offset:33792
	ds_read_b128 v[190:193], v150 offset:34816
	ds_read_b128 v[194:197], v150 offset:35840
	ds_read_b128 v[198:201], v150 offset:36864
	ds_read_b128 v[202:205], v150 offset:37888
	ds_read_b128 v[206:209], v150 offset:38912
	ds_read_b128 v[210:213], v150 offset:39936
	global_load_lds_dwordx4 v222, s[98:99]
	s_add_u32 s98, s98, 0x20000
	s_addc_u32 s99, s99, 0
	s_add_i32 m0, s85, 0x1000
	s_nop 0
	global_load_lds_dwordx4 v222, s[98:99]
	s_add_u32 s98, s98, 0x20000
	s_addc_u32 s99, s99, 0
	s_add_i32 m0, s85, 0x2000
	s_nop 0
	global_load_lds_dwordx4 v222, s[98:99]
	s_add_u32 s98, s98, 0x20000
	s_addc_u32 s99, s99, 0
	s_add_i32 m0, s85, 0x3000
	s_nop 0
	global_load_lds_dwordx4 v222, s[98:99]
	s_waitcnt vmcnt(8)
	s_waitcnt lgkmcnt(0)
	s_barrier
	s_waitcnt lgkmcnt(0)
	v_mfma_f32_16x16x32_bf16 v[124:127], v[140:143], v[182:185], v[124:127]
	v_mfma_f32_16x16x32_bf16 v[120:123], v[158:161], v[182:185], v[120:123]
	v_mfma_f32_16x16x32_bf16 v[112:115], v[140:143], v[190:193], v[112:115]
	v_mfma_f32_16x16x32_bf16 v[104:107], v[158:161], v[190:193], v[104:107]
	v_mfma_f32_16x16x32_bf16 v[96:99], v[140:143], v[198:201], v[96:99]
	v_mfma_f32_16x16x32_bf16 v[88:91], v[158:161], v[198:201], v[88:91]
	v_mfma_f32_16x16x32_bf16 v[80:83], v[140:143], v[206:209], v[80:83]
	v_mfma_f32_16x16x32_bf16 v[72:75], v[158:161], v[206:209], v[72:75]
	v_mfma_f32_16x16x32_bf16 v[124:127], v[154:157], v[186:189], v[124:127]
	v_mfma_f32_16x16x32_bf16 v[120:123], v[162:165], v[186:189], v[120:123]
	v_mfma_f32_16x16x32_bf16 v[112:115], v[154:157], v[194:197], v[112:115]
	v_mfma_f32_16x16x32_bf16 v[104:107], v[162:165], v[194:197], v[104:107]
	v_mfma_f32_16x16x32_bf16 v[96:99], v[154:157], v[202:205], v[96:99]
	v_mfma_f32_16x16x32_bf16 v[88:91], v[162:165], v[202:205], v[88:91]
	v_mfma_f32_16x16x32_bf16 v[80:83], v[154:157], v[210:213], v[80:83]
	v_mfma_f32_16x16x32_bf16 v[72:75], v[162:165], v[210:213], v[72:75]
	v_mfma_f32_16x16x32_bf16 v[116:119], v[166:169], v[182:185], v[116:119]
	v_mfma_f32_16x16x32_bf16 v[108:111], v[174:177], v[182:185], v[108:111]
	v_mfma_f32_16x16x32_bf16 v[100:103], v[166:169], v[190:193], v[100:103]
	v_mfma_f32_16x16x32_bf16 v[92:95], v[174:177], v[190:193], v[92:95]
	v_mfma_f32_16x16x32_bf16 v[84:87], v[166:169], v[198:201], v[84:87]
	v_mfma_f32_16x16x32_bf16 v[76:79], v[174:177], v[198:201], v[76:79]
	v_mfma_f32_16x16x32_bf16 v[68:71], v[166:169], v[206:209], v[68:71]
	v_mfma_f32_16x16x32_bf16 v[64:67], v[174:177], v[206:209], v[64:67]
	v_mfma_f32_16x16x32_bf16 v[116:119], v[170:173], v[186:189], v[116:119]
	v_mfma_f32_16x16x32_bf16 v[108:111], v[178:181], v[186:189], v[108:111]
	v_mfma_f32_16x16x32_bf16 v[100:103], v[170:173], v[194:197], v[100:103]
	v_mfma_f32_16x16x32_bf16 v[92:95], v[178:181], v[194:197], v[92:95]
	v_mfma_f32_16x16x32_bf16 v[84:87], v[170:173], v[202:205], v[84:87]
	v_mfma_f32_16x16x32_bf16 v[76:79], v[178:181], v[202:205], v[76:79]
	v_mfma_f32_16x16x32_bf16 v[68:71], v[170:173], v[210:213], v[68:71]
	v_mfma_f32_16x16x32_bf16 v[64:67], v[178:181], v[210:213], v[64:67]
	s_barrier
	s_add_i32 s40, s61, s5
	v_lshl_add_u64 v[144:145], v[144:145], 0, s[12:13]
	s_mov_b32 m0, s40
	ds_read_b128 v[182:185], v150 offset:49152
	ds_read_b128 v[186:189], v150 offset:50176
	ds_read_b128 v[190:193], v150 offset:51200
	ds_read_b128 v[194:197], v150 offset:52224
	ds_read_b128 v[198:201], v150 offset:53248
	ds_read_b128 v[202:205], v150 offset:54272
	ds_read_b128 v[206:209], v150 offset:55296
	ds_read_b128 v[210:213], v150 offset:56320
	global_load_lds_dwordx4 v[144:145], off
	s_add_i32 m0, s40, 0x2000
	s_add_u32 s38, s38, 0x80080
	v_lshl_add_u64 v[144:145], v[214:215], 0, s[12:13]
	s_addc_u32 s39, s39, 0
	s_add_i32 s40, s62, s5
	global_load_lds_dwordx4 v[144:145], off
	v_lshl_add_u64 v[144:145], s[38:39], 0, v[130:131]
	s_mov_b32 m0, s40
	s_nop 0
	global_load_lds_dwordx4 v[144:145], off
	v_lshl_add_u64 v[144:145], s[38:39], 0, v[134:135]
	s_add_i32 m0, s40, 0x2000
	s_nop 0
	global_load_lds_dwordx4 v[144:145], off
	s_waitcnt vmcnt(8)
	s_waitcnt lgkmcnt(0)
	s_barrier
	s_waitcnt lgkmcnt(0)
	v_mfma_f32_16x16x32_bf16 v[60:63], v[140:143], v[182:185], v[60:63]
	v_mfma_f32_16x16x32_bf16 v[56:59], v[158:161], v[182:185], v[56:59]
	v_mfma_f32_16x16x32_bf16 v[48:51], v[140:143], v[190:193], v[48:51]
	v_mfma_f32_16x16x32_bf16 v[40:43], v[158:161], v[190:193], v[40:43]
	v_mfma_f32_16x16x32_bf16 v[32:35], v[140:143], v[198:201], v[32:35]
	v_mfma_f32_16x16x32_bf16 v[24:27], v[158:161], v[198:201], v[24:27]
	v_mfma_f32_16x16x32_bf16 v[16:19], v[140:143], v[206:209], v[16:19]
	v_mfma_f32_16x16x32_bf16 v[8:11], v[158:161], v[206:209], v[8:11]
	v_mfma_f32_16x16x32_bf16 v[60:63], v[154:157], v[186:189], v[60:63]
	v_mfma_f32_16x16x32_bf16 v[56:59], v[162:165], v[186:189], v[56:59]
	v_mfma_f32_16x16x32_bf16 v[48:51], v[154:157], v[194:197], v[48:51]
	v_mfma_f32_16x16x32_bf16 v[40:43], v[162:165], v[194:197], v[40:43]
	v_mfma_f32_16x16x32_bf16 v[32:35], v[154:157], v[202:205], v[32:35]
	v_mfma_f32_16x16x32_bf16 v[24:27], v[162:165], v[202:205], v[24:27]
	v_mfma_f32_16x16x32_bf16 v[16:19], v[154:157], v[210:213], v[16:19]
	v_mfma_f32_16x16x32_bf16 v[8:11], v[162:165], v[210:213], v[8:11]
	v_mfma_f32_16x16x32_bf16 v[52:55], v[166:169], v[182:185], v[52:55]
	v_mfma_f32_16x16x32_bf16 v[44:47], v[174:177], v[182:185], v[44:47]
	v_mfma_f32_16x16x32_bf16 v[36:39], v[166:169], v[190:193], v[36:39]
	v_mfma_f32_16x16x32_bf16 v[28:31], v[174:177], v[190:193], v[28:31]
	v_mfma_f32_16x16x32_bf16 v[20:23], v[166:169], v[198:201], v[20:23]
	v_mfma_f32_16x16x32_bf16 v[12:15], v[174:177], v[198:201], v[12:15]
	v_mfma_f32_16x16x32_bf16 v[4:7], v[166:169], v[206:209], v[4:7]
	v_mfma_f32_16x16x32_bf16 v[0:3], v[174:177], v[206:209], v[0:3]
	v_mfma_f32_16x16x32_bf16 v[52:55], v[170:173], v[186:189], v[52:55]
	v_mfma_f32_16x16x32_bf16 v[44:47], v[178:181], v[186:189], v[44:47]
	v_mfma_f32_16x16x32_bf16 v[36:39], v[170:173], v[194:197], v[36:39]
	v_mfma_f32_16x16x32_bf16 v[28:31], v[178:181], v[194:197], v[28:31]
	v_mfma_f32_16x16x32_bf16 v[20:23], v[170:173], v[202:205], v[20:23]
	v_mfma_f32_16x16x32_bf16 v[12:15], v[178:181], v[202:205], v[12:15]
	v_mfma_f32_16x16x32_bf16 v[4:7], v[170:173], v[210:213], v[4:7]
	v_mfma_f32_16x16x32_bf16 v[0:3], v[178:181], v[210:213], v[0:3]
	s_waitcnt vmcnt(4)
	s_add_i32 s75, s75, 2
	s_add_u32 s36, s36, 0x100
	s_addc_u32 s37, s37, 0
	s_add_u32 s73, s73, 0x100
	s_addc_u32 s74, s74, 0
	s_cmp_gt_u32 s75, 29
	s_barrier
	s_cbranch_scc0 .LBB0_785
	s_setprio 0
	s_and_b64 vcc, exec, s[14:15]
	s_cbranch_vccz .LBB0_788
	s_barrier

.Lprio_skip7:
.LBB0_1084:
	ds_read_b128 v[140:143], v150
	ds_read_b128 v[144:147], v150 offset:1024
	ds_read_b128 v[156:159], v150 offset:2048
	ds_read_b128 v[160:163], v150 offset:3072
	ds_read_b128 v[164:167], v151
	ds_read_b128 v[168:171], v151 offset:1024
	ds_read_b128 v[172:175], v151 offset:2048
	ds_read_b128 v[176:179], v151 offset:3072
	s_add_u32 s36, s0, 0xfff80080
	s_addc_u32 s37, s1, -1
	s_cmp_eq_u32 s74, 28
	s_cselect_b32 s39, s68, s37
	s_cselect_b32 s38, s69, s36
	s_cselect_b32 s37, s70, s73
	s_cselect_b32 s36, s71, s72
	s_sub_u32 s98, s0, 0x80000
	s_subb_u32 s99, s1, 0
	s_add_i32 m0, s85, 0x8000
	ds_read_b128 v[180:183], v152
	ds_read_b128 v[184:187], v152 offset:1024
	ds_read_b128 v[188:191], v152 offset:2048
	ds_read_b128 v[192:195], v152 offset:3072
	ds_read_b128 v[196:199], v152 offset:4096
	ds_read_b128 v[200:203], v152 offset:5120
	ds_read_b128 v[204:207], v152 offset:6144
	ds_read_b128 v[208:211], v152 offset:7168
	global_load_lds_dwordx4 v222, s[98:99]
	s_add_u32 s98, s98, 0x20000
	s_addc_u32 s99, s99, 0
	s_add_i32 m0, s85, 0x9000
	s_nop 0
	global_load_lds_dwordx4 v222, s[98:99]
	s_add_u32 s98, s98, 0x20000
	s_addc_u32 s99, s99, 0
	s_add_i32 m0, s85, 0xa000
	s_nop 0
	global_load_lds_dwordx4 v222, s[98:99]
	s_add_u32 s98, s98, 0x20000
	s_addc_u32 s99, s99, 0
	s_add_i32 m0, s85, 0xb000
	s_nop 0
	global_load_lds_dwordx4 v222, s[98:99]
	s_waitcnt vmcnt(8)
	s_waitcnt lgkmcnt(0)
	s_barrier
	s_waitcnt lgkmcnt(0)
	v_mfma_f32_16x16x32_bf16 v[124:127], v[140:143], v[180:183], v[124:127]
	v_mfma_f32_16x16x32_bf16 v[120:123], v[156:159], v[180:183], v[120:123]
	v_mfma_f32_16x16x32_bf16 v[108:111], v[140:143], v[188:191], v[108:111]
	v_mfma_f32_16x16x32_bf16 v[104:107], v[156:159], v[188:191], v[104:107]
	v_mfma_f32_16x16x32_bf16 v[92:95], v[140:143], v[196:199], v[92:95]
	v_mfma_f32_16x16x32_bf16 v[88:91], v[156:159], v[196:199], v[88:91]
	v_mfma_f32_16x16x32_bf16 v[76:79], v[140:143], v[204:207], v[76:79]
	v_mfma_f32_16x16x32_bf16 v[72:75], v[156:159], v[204:207], v[72:75]
	v_mfma_f32_16x16x32_bf16 v[124:127], v[144:147], v[184:187], v[124:127]
	v_mfma_f32_16x16x32_bf16 v[120:123], v[160:163], v[184:187], v[120:123]
	v_mfma_f32_16x16x32_bf16 v[108:111], v[144:147], v[192:195], v[108:111]
	v_mfma_f32_16x16x32_bf16 v[104:107], v[160:163], v[192:195], v[104:107]
	v_mfma_f32_16x16x32_bf16 v[92:95], v[144:147], v[200:203], v[92:95]
	v_mfma_f32_16x16x32_bf16 v[88:91], v[160:163], v[200:203], v[88:91]
	v_mfma_f32_16x16x32_bf16 v[76:79], v[144:147], v[208:211], v[76:79]
	v_mfma_f32_16x16x32_bf16 v[72:75], v[160:163], v[208:211], v[72:75]
	v_mfma_f32_16x16x32_bf16 v[116:119], v[164:167], v[180:183], v[116:119]
	v_mfma_f32_16x16x32_bf16 v[112:115], v[172:175], v[180:183], v[112:115]
	v_mfma_f32_16x16x32_bf16 v[100:103], v[164:167], v[188:191], v[100:103]
	v_mfma_f32_16x16x32_bf16 v[96:99], v[172:175], v[188:191], v[96:99]
	v_mfma_f32_16x16x32_bf16 v[84:87], v[164:167], v[196:199], v[84:87]
	v_mfma_f32_16x16x32_bf16 v[80:83], v[172:175], v[196:199], v[80:83]
	v_mfma_f32_16x16x32_bf16 v[68:71], v[164:167], v[204:207], v[68:71]
	v_mfma_f32_16x16x32_bf16 v[64:67], v[172:175], v[204:207], v[64:67]
	v_mfma_f32_16x16x32_bf16 v[116:119], v[168:171], v[184:187], v[116:119]
	v_mfma_f32_16x16x32_bf16 v[112:115], v[176:179], v[184:187], v[112:115]
	v_mfma_f32_16x16x32_bf16 v[100:103], v[168:171], v[192:195], v[100:103]
	v_mfma_f32_16x16x32_bf16 v[96:99], v[176:179], v[192:195], v[96:99]
	v_mfma_f32_16x16x32_bf16 v[84:87], v[168:171], v[200:203], v[84:87]
	v_mfma_f32_16x16x32_bf16 v[80:83], v[176:179], v[200:203], v[80:83]
	v_mfma_f32_16x16x32_bf16 v[68:71], v[168:171], v[208:211], v[68:71]
	v_mfma_f32_16x16x32_bf16 v[64:67], v[176:179], v[208:211], v[64:67]
	s_barrier
	s_add_i32 s75, s56, s5
	v_lshl_add_u64 v[212:213], s[36:37], 0, v[130:131]
	s_mov_b32 m0, s75
	ds_read_b128 v[180:183], v152 offset:16384
	ds_read_b128 v[184:187], v152 offset:17408
	ds_read_b128 v[188:191], v152 offset:18432
	ds_read_b128 v[192:195], v152 offset:19456
	ds_read_b128 v[196:199], v152 offset:20480
	ds_read_b128 v[200:203], v152 offset:21504
	ds_read_b128 v[204:207], v152 offset:22528
	ds_read_b128 v[208:211], v152 offset:23552
	global_load_lds_dwordx4 v[212:213], off
	s_add_i32 m0, s75, 0x2000
	s_add_u32 s76, s36, 0x80000
	v_lshl_add_u64 v[214:215], s[36:37], 0, v[134:135]
	s_addc_u32 s77, s37, 0
	s_add_i32 s75, s57, s5
	global_load_lds_dwordx4 v[214:215], off
	v_lshl_add_u64 v[216:217], s[76:77], 0, v[130:131]
	s_mov_b32 m0, s75
	global_load_lds_dwordx4 v[216:217], off
	v_lshl_add_u64 v[216:217], s[76:77], 0, v[134:135]
	s_add_i32 m0, s75, 0x2000
	s_nop 0
	global_load_lds_dwordx4 v[216:217], off
	s_waitcnt vmcnt(8)
	s_waitcnt lgkmcnt(0)
	s_barrier
	s_waitcnt lgkmcnt(0)
	v_mfma_f32_16x16x32_bf16 v[60:63], v[140:143], v[180:183], v[60:63]
	v_mfma_f32_16x16x32_bf16 v[56:59], v[156:159], v[180:183], v[56:59]
	v_mfma_f32_16x16x32_bf16 v[44:47], v[140:143], v[188:191], v[44:47]
	v_mfma_f32_16x16x32_bf16 v[40:43], v[156:159], v[188:191], v[40:43]
	v_mfma_f32_16x16x32_bf16 v[28:31], v[140:143], v[196:199], v[28:31]
	v_mfma_f32_16x16x32_bf16 v[24:27], v[156:159], v[196:199], v[24:27]
	v_mfma_f32_16x16x32_bf16 v[12:15], v[140:143], v[204:207], v[12:15]
	v_mfma_f32_16x16x32_bf16 v[8:11], v[156:159], v[204:207], v[8:11]
	v_mfma_f32_16x16x32_bf16 v[60:63], v[144:147], v[184:187], v[60:63]
	v_mfma_f32_16x16x32_bf16 v[56:59], v[160:163], v[184:187], v[56:59]
	v_mfma_f32_16x16x32_bf16 v[44:47], v[144:147], v[192:195], v[44:47]
	v_mfma_f32_16x16x32_bf16 v[40:43], v[160:163], v[192:195], v[40:43]
	v_mfma_f32_16x16x32_bf16 v[28:31], v[144:147], v[200:203], v[28:31]
	v_mfma_f32_16x16x32_bf16 v[24:27], v[160:163], v[200:203], v[24:27]
	v_mfma_f32_16x16x32_bf16 v[12:15], v[144:147], v[208:211], v[12:15]
	v_mfma_f32_16x16x32_bf16 v[8:11], v[160:163], v[208:211], v[8:11]
	v_mfma_f32_16x16x32_bf16 v[52:55], v[164:167], v[180:183], v[52:55]
	v_mfma_f32_16x16x32_bf16 v[48:51], v[172:175], v[180:183], v[48:51]
	v_mfma_f32_16x16x32_bf16 v[36:39], v[164:167], v[188:191], v[36:39]
	v_mfma_f32_16x16x32_bf16 v[32:35], v[172:175], v[188:191], v[32:35]
	v_mfma_f32_16x16x32_bf16 v[20:23], v[164:167], v[196:199], v[20:23]
	v_mfma_f32_16x16x32_bf16 v[16:19], v[172:175], v[196:199], v[16:19]
	v_mfma_f32_16x16x32_bf16 v[4:7], v[164:167], v[204:207], v[4:7]
	v_mfma_f32_16x16x32_bf16 v[0:3], v[172:175], v[204:207], v[0:3]
	v_mfma_f32_16x16x32_bf16 v[52:55], v[168:171], v[184:187], v[52:55]
	v_mfma_f32_16x16x32_bf16 v[48:51], v[176:179], v[184:187], v[48:51]
	v_mfma_f32_16x16x32_bf16 v[36:39], v[168:171], v[192:195], v[36:39]
	v_mfma_f32_16x16x32_bf16 v[32:35], v[176:179], v[192:195], v[32:35]
	v_mfma_f32_16x16x32_bf16 v[20:23], v[168:171], v[200:203], v[20:23]
	v_mfma_f32_16x16x32_bf16 v[16:19], v[176:179], v[200:203], v[16:19]
	v_mfma_f32_16x16x32_bf16 v[4:7], v[168:171], v[208:211], v[4:7]
	v_mfma_f32_16x16x32_bf16 v[0:3], v[176:179], v[208:211], v[0:3]
	s_waitcnt vmcnt(4)
	s_barrier
	ds_read_b128 v[140:143], v153
	ds_read_b128 v[144:147], v153 offset:1024
	ds_read_b128 v[156:159], v153 offset:2048
	ds_read_b128 v[160:163], v153 offset:3072
	ds_read_b128 v[164:167], v154
	ds_read_b128 v[168:171], v154 offset:1024
	ds_read_b128 v[172:175], v154 offset:2048
	ds_read_b128 v[176:179], v154 offset:3072
	s_mov_b32 s98, s38
	s_mov_b32 s99, s39
	s_add_i32 m0, s85, 0
	ds_read_b128 v[180:183], v152 offset:32768
	ds_read_b128 v[184:187], v152 offset:33792
	ds_read_b128 v[188:191], v152 offset:34816
	ds_read_b128 v[192:195], v152 offset:35840
	ds_read_b128 v[196:199], v152 offset:36864
	ds_read_b128 v[200:203], v152 offset:37888
	ds_read_b128 v[204:207], v152 offset:38912
	ds_read_b128 v[208:211], v152 offset:39936
	global_load_lds_dwordx4 v222, s[98:99]
	s_add_u32 s98, s98, 0x20000
	s_addc_u32 s99, s99, 0
	s_add_i32 m0, s85, 0x1000
	s_nop 0
	global_load_lds_dwordx4 v222, s[98:99]
	s_add_u32 s98, s98, 0x20000
	s_addc_u32 s99, s99, 0
	s_add_i32 m0, s85, 0x2000
	s_nop 0
	global_load_lds_dwordx4 v222, s[98:99]
	s_add_u32 s98, s98, 0x20000
	s_addc_u32 s99, s99, 0
	s_add_i32 m0, s85, 0x3000
	s_nop 0
	global_load_lds_dwordx4 v222, s[98:99]
	s_waitcnt vmcnt(8)
	s_waitcnt lgkmcnt(0)
	s_barrier
	s_waitcnt lgkmcnt(0)
	v_mfma_f32_16x16x32_bf16 v[124:127], v[140:143], v[180:183], v[124:127]
	v_mfma_f32_16x16x32_bf16 v[120:123], v[156:159], v[180:183], v[120:123]
	v_mfma_f32_16x16x32_bf16 v[108:111], v[140:143], v[188:191], v[108:111]
	v_mfma_f32_16x16x32_bf16 v[104:107], v[156:159], v[188:191], v[104:107]
	v_mfma_f32_16x16x32_bf16 v[92:95], v[140:143], v[196:199], v[92:95]
	v_mfma_f32_16x16x32_bf16 v[88:91], v[156:159], v[196:199], v[88:91]
	v_mfma_f32_16x16x32_bf16 v[76:79], v[140:143], v[204:207], v[76:79]
	v_mfma_f32_16x16x32_bf16 v[72:75], v[156:159], v[204:207], v[72:75]
	v_mfma_f32_16x16x32_bf16 v[124:127], v[144:147], v[184:187], v[124:127]
	v_mfma_f32_16x16x32_bf16 v[120:123], v[160:163], v[184:187], v[120:123]
	v_mfma_f32_16x16x32_bf16 v[108:111], v[144:147], v[192:195], v[108:111]
	v_mfma_f32_16x16x32_bf16 v[104:107], v[160:163], v[192:195], v[104:107]
	v_mfma_f32_16x16x32_bf16 v[92:95], v[144:147], v[200:203], v[92:95]
	v_mfma_f32_16x16x32_bf16 v[88:91], v[160:163], v[200:203], v[88:91]
	v_mfma_f32_16x16x32_bf16 v[76:79], v[144:147], v[208:211], v[76:79]
	v_mfma_f32_16x16x32_bf16 v[72:75], v[160:163], v[208:211], v[72:75]
	v_mfma_f32_16x16x32_bf16 v[116:119], v[164:167], v[180:183], v[116:119]
	v_mfma_f32_16x16x32_bf16 v[112:115], v[172:175], v[180:183], v[112:115]
	v_mfma_f32_16x16x32_bf16 v[100:103], v[164:167], v[188:191], v[100:103]
	v_mfma_f32_16x16x32_bf16 v[96:99], v[172:175], v[188:191], v[96:99]
	v_mfma_f32_16x16x32_bf16 v[84:87], v[164:167], v[196:199], v[84:87]
	v_mfma_f32_16x16x32_bf16 v[80:83], v[172:175], v[196:199], v[80:83]
	v_mfma_f32_16x16x32_bf16 v[68:71], v[164:167], v[204:207], v[68:71]
	v_mfma_f32_16x16x32_bf16 v[64:67], v[172:175], v[204:207], v[64:67]
	v_mfma_f32_16x16x32_bf16 v[116:119], v[168:171], v[184:187], v[116:119]
	v_mfma_f32_16x16x32_bf16 v[112:115], v[176:179], v[184:187], v[112:115]
	v_mfma_f32_16x16x32_bf16 v[100:103], v[168:171], v[192:195], v[100:103]
	v_mfma_f32_16x16x32_bf16 v[96:99], v[176:179], v[192:195], v[96:99]
	v_mfma_f32_16x16x32_bf16 v[84:87], v[168:171], v[200:203], v[84:87]
	v_mfma_f32_16x16x32_bf16 v[80:83], v[176:179], v[200:203], v[80:83]
	v_mfma_f32_16x16x32_bf16 v[68:71], v[168:171], v[208:211], v[68:71]
	v_mfma_f32_16x16x32_bf16 v[64:67], v[176:179], v[208:211], v[64:67]
	s_barrier
	s_add_i32 s38, s58, s5
	v_lshl_add_u64 v[212:213], v[212:213], 0, s[14:15]
	s_mov_b32 m0, s38
	ds_read_b128 v[180:183], v152 offset:49152
	ds_read_b128 v[184:187], v152 offset:50176
	ds_read_b128 v[188:191], v152 offset:51200
	ds_read_b128 v[192:195], v152 offset:52224
	ds_read_b128 v[196:199], v152 offset:53248
	ds_read_b128 v[200:203], v152 offset:54272
	ds_read_b128 v[204:207], v152 offset:55296
	ds_read_b128 v[208:211], v152 offset:56320
	global_load_lds_dwordx4 v[212:213], off
	s_add_i32 m0, s38, 0x2000
	s_add_u32 s36, s36, 0x80080
	v_lshl_add_u64 v[212:213], v[214:215], 0, s[14:15]
	s_addc_u32 s37, s37, 0
	s_add_i32 s38, s59, s5
	global_load_lds_dwordx4 v[212:213], off
	v_lshl_add_u64 v[212:213], s[36:37], 0, v[130:131]
	s_mov_b32 m0, s38
	s_nop 0
	global_load_lds_dwordx4 v[212:213], off
	v_lshl_add_u64 v[212:213], s[36:37], 0, v[134:135]
	s_add_i32 m0, s38, 0x2000
	s_nop 0
	global_load_lds_dwordx4 v[212:213], off
	s_waitcnt vmcnt(8)
	s_waitcnt lgkmcnt(0)
	s_barrier
	s_waitcnt lgkmcnt(0)
	v_mfma_f32_16x16x32_bf16 v[60:63], v[140:143], v[180:183], v[60:63]
	v_mfma_f32_16x16x32_bf16 v[56:59], v[156:159], v[180:183], v[56:59]
	v_mfma_f32_16x16x32_bf16 v[44:47], v[140:143], v[188:191], v[44:47]
	v_mfma_f32_16x16x32_bf16 v[40:43], v[156:159], v[188:191], v[40:43]
	v_mfma_f32_16x16x32_bf16 v[28:31], v[140:143], v[196:199], v[28:31]
	v_mfma_f32_16x16x32_bf16 v[24:27], v[156:159], v[196:199], v[24:27]
	v_mfma_f32_16x16x32_bf16 v[12:15], v[140:143], v[204:207], v[12:15]
	v_mfma_f32_16x16x32_bf16 v[8:11], v[156:159], v[204:207], v[8:11]
	v_mfma_f32_16x16x32_bf16 v[60:63], v[144:147], v[184:187], v[60:63]
	v_mfma_f32_16x16x32_bf16 v[56:59], v[160:163], v[184:187], v[56:59]
	v_mfma_f32_16x16x32_bf16 v[44:47], v[144:147], v[192:195], v[44:47]
	v_mfma_f32_16x16x32_bf16 v[40:43], v[160:163], v[192:195], v[40:43]
	v_mfma_f32_16x16x32_bf16 v[28:31], v[144:147], v[200:203], v[28:31]
	v_mfma_f32_16x16x32_bf16 v[24:27], v[160:163], v[200:203], v[24:27]
	v_mfma_f32_16x16x32_bf16 v[12:15], v[144:147], v[208:211], v[12:15]
	v_mfma_f32_16x16x32_bf16 v[8:11], v[160:163], v[208:211], v[8:11]
	v_mfma_f32_16x16x32_bf16 v[52:55], v[164:167], v[180:183], v[52:55]
	v_mfma_f32_16x16x32_bf16 v[48:51], v[172:175], v[180:183], v[48:51]
	v_mfma_f32_16x16x32_bf16 v[36:39], v[164:167], v[188:191], v[36:39]
	v_mfma_f32_16x16x32_bf16 v[32:35], v[172:175], v[188:191], v[32:35]
	v_mfma_f32_16x16x32_bf16 v[20:23], v[164:167], v[196:199], v[20:23]
	v_mfma_f32_16x16x32_bf16 v[16:19], v[172:175], v[196:199], v[16:19]
	v_mfma_f32_16x16x32_bf16 v[4:7], v[164:167], v[204:207], v[4:7]
	v_mfma_f32_16x16x32_bf16 v[0:3], v[172:175], v[204:207], v[0:3]
	v_mfma_f32_16x16x32_bf16 v[52:55], v[168:171], v[184:187], v[52:55]
	v_mfma_f32_16x16x32_bf16 v[48:51], v[176:179], v[184:187], v[48:51]
	v_mfma_f32_16x16x32_bf16 v[36:39], v[168:171], v[192:195], v[36:39]
	v_mfma_f32_16x16x32_bf16 v[32:35], v[176:179], v[192:195], v[32:35]
	v_mfma_f32_16x16x32_bf16 v[20:23], v[168:171], v[200:203], v[20:23]
	v_mfma_f32_16x16x32_bf16 v[16:19], v[176:179], v[200:203], v[16:19]
	v_mfma_f32_16x16x32_bf16 v[4:7], v[168:171], v[208:211], v[4:7]
	v_mfma_f32_16x16x32_bf16 v[0:3], v[176:179], v[208:211], v[0:3]
	s_waitcnt vmcnt(4)
	s_add_i32 s74, s74, 2
	s_add_u32 s0, s0, 0x100
	s_addc_u32 s1, s1, 0
	s_add_u32 s72, s72, 0x100
	s_addc_u32 s73, s73, 0
	s_cmp_gt_u32 s74, 29
	s_barrier
	s_cbranch_scc0 .LBB0_1084
	s_setprio 0
	s_and_b64 vcc, exec, s[16:17]
	s_cbranch_vccz .LBB0_1087
	s_barrier

.Lprio_skip8:
.LBB0_1194:
	ds_read_b128 v[120:123], v230
	ds_read_b128 v[132:135], v230 offset:1024
	ds_read_b128 v[136:139], v230 offset:2048
	ds_read_b128 v[140:143], v230 offset:3072
	ds_read_b128 v[144:147], v231
	ds_read_b128 v[148:151], v231 offset:1024
	ds_read_b128 v[152:155], v231 offset:2048
	ds_read_b128 v[156:159], v231 offset:3072
	s_add_u32 s28, s0, s2
	s_addc_u32 s29, s1, s3
	s_cmpk_eq_i32 s2, 0x4000
	s_cselect_b32 s30, 0, s2
	s_cselect_b32 s31, 0, s3
	s_cselect_b32 s28, s57, s28
	s_cselect_b32 s29, s7, s29
	s_add_u32 s30, s10, s30
	s_addc_u32 s31, s11, s31
	s_add_u32 s98, s2, s86
	s_addc_u32 s99, s3, s87
	s_add_i32 m0, s85, 0x8000
	v_lshl_add_u64 v[204:205], v[192:193], 0, s[98:99]
	ds_read_b128 v[160:163], v232
	ds_read_b128 v[164:167], v232 offset:1024
	ds_read_b128 v[168:171], v232 offset:2048
	ds_read_b128 v[172:175], v232 offset:3072
	ds_read_b128 v[176:179], v232 offset:4096
	ds_read_b128 v[180:183], v232 offset:5120
	ds_read_b128 v[196:199], v232 offset:6144
	ds_read_b128 v[200:203], v232 offset:7168
	global_load_lds_dwordx4 v[204:205], off
	s_add_u32 s98, s98, 0x80000
	s_addc_u32 s99, s99, 0
	s_add_i32 m0, s85, 0x9000
	v_lshl_add_u64 v[204:205], v[192:193], 0, s[98:99]
	global_load_lds_dwordx4 v[204:205], off
	s_add_u32 s98, s98, 0x80000
	s_addc_u32 s99, s99, 0
	s_add_i32 m0, s85, 0xa000
	v_lshl_add_u64 v[204:205], v[192:193], 0, s[98:99]
	global_load_lds_dwordx4 v[204:205], off
	s_add_u32 s98, s98, 0x80000
	s_addc_u32 s99, s99, 0
	s_add_i32 m0, s85, 0xb000
	v_lshl_add_u64 v[204:205], v[192:193], 0, s[98:99]
	global_load_lds_dwordx4 v[204:205], off
	s_waitcnt vmcnt(8)
	s_waitcnt lgkmcnt(0)
	s_barrier
	s_waitcnt lgkmcnt(0)
	v_mfma_f32_16x16x32_bf16 v[128:131], v[120:123], v[160:163], v[128:131]
	v_mfma_f32_16x16x32_bf16 v[124:127], v[136:139], v[160:163], v[124:127]
	v_mfma_f32_16x16x32_bf16 v[108:111], v[120:123], v[168:171], v[108:111]
	v_mfma_f32_16x16x32_bf16 v[104:107], v[136:139], v[168:171], v[104:107]
	v_mfma_f32_16x16x32_bf16 v[92:95], v[120:123], v[176:179], v[92:95]
	v_mfma_f32_16x16x32_bf16 v[88:91], v[136:139], v[176:179], v[88:91]
	v_mfma_f32_16x16x32_bf16 v[76:79], v[120:123], v[196:199], v[76:79]
	v_mfma_f32_16x16x32_bf16 v[72:75], v[136:139], v[196:199], v[72:75]
	v_mfma_f32_16x16x32_bf16 v[128:131], v[132:135], v[164:167], v[128:131]
	v_mfma_f32_16x16x32_bf16 v[124:127], v[140:143], v[164:167], v[124:127]
	v_mfma_f32_16x16x32_bf16 v[108:111], v[132:135], v[172:175], v[108:111]
	v_mfma_f32_16x16x32_bf16 v[104:107], v[140:143], v[172:175], v[104:107]
	v_mfma_f32_16x16x32_bf16 v[92:95], v[132:135], v[180:183], v[92:95]
	v_mfma_f32_16x16x32_bf16 v[88:91], v[140:143], v[180:183], v[88:91]
	v_mfma_f32_16x16x32_bf16 v[76:79], v[132:135], v[200:203], v[76:79]
	v_mfma_f32_16x16x32_bf16 v[72:75], v[140:143], v[200:203], v[72:75]
	v_mfma_f32_16x16x32_bf16 v[116:119], v[144:147], v[160:163], v[116:119]
	v_mfma_f32_16x16x32_bf16 v[112:115], v[152:155], v[160:163], v[112:115]
	v_mfma_f32_16x16x32_bf16 v[100:103], v[144:147], v[168:171], v[100:103]
	v_mfma_f32_16x16x32_bf16 v[96:99], v[152:155], v[168:171], v[96:99]
	v_mfma_f32_16x16x32_bf16 v[84:87], v[144:147], v[176:179], v[84:87]
	v_mfma_f32_16x16x32_bf16 v[80:83], v[152:155], v[176:179], v[80:83]
	v_mfma_f32_16x16x32_bf16 v[68:71], v[144:147], v[196:199], v[68:71]
	v_mfma_f32_16x16x32_bf16 v[64:67], v[152:155], v[196:199], v[64:67]
	v_mfma_f32_16x16x32_bf16 v[116:119], v[148:151], v[164:167], v[116:119]
	v_mfma_f32_16x16x32_bf16 v[112:115], v[156:159], v[164:167], v[112:115]
	v_mfma_f32_16x16x32_bf16 v[100:103], v[148:151], v[172:175], v[100:103]
	v_mfma_f32_16x16x32_bf16 v[96:99], v[156:159], v[172:175], v[96:99]
	v_mfma_f32_16x16x32_bf16 v[84:87], v[148:151], v[180:183], v[84:87]
	v_mfma_f32_16x16x32_bf16 v[80:83], v[156:159], v[180:183], v[80:83]
	v_mfma_f32_16x16x32_bf16 v[68:71], v[148:151], v[200:203], v[68:71]
	v_mfma_f32_16x16x32_bf16 v[64:67], v[156:159], v[200:203], v[64:67]
	s_barrier
	s_mov_b32 m0, s50
	v_lshl_add_u64 v[204:205], s[28:29], 0, v[188:189]
	s_add_u32 s60, s28, 0x200000
	ds_read_b128 v[160:163], v232 offset:16384
	ds_read_b128 v[164:167], v232 offset:17408
	ds_read_b128 v[168:171], v232 offset:18432
	ds_read_b128 v[172:175], v232 offset:19456
	ds_read_b128 v[176:179], v232 offset:20480
	ds_read_b128 v[180:183], v232 offset:21504
	ds_read_b128 v[196:199], v232 offset:22528
	ds_read_b128 v[200:203], v232 offset:23552
	global_load_lds_dwordx4 v[204:205], off
	v_lshl_add_u64 v[206:207], s[28:29], 0, v[184:185]
	s_mov_b32 m0, s51
	s_addc_u32 s61, s29, 0
	global_load_lds_dwordx4 v[206:207], off
	v_lshl_add_u64 v[208:209], s[60:61], 0, v[188:189]
	s_mov_b32 m0, s52
	global_load_lds_dwordx4 v[208:209], off
	v_lshl_add_u64 v[208:209], s[60:61], 0, v[184:185]
	s_mov_b32 m0, s53
	s_nop 0
	global_load_lds_dwordx4 v[208:209], off
	s_waitcnt vmcnt(8)
	s_waitcnt lgkmcnt(0)
	s_barrier
	s_waitcnt lgkmcnt(0)
	v_mfma_f32_16x16x32_bf16 v[60:63], v[120:123], v[160:163], v[60:63]
	v_mfma_f32_16x16x32_bf16 v[56:59], v[136:139], v[160:163], v[56:59]
	v_mfma_f32_16x16x32_bf16 v[44:47], v[120:123], v[168:171], v[44:47]
	v_mfma_f32_16x16x32_bf16 v[40:43], v[136:139], v[168:171], v[40:43]
	v_mfma_f32_16x16x32_bf16 v[28:31], v[120:123], v[176:179], v[28:31]
	v_mfma_f32_16x16x32_bf16 v[24:27], v[136:139], v[176:179], v[24:27]
	v_mfma_f32_16x16x32_bf16 v[12:15], v[120:123], v[196:199], v[12:15]
	v_mfma_f32_16x16x32_bf16 v[8:11], v[136:139], v[196:199], v[8:11]
	v_mfma_f32_16x16x32_bf16 v[60:63], v[132:135], v[164:167], v[60:63]
	v_mfma_f32_16x16x32_bf16 v[56:59], v[140:143], v[164:167], v[56:59]
	v_mfma_f32_16x16x32_bf16 v[44:47], v[132:135], v[172:175], v[44:47]
	v_mfma_f32_16x16x32_bf16 v[40:43], v[140:143], v[172:175], v[40:43]
	v_mfma_f32_16x16x32_bf16 v[28:31], v[132:135], v[180:183], v[28:31]
	v_mfma_f32_16x16x32_bf16 v[24:27], v[140:143], v[180:183], v[24:27]
	v_mfma_f32_16x16x32_bf16 v[12:15], v[132:135], v[200:203], v[12:15]
	v_mfma_f32_16x16x32_bf16 v[8:11], v[140:143], v[200:203], v[8:11]
	v_mfma_f32_16x16x32_bf16 v[52:55], v[144:147], v[160:163], v[52:55]
	v_mfma_f32_16x16x32_bf16 v[48:51], v[152:155], v[160:163], v[48:51]
	v_mfma_f32_16x16x32_bf16 v[36:39], v[144:147], v[168:171], v[36:39]
	v_mfma_f32_16x16x32_bf16 v[32:35], v[152:155], v[168:171], v[32:35]
	v_mfma_f32_16x16x32_bf16 v[20:23], v[144:147], v[176:179], v[20:23]
	v_mfma_f32_16x16x32_bf16 v[16:19], v[152:155], v[176:179], v[16:19]
	v_mfma_f32_16x16x32_bf16 v[4:7], v[144:147], v[196:199], v[4:7]
	v_mfma_f32_16x16x32_bf16 v[0:3], v[152:155], v[196:199], v[0:3]
	v_mfma_f32_16x16x32_bf16 v[52:55], v[148:151], v[164:167], v[52:55]
	v_mfma_f32_16x16x32_bf16 v[48:51], v[156:159], v[164:167], v[48:51]
	v_mfma_f32_16x16x32_bf16 v[36:39], v[148:151], v[172:175], v[36:39]
	v_mfma_f32_16x16x32_bf16 v[32:35], v[156:159], v[172:175], v[32:35]
	v_mfma_f32_16x16x32_bf16 v[20:23], v[148:151], v[180:183], v[20:23]
	v_mfma_f32_16x16x32_bf16 v[16:19], v[156:159], v[180:183], v[16:19]
	v_mfma_f32_16x16x32_bf16 v[4:7], v[148:151], v[200:203], v[4:7]
	v_mfma_f32_16x16x32_bf16 v[0:3], v[156:159], v[200:203], v[0:3]
	s_waitcnt vmcnt(4)
	s_barrier
	ds_read_b128 v[120:123], v234
	ds_read_b128 v[132:135], v234 offset:1024
	ds_read_b128 v[136:139], v234 offset:2048
	ds_read_b128 v[140:143], v234 offset:3072
	ds_read_b128 v[144:147], v235
	ds_read_b128 v[148:151], v235 offset:1024
	ds_read_b128 v[152:155], v235 offset:2048
	ds_read_b128 v[156:159], v235 offset:3072
	s_add_u32 s98, s30, s96
	s_addc_u32 s99, s31, s97
	s_add_i32 m0, s85, 0
	v_lshl_add_u64 v[212:213], s[98:99], 0, v[190:191]
	ds_read_b128 v[160:163], v232 offset:32768
	ds_read_b128 v[164:167], v232 offset:33792
	ds_read_b128 v[168:171], v232 offset:34816
	ds_read_b128 v[172:175], v232 offset:35840
	ds_read_b128 v[176:179], v232 offset:36864
	ds_read_b128 v[180:183], v232 offset:37888
	ds_read_b128 v[196:199], v232 offset:38912
	ds_read_b128 v[200:203], v232 offset:39936
	global_load_lds_dwordx4 v[212:213], off
	s_add_u32 s98, s98, 0x80000
	s_addc_u32 s99, s99, 0
	s_add_i32 m0, s85, 0x1000
	v_lshl_add_u64 v[212:213], s[98:99], 0, v[190:191]
	global_load_lds_dwordx4 v[212:213], off
	s_add_u32 s98, s98, 0x80000
	s_addc_u32 s99, s99, 0
	s_add_i32 m0, s85, 0x2000
	v_lshl_add_u64 v[212:213], s[98:99], 0, v[190:191]
	global_load_lds_dwordx4 v[212:213], off
	s_add_u32 s98, s98, 0x80000
	s_addc_u32 s99, s99, 0
	s_add_i32 m0, s85, 0x3000
	v_lshl_add_u64 v[212:213], s[98:99], 0, v[190:191]
	global_load_lds_dwordx4 v[212:213], off
	s_waitcnt vmcnt(8)
	s_waitcnt lgkmcnt(0)
	s_barrier
	s_waitcnt lgkmcnt(0)
	v_mfma_f32_16x16x32_bf16 v[128:131], v[120:123], v[160:163], v[128:131]
	v_mfma_f32_16x16x32_bf16 v[124:127], v[136:139], v[160:163], v[124:127]
	v_mfma_f32_16x16x32_bf16 v[108:111], v[120:123], v[168:171], v[108:111]
	v_mfma_f32_16x16x32_bf16 v[104:107], v[136:139], v[168:171], v[104:107]
	v_mfma_f32_16x16x32_bf16 v[92:95], v[120:123], v[176:179], v[92:95]
	v_mfma_f32_16x16x32_bf16 v[88:91], v[136:139], v[176:179], v[88:91]
	v_mfma_f32_16x16x32_bf16 v[76:79], v[120:123], v[196:199], v[76:79]
	v_mfma_f32_16x16x32_bf16 v[72:75], v[136:139], v[196:199], v[72:75]
	v_mfma_f32_16x16x32_bf16 v[128:131], v[132:135], v[164:167], v[128:131]
	v_mfma_f32_16x16x32_bf16 v[124:127], v[140:143], v[164:167], v[124:127]
	v_mfma_f32_16x16x32_bf16 v[108:111], v[132:135], v[172:175], v[108:111]
	v_mfma_f32_16x16x32_bf16 v[104:107], v[140:143], v[172:175], v[104:107]
	v_mfma_f32_16x16x32_bf16 v[92:95], v[132:135], v[180:183], v[92:95]
	v_mfma_f32_16x16x32_bf16 v[88:91], v[140:143], v[180:183], v[88:91]
	v_mfma_f32_16x16x32_bf16 v[76:79], v[132:135], v[200:203], v[76:79]
	v_mfma_f32_16x16x32_bf16 v[72:75], v[140:143], v[200:203], v[72:75]
	v_mfma_f32_16x16x32_bf16 v[116:119], v[144:147], v[160:163], v[116:119]
	v_mfma_f32_16x16x32_bf16 v[112:115], v[152:155], v[160:163], v[112:115]
	v_mfma_f32_16x16x32_bf16 v[100:103], v[144:147], v[168:171], v[100:103]
	v_mfma_f32_16x16x32_bf16 v[96:99], v[152:155], v[168:171], v[96:99]
	v_mfma_f32_16x16x32_bf16 v[84:87], v[144:147], v[176:179], v[84:87]
	v_mfma_f32_16x16x32_bf16 v[80:83], v[152:155], v[176:179], v[80:83]
	v_mfma_f32_16x16x32_bf16 v[68:71], v[144:147], v[196:199], v[68:71]
	v_mfma_f32_16x16x32_bf16 v[64:67], v[152:155], v[196:199], v[64:67]
	v_mfma_f32_16x16x32_bf16 v[116:119], v[148:151], v[164:167], v[116:119]
	v_mfma_f32_16x16x32_bf16 v[112:115], v[156:159], v[164:167], v[112:115]
	v_mfma_f32_16x16x32_bf16 v[100:103], v[148:151], v[172:175], v[100:103]
	v_mfma_f32_16x16x32_bf16 v[96:99], v[156:159], v[172:175], v[96:99]
	v_mfma_f32_16x16x32_bf16 v[84:87], v[148:151], v[180:183], v[84:87]
	v_mfma_f32_16x16x32_bf16 v[80:83], v[156:159], v[180:183], v[80:83]
	v_mfma_f32_16x16x32_bf16 v[68:71], v[148:151], v[200:203], v[68:71]
	v_mfma_f32_16x16x32_bf16 v[64:67], v[156:159], v[200:203], v[64:67]
	s_barrier
	s_add_i32 s30, s54, s37
	v_lshl_add_u64 v[204:205], v[204:205], 0, s[18:19]
	s_mov_b32 m0, s30
	ds_read_b128 v[160:163], v232 offset:49152
	ds_read_b128 v[164:167], v232 offset:50176
	ds_read_b128 v[168:171], v232 offset:51200
	ds_read_b128 v[172:175], v232 offset:52224
	ds_read_b128 v[176:179], v232 offset:53248
	ds_read_b128 v[180:183], v232 offset:54272
	ds_read_b128 v[196:199], v232 offset:55296
	ds_read_b128 v[200:203], v232 offset:56320
	global_load_lds_dwordx4 v[204:205], off
	s_add_i32 m0, s30, 0x2000
	s_add_u32 s28, s28, 0x200080
	v_lshl_add_u64 v[204:205], v[206:207], 0, s[18:19]
	s_addc_u32 s29, s29, 0
	s_add_i32 s30, s55, s37
	global_load_lds_dwordx4 v[204:205], off
	v_lshl_add_u64 v[204:205], s[28:29], 0, v[188:189]
	s_mov_b32 m0, s30
	s_nop 0
	global_load_lds_dwordx4 v[204:205], off
	v_lshl_add_u64 v[204:205], s[28:29], 0, v[184:185]
	s_add_i32 m0, s30, 0x2000
	s_nop 0
	global_load_lds_dwordx4 v[204:205], off
	s_waitcnt vmcnt(8)
	s_waitcnt lgkmcnt(0)
	s_barrier
	s_waitcnt lgkmcnt(0)
	v_mfma_f32_16x16x32_bf16 v[60:63], v[120:123], v[160:163], v[60:63]
	v_mfma_f32_16x16x32_bf16 v[56:59], v[136:139], v[160:163], v[56:59]
	v_mfma_f32_16x16x32_bf16 v[44:47], v[120:123], v[168:171], v[44:47]
	v_mfma_f32_16x16x32_bf16 v[40:43], v[136:139], v[168:171], v[40:43]
	v_mfma_f32_16x16x32_bf16 v[28:31], v[120:123], v[176:179], v[28:31]
	v_mfma_f32_16x16x32_bf16 v[24:27], v[136:139], v[176:179], v[24:27]
	v_mfma_f32_16x16x32_bf16 v[12:15], v[120:123], v[196:199], v[12:15]
	v_mfma_f32_16x16x32_bf16 v[8:11], v[136:139], v[196:199], v[8:11]
	v_mfma_f32_16x16x32_bf16 v[60:63], v[132:135], v[164:167], v[60:63]
	v_mfma_f32_16x16x32_bf16 v[56:59], v[140:143], v[164:167], v[56:59]
	v_mfma_f32_16x16x32_bf16 v[44:47], v[132:135], v[172:175], v[44:47]
	v_mfma_f32_16x16x32_bf16 v[40:43], v[140:143], v[172:175], v[40:43]
	v_mfma_f32_16x16x32_bf16 v[28:31], v[132:135], v[180:183], v[28:31]
	v_mfma_f32_16x16x32_bf16 v[24:27], v[140:143], v[180:183], v[24:27]
	v_mfma_f32_16x16x32_bf16 v[12:15], v[132:135], v[200:203], v[12:15]
	v_mfma_f32_16x16x32_bf16 v[8:11], v[140:143], v[200:203], v[8:11]
	v_mfma_f32_16x16x32_bf16 v[52:55], v[144:147], v[160:163], v[52:55]
	v_mfma_f32_16x16x32_bf16 v[48:51], v[152:155], v[160:163], v[48:51]
	v_mfma_f32_16x16x32_bf16 v[36:39], v[144:147], v[168:171], v[36:39]
	v_mfma_f32_16x16x32_bf16 v[32:35], v[152:155], v[168:171], v[32:35]
	v_mfma_f32_16x16x32_bf16 v[20:23], v[144:147], v[176:179], v[20:23]
	v_mfma_f32_16x16x32_bf16 v[16:19], v[152:155], v[176:179], v[16:19]
	v_mfma_f32_16x16x32_bf16 v[4:7], v[144:147], v[196:199], v[4:7]
	v_mfma_f32_16x16x32_bf16 v[0:3], v[152:155], v[196:199], v[0:3]
	v_mfma_f32_16x16x32_bf16 v[52:55], v[148:151], v[164:167], v[52:55]
	v_mfma_f32_16x16x32_bf16 v[48:51], v[156:159], v[164:167], v[48:51]
	v_mfma_f32_16x16x32_bf16 v[36:39], v[148:151], v[172:175], v[36:39]
	v_mfma_f32_16x16x32_bf16 v[32:35], v[156:159], v[172:175], v[32:35]
	v_mfma_f32_16x16x32_bf16 v[20:23], v[148:151], v[180:183], v[20:23]
	v_mfma_f32_16x16x32_bf16 v[16:19], v[156:159], v[180:183], v[16:19]
	v_mfma_f32_16x16x32_bf16 v[4:7], v[148:151], v[200:203], v[4:7]
	v_mfma_f32_16x16x32_bf16 v[0:3], v[156:159], v[200:203], v[0:3]
	s_waitcnt vmcnt(4)
	s_add_i32 s58, s58, 2
	s_add_u32 s2, s2, 0x100
	s_addc_u32 s3, s3, 0
	s_cmpk_gt_u32 s58, 0x7d
	s_barrier
	s_cbranch_scc0 .LBB0_1194
	s_setprio 0
	s_and_b64 vcc, exec, s[22:23]
	s_cbranch_vccz .LBB0_1197
	s_barrier

.Lprio_skip9:
.LBB0_1324:
	ds_read_b128 v[140:143], v148
	ds_read_b128 v[154:157], v148 offset:1024
	ds_read_b128 v[158:161], v148 offset:2048
	ds_read_b128 v[162:165], v148 offset:3072
	ds_read_b128 v[166:169], v149
	ds_read_b128 v[170:173], v149 offset:1024
	ds_read_b128 v[174:177], v149 offset:2048
	ds_read_b128 v[178:181], v149 offset:3072
	s_add_u32 s34, s30, 0xfff80080
	s_addc_u32 s35, s31, -1
	s_cmp_eq_u32 s72, 28
	s_cselect_b32 s37, s66, s35
	s_cselect_b32 s36, s67, s34
	s_cselect_b32 s35, s68, s71
	s_cselect_b32 s34, s69, s70
	s_sub_u32 s98, s30, 0x80000
	s_subb_u32 s99, s31, 0
	s_add_i32 m0, s85, 0x8000
	ds_read_b128 v[182:185], v150
	ds_read_b128 v[186:189], v150 offset:1024
	ds_read_b128 v[190:193], v150 offset:2048
	ds_read_b128 v[194:197], v150 offset:3072
	ds_read_b128 v[198:201], v150 offset:4096
	ds_read_b128 v[202:205], v150 offset:5120
	ds_read_b128 v[206:209], v150 offset:6144
	ds_read_b128 v[210:213], v150 offset:7168
	global_load_lds_dwordx4 v222, s[98:99]
	s_add_u32 s98, s98, 0x20000
	s_addc_u32 s99, s99, 0
	s_add_i32 m0, s85, 0x9000
	s_nop 0
	global_load_lds_dwordx4 v222, s[98:99]
	s_add_u32 s98, s98, 0x20000
	s_addc_u32 s99, s99, 0
	s_add_i32 m0, s85, 0xa000
	s_nop 0
	global_load_lds_dwordx4 v222, s[98:99]
	s_add_u32 s98, s98, 0x20000
	s_addc_u32 s99, s99, 0
	s_add_i32 m0, s85, 0xb000
	s_nop 0
	global_load_lds_dwordx4 v222, s[98:99]
	s_waitcnt vmcnt(8)
	s_waitcnt lgkmcnt(0)
	s_barrier
	s_waitcnt lgkmcnt(0)
	v_mfma_f32_16x16x32_bf16 v[124:127], v[140:143], v[182:185], v[124:127]
	v_mfma_f32_16x16x32_bf16 v[120:123], v[158:161], v[182:185], v[120:123]
	v_mfma_f32_16x16x32_bf16 v[112:115], v[140:143], v[190:193], v[112:115]
	v_mfma_f32_16x16x32_bf16 v[104:107], v[158:161], v[190:193], v[104:107]
	v_mfma_f32_16x16x32_bf16 v[96:99], v[140:143], v[198:201], v[96:99]
	v_mfma_f32_16x16x32_bf16 v[88:91], v[158:161], v[198:201], v[88:91]
	v_mfma_f32_16x16x32_bf16 v[80:83], v[140:143], v[206:209], v[80:83]
	v_mfma_f32_16x16x32_bf16 v[72:75], v[158:161], v[206:209], v[72:75]
	v_mfma_f32_16x16x32_bf16 v[124:127], v[154:157], v[186:189], v[124:127]
	v_mfma_f32_16x16x32_bf16 v[120:123], v[162:165], v[186:189], v[120:123]
	v_mfma_f32_16x16x32_bf16 v[112:115], v[154:157], v[194:197], v[112:115]
	v_mfma_f32_16x16x32_bf16 v[104:107], v[162:165], v[194:197], v[104:107]
	v_mfma_f32_16x16x32_bf16 v[96:99], v[154:157], v[202:205], v[96:99]
	v_mfma_f32_16x16x32_bf16 v[88:91], v[162:165], v[202:205], v[88:91]
	v_mfma_f32_16x16x32_bf16 v[80:83], v[154:157], v[210:213], v[80:83]
	v_mfma_f32_16x16x32_bf16 v[72:75], v[162:165], v[210:213], v[72:75]
	v_mfma_f32_16x16x32_bf16 v[116:119], v[166:169], v[182:185], v[116:119]
	v_mfma_f32_16x16x32_bf16 v[108:111], v[174:177], v[182:185], v[108:111]
	v_mfma_f32_16x16x32_bf16 v[100:103], v[166:169], v[190:193], v[100:103]
	v_mfma_f32_16x16x32_bf16 v[92:95], v[174:177], v[190:193], v[92:95]
	v_mfma_f32_16x16x32_bf16 v[84:87], v[166:169], v[198:201], v[84:87]
	v_mfma_f32_16x16x32_bf16 v[76:79], v[174:177], v[198:201], v[76:79]
	v_mfma_f32_16x16x32_bf16 v[68:71], v[166:169], v[206:209], v[68:71]
	v_mfma_f32_16x16x32_bf16 v[64:67], v[174:177], v[206:209], v[64:67]
	v_mfma_f32_16x16x32_bf16 v[116:119], v[170:173], v[186:189], v[116:119]
	v_mfma_f32_16x16x32_bf16 v[108:111], v[178:181], v[186:189], v[108:111]
	v_mfma_f32_16x16x32_bf16 v[100:103], v[170:173], v[194:197], v[100:103]
	v_mfma_f32_16x16x32_bf16 v[92:95], v[178:181], v[194:197], v[92:95]
	v_mfma_f32_16x16x32_bf16 v[84:87], v[170:173], v[202:205], v[84:87]
	v_mfma_f32_16x16x32_bf16 v[76:79], v[178:181], v[202:205], v[76:79]
	v_mfma_f32_16x16x32_bf16 v[68:71], v[170:173], v[210:213], v[68:71]
	v_mfma_f32_16x16x32_bf16 v[64:67], v[178:181], v[210:213], v[64:67]
	s_barrier
	s_add_i32 s73, s56, s5
	v_lshl_add_u64 v[144:145], s[34:35], 0, v[130:131]
	s_mov_b32 m0, s73
	ds_read_b128 v[182:185], v150 offset:16384
	ds_read_b128 v[186:189], v150 offset:17408
	ds_read_b128 v[190:193], v150 offset:18432
	ds_read_b128 v[194:197], v150 offset:19456
	ds_read_b128 v[198:201], v150 offset:20480
	ds_read_b128 v[202:205], v150 offset:21504
	ds_read_b128 v[206:209], v150 offset:22528
	ds_read_b128 v[210:213], v150 offset:23552
	global_load_lds_dwordx4 v[144:145], off
	s_add_i32 m0, s73, 0x2000
	s_add_u32 s74, s34, 0x80000
	v_lshl_add_u64 v[214:215], s[34:35], 0, v[134:135]
	s_addc_u32 s75, s35, 0
	s_add_i32 s73, s57, s5
	global_load_lds_dwordx4 v[214:215], off
	v_lshl_add_u64 v[216:217], s[74:75], 0, v[130:131]
	s_mov_b32 m0, s73
	global_load_lds_dwordx4 v[216:217], off
	v_lshl_add_u64 v[216:217], s[74:75], 0, v[134:135]
	s_add_i32 m0, s73, 0x2000
	s_nop 0
	global_load_lds_dwordx4 v[216:217], off
	s_waitcnt vmcnt(8)
	s_waitcnt lgkmcnt(0)
	s_barrier
	s_waitcnt lgkmcnt(0)
	v_mfma_f32_16x16x32_bf16 v[60:63], v[140:143], v[182:185], v[60:63]
	v_mfma_f32_16x16x32_bf16 v[56:59], v[158:161], v[182:185], v[56:59]
	v_mfma_f32_16x16x32_bf16 v[48:51], v[140:143], v[190:193], v[48:51]
	v_mfma_f32_16x16x32_bf16 v[40:43], v[158:161], v[190:193], v[40:43]
	v_mfma_f32_16x16x32_bf16 v[32:35], v[140:143], v[198:201], v[32:35]
	v_mfma_f32_16x16x32_bf16 v[24:27], v[158:161], v[198:201], v[24:27]
	v_mfma_f32_16x16x32_bf16 v[16:19], v[140:143], v[206:209], v[16:19]
	v_mfma_f32_16x16x32_bf16 v[8:11], v[158:161], v[206:209], v[8:11]
	v_mfma_f32_16x16x32_bf16 v[60:63], v[154:157], v[186:189], v[60:63]
	v_mfma_f32_16x16x32_bf16 v[56:59], v[162:165], v[186:189], v[56:59]
	v_mfma_f32_16x16x32_bf16 v[48:51], v[154:157], v[194:197], v[48:51]
	v_mfma_f32_16x16x32_bf16 v[40:43], v[162:165], v[194:197], v[40:43]
	v_mfma_f32_16x16x32_bf16 v[32:35], v[154:157], v[202:205], v[32:35]
	v_mfma_f32_16x16x32_bf16 v[24:27], v[162:165], v[202:205], v[24:27]
	v_mfma_f32_16x16x32_bf16 v[16:19], v[154:157], v[210:213], v[16:19]
	v_mfma_f32_16x16x32_bf16 v[8:11], v[162:165], v[210:213], v[8:11]
	v_mfma_f32_16x16x32_bf16 v[52:55], v[166:169], v[182:185], v[52:55]
	v_mfma_f32_16x16x32_bf16 v[44:47], v[174:177], v[182:185], v[44:47]
	v_mfma_f32_16x16x32_bf16 v[36:39], v[166:169], v[190:193], v[36:39]
	v_mfma_f32_16x16x32_bf16 v[28:31], v[174:177], v[190:193], v[28:31]
	v_mfma_f32_16x16x32_bf16 v[20:23], v[166:169], v[198:201], v[20:23]
	v_mfma_f32_16x16x32_bf16 v[12:15], v[174:177], v[198:201], v[12:15]
	v_mfma_f32_16x16x32_bf16 v[4:7], v[166:169], v[206:209], v[4:7]
	v_mfma_f32_16x16x32_bf16 v[0:3], v[174:177], v[206:209], v[0:3]
	v_mfma_f32_16x16x32_bf16 v[52:55], v[170:173], v[186:189], v[52:55]
	v_mfma_f32_16x16x32_bf16 v[44:47], v[178:181], v[186:189], v[44:47]
	v_mfma_f32_16x16x32_bf16 v[36:39], v[170:173], v[194:197], v[36:39]
	v_mfma_f32_16x16x32_bf16 v[28:31], v[178:181], v[194:197], v[28:31]
	v_mfma_f32_16x16x32_bf16 v[20:23], v[170:173], v[202:205], v[20:23]
	v_mfma_f32_16x16x32_bf16 v[12:15], v[178:181], v[202:205], v[12:15]
	v_mfma_f32_16x16x32_bf16 v[4:7], v[170:173], v[210:213], v[4:7]
	v_mfma_f32_16x16x32_bf16 v[0:3], v[178:181], v[210:213], v[0:3]
	s_waitcnt vmcnt(4)
	s_barrier
	ds_read_b128 v[140:143], v151
	ds_read_b128 v[154:157], v151 offset:1024
	ds_read_b128 v[158:161], v151 offset:2048
	ds_read_b128 v[162:165], v151 offset:3072
	ds_read_b128 v[166:169], v152
	ds_read_b128 v[170:173], v152 offset:1024
	ds_read_b128 v[174:177], v152 offset:2048
	ds_read_b128 v[178:181], v152 offset:3072
	s_mov_b32 s98, s36
	s_mov_b32 s99, s37
	s_add_i32 m0, s85, 0
	ds_read_b128 v[182:185], v150 offset:32768
	ds_read_b128 v[186:189], v150 offset:33792
	ds_read_b128 v[190:193], v150 offset:34816
	ds_read_b128 v[194:197], v150 offset:35840
	ds_read_b128 v[198:201], v150 offset:36864
	ds_read_b128 v[202:205], v150 offset:37888
	ds_read_b128 v[206:209], v150 offset:38912
	ds_read_b128 v[210:213], v150 offset:39936
	global_load_lds_dwordx4 v222, s[98:99]
	s_add_u32 s98, s98, 0x20000
	s_addc_u32 s99, s99, 0
	s_add_i32 m0, s85, 0x1000
	s_nop 0
	global_load_lds_dwordx4 v222, s[98:99]
	s_add_u32 s98, s98, 0x20000
	s_addc_u32 s99, s99, 0
	s_add_i32 m0, s85, 0x2000
	s_nop 0
	global_load_lds_dwordx4 v222, s[98:99]
	s_add_u32 s98, s98, 0x20000
	s_addc_u32 s99, s99, 0
	s_add_i32 m0, s85, 0x3000
	s_nop 0
	global_load_lds_dwordx4 v222, s[98:99]
	s_waitcnt vmcnt(8)
	s_waitcnt lgkmcnt(0)
	s_barrier
	s_waitcnt lgkmcnt(0)
	v_mfma_f32_16x16x32_bf16 v[124:127], v[140:143], v[182:185], v[124:127]
	v_mfma_f32_16x16x32_bf16 v[120:123], v[158:161], v[182:185], v[120:123]
	v_mfma_f32_16x16x32_bf16 v[112:115], v[140:143], v[190:193], v[112:115]
	v_mfma_f32_16x16x32_bf16 v[104:107], v[158:161], v[190:193], v[104:107]
	v_mfma_f32_16x16x32_bf16 v[96:99], v[140:143], v[198:201], v[96:99]
	v_mfma_f32_16x16x32_bf16 v[88:91], v[158:161], v[198:201], v[88:91]
	v_mfma_f32_16x16x32_bf16 v[80:83], v[140:143], v[206:209], v[80:83]
	v_mfma_f32_16x16x32_bf16 v[72:75], v[158:161], v[206:209], v[72:75]
	v_mfma_f32_16x16x32_bf16 v[124:127], v[154:157], v[186:189], v[124:127]
	v_mfma_f32_16x16x32_bf16 v[120:123], v[162:165], v[186:189], v[120:123]
	v_mfma_f32_16x16x32_bf16 v[112:115], v[154:157], v[194:197], v[112:115]
	v_mfma_f32_16x16x32_bf16 v[104:107], v[162:165], v[194:197], v[104:107]
	v_mfma_f32_16x16x32_bf16 v[96:99], v[154:157], v[202:205], v[96:99]
	v_mfma_f32_16x16x32_bf16 v[88:91], v[162:165], v[202:205], v[88:91]
	v_mfma_f32_16x16x32_bf16 v[80:83], v[154:157], v[210:213], v[80:83]
	v_mfma_f32_16x16x32_bf16 v[72:75], v[162:165], v[210:213], v[72:75]
	v_mfma_f32_16x16x32_bf16 v[116:119], v[166:169], v[182:185], v[116:119]
	v_mfma_f32_16x16x32_bf16 v[108:111], v[174:177], v[182:185], v[108:111]
	v_mfma_f32_16x16x32_bf16 v[100:103], v[166:169], v[190:193], v[100:103]
	v_mfma_f32_16x16x32_bf16 v[92:95], v[174:177], v[190:193], v[92:95]
	v_mfma_f32_16x16x32_bf16 v[84:87], v[166:169], v[198:201], v[84:87]
	v_mfma_f32_16x16x32_bf16 v[76:79], v[174:177], v[198:201], v[76:79]
	v_mfma_f32_16x16x32_bf16 v[68:71], v[166:169], v[206:209], v[68:71]
	v_mfma_f32_16x16x32_bf16 v[64:67], v[174:177], v[206:209], v[64:67]
	v_mfma_f32_16x16x32_bf16 v[116:119], v[170:173], v[186:189], v[116:119]
	v_mfma_f32_16x16x32_bf16 v[108:111], v[178:181], v[186:189], v[108:111]
	v_mfma_f32_16x16x32_bf16 v[100:103], v[170:173], v[194:197], v[100:103]
	v_mfma_f32_16x16x32_bf16 v[92:95], v[178:181], v[194:197], v[92:95]
	v_mfma_f32_16x16x32_bf16 v[84:87], v[170:173], v[202:205], v[84:87]
	v_mfma_f32_16x16x32_bf16 v[76:79], v[178:181], v[202:205], v[76:79]
	v_mfma_f32_16x16x32_bf16 v[68:71], v[170:173], v[210:213], v[68:71]
	v_mfma_f32_16x16x32_bf16 v[64:67], v[178:181], v[210:213], v[64:67]
	s_barrier
	s_add_i32 s36, s58, s5
	v_lshl_add_u64 v[144:145], v[144:145], 0, s[10:11]
	s_mov_b32 m0, s36
	ds_read_b128 v[182:185], v150 offset:49152
	ds_read_b128 v[186:189], v150 offset:50176
	ds_read_b128 v[190:193], v150 offset:51200
	ds_read_b128 v[194:197], v150 offset:52224
	ds_read_b128 v[198:201], v150 offset:53248
	ds_read_b128 v[202:205], v150 offset:54272
	ds_read_b128 v[206:209], v150 offset:55296
	ds_read_b128 v[210:213], v150 offset:56320
	global_load_lds_dwordx4 v[144:145], off
	s_add_i32 m0, s36, 0x2000
	s_add_u32 s34, s34, 0x80080
	v_lshl_add_u64 v[144:145], v[214:215], 0, s[10:11]
	s_addc_u32 s35, s35, 0
	s_add_i32 s36, s59, s5
	global_load_lds_dwordx4 v[144:145], off
	v_lshl_add_u64 v[144:145], s[34:35], 0, v[130:131]
	s_mov_b32 m0, s36
	s_nop 0
	global_load_lds_dwordx4 v[144:145], off
	v_lshl_add_u64 v[144:145], s[34:35], 0, v[134:135]
	s_add_i32 m0, s36, 0x2000
	s_nop 0
	global_load_lds_dwordx4 v[144:145], off
	s_waitcnt vmcnt(8)
	s_waitcnt lgkmcnt(0)
	s_barrier
	s_waitcnt lgkmcnt(0)
	v_mfma_f32_16x16x32_bf16 v[60:63], v[140:143], v[182:185], v[60:63]
	v_mfma_f32_16x16x32_bf16 v[56:59], v[158:161], v[182:185], v[56:59]
	v_mfma_f32_16x16x32_bf16 v[48:51], v[140:143], v[190:193], v[48:51]
	v_mfma_f32_16x16x32_bf16 v[40:43], v[158:161], v[190:193], v[40:43]
	v_mfma_f32_16x16x32_bf16 v[32:35], v[140:143], v[198:201], v[32:35]
	v_mfma_f32_16x16x32_bf16 v[24:27], v[158:161], v[198:201], v[24:27]
	v_mfma_f32_16x16x32_bf16 v[16:19], v[140:143], v[206:209], v[16:19]
	v_mfma_f32_16x16x32_bf16 v[8:11], v[158:161], v[206:209], v[8:11]
	v_mfma_f32_16x16x32_bf16 v[60:63], v[154:157], v[186:189], v[60:63]
	v_mfma_f32_16x16x32_bf16 v[56:59], v[162:165], v[186:189], v[56:59]
	v_mfma_f32_16x16x32_bf16 v[48:51], v[154:157], v[194:197], v[48:51]
	v_mfma_f32_16x16x32_bf16 v[40:43], v[162:165], v[194:197], v[40:43]
	v_mfma_f32_16x16x32_bf16 v[32:35], v[154:157], v[202:205], v[32:35]
	v_mfma_f32_16x16x32_bf16 v[24:27], v[162:165], v[202:205], v[24:27]
	v_mfma_f32_16x16x32_bf16 v[16:19], v[154:157], v[210:213], v[16:19]
	v_mfma_f32_16x16x32_bf16 v[8:11], v[162:165], v[210:213], v[8:11]
	v_mfma_f32_16x16x32_bf16 v[52:55], v[166:169], v[182:185], v[52:55]
	v_mfma_f32_16x16x32_bf16 v[44:47], v[174:177], v[182:185], v[44:47]
	v_mfma_f32_16x16x32_bf16 v[36:39], v[166:169], v[190:193], v[36:39]
	v_mfma_f32_16x16x32_bf16 v[28:31], v[174:177], v[190:193], v[28:31]
	v_mfma_f32_16x16x32_bf16 v[20:23], v[166:169], v[198:201], v[20:23]
	v_mfma_f32_16x16x32_bf16 v[12:15], v[174:177], v[198:201], v[12:15]
	v_mfma_f32_16x16x32_bf16 v[4:7], v[166:169], v[206:209], v[4:7]
	v_mfma_f32_16x16x32_bf16 v[0:3], v[174:177], v[206:209], v[0:3]
	v_mfma_f32_16x16x32_bf16 v[52:55], v[170:173], v[186:189], v[52:55]
	v_mfma_f32_16x16x32_bf16 v[44:47], v[178:181], v[186:189], v[44:47]
	v_mfma_f32_16x16x32_bf16 v[36:39], v[170:173], v[194:197], v[36:39]
	v_mfma_f32_16x16x32_bf16 v[28:31], v[178:181], v[194:197], v[28:31]
	v_mfma_f32_16x16x32_bf16 v[20:23], v[170:173], v[202:205], v[20:23]
	v_mfma_f32_16x16x32_bf16 v[12:15], v[178:181], v[202:205], v[12:15]
	v_mfma_f32_16x16x32_bf16 v[4:7], v[170:173], v[210:213], v[4:7]
	v_mfma_f32_16x16x32_bf16 v[0:3], v[178:181], v[210:213], v[0:3]
	s_waitcnt vmcnt(4)
	s_add_i32 s72, s72, 2
	s_add_u32 s30, s30, 0x100
	s_addc_u32 s31, s31, 0
	s_add_u32 s70, s70, 0x100
	s_addc_u32 s71, s71, 0
	s_cmp_gt_u32 s72, 29
	s_barrier
	s_cbranch_scc0 .LBB0_1324
	s_setprio 0
	s_and_b64 vcc, exec, s[12:13]
	s_cbranch_vccz .LBB0_1327
	s_barrier

.Lprio_skip10:
.LBB0_1526:
	ds_read_b128 v[80:83], v185
	ds_read_b128 v[84:87], v185 offset:1024
	ds_read_b128 v[92:95], v185 offset:2048
	ds_read_b128 v[100:103], v185 offset:3072
	ds_read_b128 v[152:155], v186
	ds_read_b128 v[156:159], v186 offset:1024
	ds_read_b128 v[160:163], v186 offset:2048
	ds_read_b128 v[164:167], v186 offset:3072
	s_add_u32 s2, s0, 0xfff80080
	s_addc_u32 s3, s1, -1
	s_cmp_eq_u32 s58, 28
	s_cselect_b32 s31, s52, s3
	s_cselect_b32 s30, s53, s2
	s_cselect_b32 s3, s54, s57
	s_cselect_b32 s2, s55, s56
	s_sub_u32 s98, s0, 0x80000
	s_subb_u32 s99, s1, 0
	s_add_i32 m0, s85, 0x8000
	ds_read_b128 v[168:171], v187
	ds_read_b128 v[172:175], v187 offset:1024
	ds_read_b128 v[176:179], v187 offset:2048
	ds_read_b128 v[190:193], v187 offset:3072
	ds_read_b128 v[194:197], v187 offset:4096
	ds_read_b128 v[198:201], v187 offset:5120
	ds_read_b128 v[202:205], v187 offset:6144
	ds_read_b128 v[206:209], v187 offset:7168
	global_load_lds_dwordx4 v222, s[98:99]
	s_add_u32 s98, s98, 0x20000
	s_addc_u32 s99, s99, 0
	s_add_i32 m0, s85, 0x9000
	s_nop 0
	global_load_lds_dwordx4 v222, s[98:99]
	s_add_u32 s98, s98, 0x20000
	s_addc_u32 s99, s99, 0
	s_add_i32 m0, s85, 0xa000
	s_nop 0
	global_load_lds_dwordx4 v222, s[98:99]
	s_add_u32 s98, s98, 0x20000
	s_addc_u32 s99, s99, 0
	s_add_i32 m0, s85, 0xb000
	s_nop 0
	global_load_lds_dwordx4 v222, s[98:99]
	s_waitcnt vmcnt(8)
	s_waitcnt lgkmcnt(0)
	s_barrier
	s_waitcnt lgkmcnt(0)
	v_mfma_f32_16x16x32_bf16 v[136:139], v[80:83], v[168:171], v[136:139]
	v_mfma_f32_16x16x32_bf16 v[140:143], v[92:95], v[168:171], v[140:143]
	v_mfma_f32_16x16x32_bf16 v[120:123], v[80:83], v[176:179], v[120:123]
	v_mfma_f32_16x16x32_bf16 v[124:127], v[92:95], v[176:179], v[124:127]
	v_mfma_f32_16x16x32_bf16 v[104:107], v[80:83], v[194:197], v[104:107]
	v_mfma_f32_16x16x32_bf16 v[108:111], v[92:95], v[194:197], v[108:111]
	v_mfma_f32_16x16x32_bf16 v[72:75], v[80:83], v[202:205], v[72:75]
	v_mfma_f32_16x16x32_bf16 v[76:79], v[92:95], v[202:205], v[76:79]
	v_mfma_f32_16x16x32_bf16 v[136:139], v[84:87], v[172:175], v[136:139]
	v_mfma_f32_16x16x32_bf16 v[140:143], v[100:103], v[172:175], v[140:143]
	v_mfma_f32_16x16x32_bf16 v[120:123], v[84:87], v[190:193], v[120:123]
	v_mfma_f32_16x16x32_bf16 v[124:127], v[100:103], v[190:193], v[124:127]
	v_mfma_f32_16x16x32_bf16 v[104:107], v[84:87], v[198:201], v[104:107]
	v_mfma_f32_16x16x32_bf16 v[108:111], v[100:103], v[198:201], v[108:111]
	v_mfma_f32_16x16x32_bf16 v[72:75], v[84:87], v[206:209], v[72:75]
	v_mfma_f32_16x16x32_bf16 v[76:79], v[100:103], v[206:209], v[76:79]
	v_mfma_f32_16x16x32_bf16 v[128:131], v[152:155], v[168:171], v[128:131]
	v_mfma_f32_16x16x32_bf16 v[132:135], v[160:163], v[168:171], v[132:135]
	v_mfma_f32_16x16x32_bf16 v[112:115], v[152:155], v[176:179], v[112:115]
	v_mfma_f32_16x16x32_bf16 v[116:119], v[160:163], v[176:179], v[116:119]
	v_mfma_f32_16x16x32_bf16 v[88:91], v[152:155], v[194:197], v[88:91]
	v_mfma_f32_16x16x32_bf16 v[96:99], v[160:163], v[194:197], v[96:99]
	v_mfma_f32_16x16x32_bf16 v[64:67], v[152:155], v[202:205], v[64:67]
	v_mfma_f32_16x16x32_bf16 v[68:71], v[160:163], v[202:205], v[68:71]
	v_mfma_f32_16x16x32_bf16 v[128:131], v[156:159], v[172:175], v[128:131]
	v_mfma_f32_16x16x32_bf16 v[132:135], v[164:167], v[172:175], v[132:135]
	v_mfma_f32_16x16x32_bf16 v[112:115], v[156:159], v[190:193], v[112:115]
	v_mfma_f32_16x16x32_bf16 v[116:119], v[164:167], v[190:193], v[116:119]
	v_mfma_f32_16x16x32_bf16 v[88:91], v[156:159], v[198:201], v[88:91]
	v_mfma_f32_16x16x32_bf16 v[96:99], v[164:167], v[198:201], v[96:99]
	v_mfma_f32_16x16x32_bf16 v[64:67], v[156:159], v[206:209], v[64:67]
	v_mfma_f32_16x16x32_bf16 v[68:71], v[164:167], v[206:209], v[68:71]
	s_barrier
	s_add_i32 s59, s49, s39
	v_lshl_add_u64 v[180:181], s[2:3], 0, v[146:147]
	s_mov_b32 m0, s59
	ds_read_b128 v[168:171], v187 offset:16384
	ds_read_b128 v[172:175], v187 offset:17408
	ds_read_b128 v[176:179], v187 offset:18432
	ds_read_b128 v[190:193], v187 offset:19456
	ds_read_b128 v[194:197], v187 offset:20480
	ds_read_b128 v[198:201], v187 offset:21504
	ds_read_b128 v[202:205], v187 offset:22528
	ds_read_b128 v[206:209], v187 offset:23552
	global_load_lds_dwordx4 v[180:181], off
	s_add_i32 m0, s59, 0x2000
	s_add_u32 s60, s2, 0x80000
	v_lshl_add_u64 v[210:211], s[2:3], 0, v[144:145]
	s_addc_u32 s61, s3, 0
	s_add_i32 s59, s50, s39
	global_load_lds_dwordx4 v[210:211], off
	v_lshl_add_u64 v[212:213], s[60:61], 0, v[146:147]
	s_mov_b32 m0, s59
	global_load_lds_dwordx4 v[212:213], off
	v_lshl_add_u64 v[212:213], s[60:61], 0, v[144:145]
	s_add_i32 m0, s59, 0x2000
	s_nop 0
	global_load_lds_dwordx4 v[212:213], off
	s_waitcnt vmcnt(8)
	s_waitcnt lgkmcnt(0)
	s_barrier
	s_waitcnt lgkmcnt(0)
	v_mfma_f32_16x16x32_bf16 v[56:59], v[80:83], v[168:171], v[56:59]
	v_mfma_f32_16x16x32_bf16 v[60:63], v[92:95], v[168:171], v[60:63]
	v_mfma_f32_16x16x32_bf16 v[40:43], v[80:83], v[176:179], v[40:43]
	v_mfma_f32_16x16x32_bf16 v[44:47], v[92:95], v[176:179], v[44:47]
	v_mfma_f32_16x16x32_bf16 v[24:27], v[80:83], v[194:197], v[24:27]
	v_mfma_f32_16x16x32_bf16 v[28:31], v[92:95], v[194:197], v[28:31]
	v_mfma_f32_16x16x32_bf16 v[8:11], v[80:83], v[202:205], v[8:11]
	v_mfma_f32_16x16x32_bf16 v[12:15], v[92:95], v[202:205], v[12:15]
	v_mfma_f32_16x16x32_bf16 v[56:59], v[84:87], v[172:175], v[56:59]
	v_mfma_f32_16x16x32_bf16 v[60:63], v[100:103], v[172:175], v[60:63]
	v_mfma_f32_16x16x32_bf16 v[40:43], v[84:87], v[190:193], v[40:43]
	v_mfma_f32_16x16x32_bf16 v[44:47], v[100:103], v[190:193], v[44:47]
	v_mfma_f32_16x16x32_bf16 v[24:27], v[84:87], v[198:201], v[24:27]
	v_mfma_f32_16x16x32_bf16 v[28:31], v[100:103], v[198:201], v[28:31]
	v_mfma_f32_16x16x32_bf16 v[8:11], v[84:87], v[206:209], v[8:11]
	v_mfma_f32_16x16x32_bf16 v[12:15], v[100:103], v[206:209], v[12:15]
	v_mfma_f32_16x16x32_bf16 v[48:51], v[152:155], v[168:171], v[48:51]
	v_mfma_f32_16x16x32_bf16 v[52:55], v[160:163], v[168:171], v[52:55]
	v_mfma_f32_16x16x32_bf16 v[32:35], v[152:155], v[176:179], v[32:35]
	v_mfma_f32_16x16x32_bf16 v[36:39], v[160:163], v[176:179], v[36:39]
	v_mfma_f32_16x16x32_bf16 v[16:19], v[152:155], v[194:197], v[16:19]
	v_mfma_f32_16x16x32_bf16 v[20:23], v[160:163], v[194:197], v[20:23]
	v_mfma_f32_16x16x32_bf16 v[0:3], v[152:155], v[202:205], v[0:3]
	v_mfma_f32_16x16x32_bf16 v[4:7], v[160:163], v[202:205], v[4:7]
	v_mfma_f32_16x16x32_bf16 v[48:51], v[156:159], v[172:175], v[48:51]
	v_mfma_f32_16x16x32_bf16 v[52:55], v[164:167], v[172:175], v[52:55]
	v_mfma_f32_16x16x32_bf16 v[32:35], v[156:159], v[190:193], v[32:35]
	v_mfma_f32_16x16x32_bf16 v[36:39], v[164:167], v[190:193], v[36:39]
	v_mfma_f32_16x16x32_bf16 v[16:19], v[156:159], v[198:201], v[16:19]
	v_mfma_f32_16x16x32_bf16 v[20:23], v[164:167], v[198:201], v[20:23]
	v_mfma_f32_16x16x32_bf16 v[0:3], v[156:159], v[206:209], v[0:3]
	v_mfma_f32_16x16x32_bf16 v[4:7], v[164:167], v[206:209], v[4:7]
	s_waitcnt vmcnt(4)
	s_barrier
	s_add_i32 s59, 0, 0x18000
	s_add_i32 s60, 0, 0x1c000
	v_add_u32_e32 v100, s59, v184
	v_add_u32_e32 v164, s60, v184
	ds_read_b128 v[80:83], v100
	ds_read_b128 v[84:87], v100 offset:1024
	ds_read_b128 v[92:95], v100 offset:2048
	ds_read_b128 v[100:103], v100 offset:3072
	ds_read_b128 v[152:155], v164
	ds_read_b128 v[156:159], v164 offset:1024
	ds_read_b128 v[160:163], v164 offset:2048
	ds_read_b128 v[164:167], v164 offset:3072
	s_mov_b32 s98, s30
	s_mov_b32 s99, s31
	s_add_i32 m0, s85, 0
	ds_read_b128 v[168:171], v187 offset:32768
	ds_read_b128 v[172:175], v187 offset:33792
	ds_read_b128 v[176:179], v187 offset:34816
	ds_read_b128 v[190:193], v187 offset:35840
	ds_read_b128 v[194:197], v187 offset:36864
	ds_read_b128 v[198:201], v187 offset:37888
	ds_read_b128 v[202:205], v187 offset:38912
	ds_read_b128 v[206:209], v187 offset:39936
	global_load_lds_dwordx4 v222, s[98:99]
	s_add_u32 s98, s98, 0x20000
	s_addc_u32 s99, s99, 0
	s_add_i32 m0, s85, 0x1000
	s_nop 0
	global_load_lds_dwordx4 v222, s[98:99]
	s_add_u32 s98, s98, 0x20000
	s_addc_u32 s99, s99, 0
	s_add_i32 m0, s85, 0x2000
	s_nop 0
	global_load_lds_dwordx4 v222, s[98:99]
	s_add_u32 s98, s98, 0x20000
	s_addc_u32 s99, s99, 0
	s_add_i32 m0, s85, 0x3000
	s_nop 0
	global_load_lds_dwordx4 v222, s[98:99]
	s_waitcnt vmcnt(8)
	s_waitcnt lgkmcnt(0)
	s_barrier
	s_waitcnt lgkmcnt(0)
	v_mfma_f32_16x16x32_bf16 v[136:139], v[80:83], v[168:171], v[136:139]
	v_mfma_f32_16x16x32_bf16 v[140:143], v[92:95], v[168:171], v[140:143]
	v_mfma_f32_16x16x32_bf16 v[120:123], v[80:83], v[176:179], v[120:123]
	v_mfma_f32_16x16x32_bf16 v[124:127], v[92:95], v[176:179], v[124:127]
	v_mfma_f32_16x16x32_bf16 v[104:107], v[80:83], v[194:197], v[104:107]
	v_mfma_f32_16x16x32_bf16 v[108:111], v[92:95], v[194:197], v[108:111]
	v_mfma_f32_16x16x32_bf16 v[72:75], v[80:83], v[202:205], v[72:75]
	v_mfma_f32_16x16x32_bf16 v[76:79], v[92:95], v[202:205], v[76:79]
	v_mfma_f32_16x16x32_bf16 v[136:139], v[84:87], v[172:175], v[136:139]
	v_mfma_f32_16x16x32_bf16 v[140:143], v[100:103], v[172:175], v[140:143]
	v_mfma_f32_16x16x32_bf16 v[120:123], v[84:87], v[190:193], v[120:123]
	v_mfma_f32_16x16x32_bf16 v[124:127], v[100:103], v[190:193], v[124:127]
	v_mfma_f32_16x16x32_bf16 v[104:107], v[84:87], v[198:201], v[104:107]
	v_mfma_f32_16x16x32_bf16 v[108:111], v[100:103], v[198:201], v[108:111]
	v_mfma_f32_16x16x32_bf16 v[72:75], v[84:87], v[206:209], v[72:75]
	v_mfma_f32_16x16x32_bf16 v[76:79], v[100:103], v[206:209], v[76:79]
	v_mfma_f32_16x16x32_bf16 v[128:131], v[152:155], v[168:171], v[128:131]
	v_mfma_f32_16x16x32_bf16 v[132:135], v[160:163], v[168:171], v[132:135]
	v_mfma_f32_16x16x32_bf16 v[112:115], v[152:155], v[176:179], v[112:115]
	v_mfma_f32_16x16x32_bf16 v[116:119], v[160:163], v[176:179], v[116:119]
	v_mfma_f32_16x16x32_bf16 v[88:91], v[152:155], v[194:197], v[88:91]
	v_mfma_f32_16x16x32_bf16 v[96:99], v[160:163], v[194:197], v[96:99]
	v_mfma_f32_16x16x32_bf16 v[64:67], v[152:155], v[202:205], v[64:67]
	v_mfma_f32_16x16x32_bf16 v[68:71], v[160:163], v[202:205], v[68:71]
	v_mfma_f32_16x16x32_bf16 v[128:131], v[156:159], v[172:175], v[128:131]
	v_mfma_f32_16x16x32_bf16 v[132:135], v[164:167], v[172:175], v[132:135]
	v_mfma_f32_16x16x32_bf16 v[112:115], v[156:159], v[190:193], v[112:115]
	v_mfma_f32_16x16x32_bf16 v[116:119], v[164:167], v[190:193], v[116:119]
	v_mfma_f32_16x16x32_bf16 v[88:91], v[156:159], v[198:201], v[88:91]
	v_mfma_f32_16x16x32_bf16 v[96:99], v[164:167], v[198:201], v[96:99]
	v_mfma_f32_16x16x32_bf16 v[64:67], v[156:159], v[206:209], v[64:67]
	v_mfma_f32_16x16x32_bf16 v[68:71], v[164:167], v[206:209], v[68:71]
	s_barrier
	s_add_i32 s30, s59, s39
	v_lshl_add_u64 v[180:181], v[180:181], 0, s[20:21]
	s_mov_b32 m0, s30
	ds_read_b128 v[168:171], v187 offset:49152
	ds_read_b128 v[172:175], v187 offset:50176
	ds_read_b128 v[176:179], v187 offset:51200
	ds_read_b128 v[190:193], v187 offset:52224
	ds_read_b128 v[194:197], v187 offset:53248
	ds_read_b128 v[198:201], v187 offset:54272
	ds_read_b128 v[202:205], v187 offset:55296
	ds_read_b128 v[206:209], v187 offset:56320
	global_load_lds_dwordx4 v[180:181], off
	s_add_i32 m0, s30, 0x2000
	s_add_u32 s2, s2, 0x80080
	v_lshl_add_u64 v[180:181], v[210:211], 0, s[20:21]
	s_addc_u32 s3, s3, 0
	s_add_i32 s30, s60, s39
	global_load_lds_dwordx4 v[180:181], off
	v_lshl_add_u64 v[180:181], s[2:3], 0, v[146:147]
	s_mov_b32 m0, s30
	s_nop 0
	global_load_lds_dwordx4 v[180:181], off
	v_lshl_add_u64 v[180:181], s[2:3], 0, v[144:145]
	s_add_i32 m0, s30, 0x2000
	s_nop 0
	global_load_lds_dwordx4 v[180:181], off
	s_waitcnt vmcnt(8)
	s_waitcnt lgkmcnt(0)
	s_barrier
	s_waitcnt lgkmcnt(0)
	v_mfma_f32_16x16x32_bf16 v[56:59], v[80:83], v[168:171], v[56:59]
	v_mfma_f32_16x16x32_bf16 v[60:63], v[92:95], v[168:171], v[60:63]
	v_mfma_f32_16x16x32_bf16 v[40:43], v[80:83], v[176:179], v[40:43]
	v_mfma_f32_16x16x32_bf16 v[44:47], v[92:95], v[176:179], v[44:47]
	v_mfma_f32_16x16x32_bf16 v[24:27], v[80:83], v[194:197], v[24:27]
	v_mfma_f32_16x16x32_bf16 v[28:31], v[92:95], v[194:197], v[28:31]
	v_mfma_f32_16x16x32_bf16 v[8:11], v[80:83], v[202:205], v[8:11]
	v_mfma_f32_16x16x32_bf16 v[12:15], v[92:95], v[202:205], v[12:15]
	v_mfma_f32_16x16x32_bf16 v[56:59], v[84:87], v[172:175], v[56:59]
	v_mfma_f32_16x16x32_bf16 v[60:63], v[100:103], v[172:175], v[60:63]
	v_mfma_f32_16x16x32_bf16 v[40:43], v[84:87], v[190:193], v[40:43]
	v_mfma_f32_16x16x32_bf16 v[44:47], v[100:103], v[190:193], v[44:47]
	v_mfma_f32_16x16x32_bf16 v[24:27], v[84:87], v[198:201], v[24:27]
	v_mfma_f32_16x16x32_bf16 v[28:31], v[100:103], v[198:201], v[28:31]
	v_mfma_f32_16x16x32_bf16 v[8:11], v[84:87], v[206:209], v[8:11]
	v_mfma_f32_16x16x32_bf16 v[12:15], v[100:103], v[206:209], v[12:15]
	v_mfma_f32_16x16x32_bf16 v[48:51], v[152:155], v[168:171], v[48:51]
	v_mfma_f32_16x16x32_bf16 v[52:55], v[160:163], v[168:171], v[52:55]
	v_mfma_f32_16x16x32_bf16 v[32:35], v[152:155], v[176:179], v[32:35]
	v_mfma_f32_16x16x32_bf16 v[36:39], v[160:163], v[176:179], v[36:39]
	v_mfma_f32_16x16x32_bf16 v[16:19], v[152:155], v[194:197], v[16:19]
	v_mfma_f32_16x16x32_bf16 v[20:23], v[160:163], v[194:197], v[20:23]
	v_mfma_f32_16x16x32_bf16 v[0:3], v[152:155], v[202:205], v[0:3]
	v_mfma_f32_16x16x32_bf16 v[4:7], v[160:163], v[202:205], v[4:7]
	v_mfma_f32_16x16x32_bf16 v[48:51], v[156:159], v[172:175], v[48:51]
	v_mfma_f32_16x16x32_bf16 v[52:55], v[164:167], v[172:175], v[52:55]
	v_mfma_f32_16x16x32_bf16 v[32:35], v[156:159], v[190:193], v[32:35]
	v_mfma_f32_16x16x32_bf16 v[36:39], v[164:167], v[190:193], v[36:39]
	v_mfma_f32_16x16x32_bf16 v[16:19], v[156:159], v[198:201], v[16:19]
	v_mfma_f32_16x16x32_bf16 v[20:23], v[164:167], v[198:201], v[20:23]
	v_mfma_f32_16x16x32_bf16 v[0:3], v[156:159], v[206:209], v[0:3]
	v_mfma_f32_16x16x32_bf16 v[4:7], v[164:167], v[206:209], v[4:7]
	s_waitcnt vmcnt(4)
	s_add_i32 s58, s58, 2
	s_add_u32 s0, s0, 0x100
	s_addc_u32 s1, s1, 0
	s_add_u32 s56, s56, 0x100
	s_addc_u32 s57, s57, 0
	s_cmp_gt_u32 s58, 29
	s_barrier
	s_cbranch_scc0 .LBB0_1526
	s_setprio 0
	s_and_b64 vcc, exec, s[24:25]
	s_cbranch_vccz .LBB0_1529
	s_barrier

.Lprio_skip12:
.LBB0_1825:
	ds_read_b128 v[120:123], v230
	ds_read_b128 v[132:135], v230 offset:1024
	ds_read_b128 v[136:139], v230 offset:2048
	ds_read_b128 v[140:143], v230 offset:3072
	ds_read_b128 v[144:147], v231
	ds_read_b128 v[148:151], v231 offset:1024
	ds_read_b128 v[152:155], v231 offset:2048
	ds_read_b128 v[156:159], v231 offset:3072
	s_add_u32 s28, s0, s2
	s_addc_u32 s29, s1, s3
	s_cmpk_eq_i32 s2, 0x1000
	s_cselect_b32 s30, 0, s2
	s_cselect_b32 s31, 0, s3
	s_cselect_b32 s28, s57, s28
	s_cselect_b32 s29, s5, s29
	s_add_u32 s30, s10, s30
	s_addc_u32 s31, s11, s31
	s_add_u32 s98, s2, s86
	s_addc_u32 s99, s3, s87
	s_add_i32 m0, s85, 0x8000
	v_lshl_add_u64 v[204:205], v[192:193], 0, s[98:99]
	ds_read_b128 v[160:163], v232
	ds_read_b128 v[164:167], v232 offset:1024
	ds_read_b128 v[168:171], v232 offset:2048
	ds_read_b128 v[172:175], v232 offset:3072
	ds_read_b128 v[176:179], v232 offset:4096
	ds_read_b128 v[180:183], v232 offset:5120
	ds_read_b128 v[196:199], v232 offset:6144
	ds_read_b128 v[200:203], v232 offset:7168
	global_load_lds_dwordx4 v[204:205], off
	s_add_u32 s98, s98, 0x20000
	s_addc_u32 s99, s99, 0
	s_add_i32 m0, s85, 0x9000
	v_lshl_add_u64 v[204:205], v[192:193], 0, s[98:99]
	global_load_lds_dwordx4 v[204:205], off
	s_add_u32 s98, s98, 0x20000
	s_addc_u32 s99, s99, 0
	s_add_i32 m0, s85, 0xa000
	v_lshl_add_u64 v[204:205], v[192:193], 0, s[98:99]
	global_load_lds_dwordx4 v[204:205], off
	s_add_u32 s98, s98, 0x20000
	s_addc_u32 s99, s99, 0
	s_add_i32 m0, s85, 0xb000
	v_lshl_add_u64 v[204:205], v[192:193], 0, s[98:99]
	global_load_lds_dwordx4 v[204:205], off
	s_waitcnt vmcnt(8)
	s_waitcnt lgkmcnt(0)
	s_barrier
	s_waitcnt lgkmcnt(0)
	v_mfma_f32_16x16x32_bf16 v[128:131], v[120:123], v[160:163], v[128:131]
	v_mfma_f32_16x16x32_bf16 v[124:127], v[136:139], v[160:163], v[124:127]
	v_mfma_f32_16x16x32_bf16 v[108:111], v[120:123], v[168:171], v[108:111]
	v_mfma_f32_16x16x32_bf16 v[104:107], v[136:139], v[168:171], v[104:107]
	v_mfma_f32_16x16x32_bf16 v[92:95], v[120:123], v[176:179], v[92:95]
	v_mfma_f32_16x16x32_bf16 v[88:91], v[136:139], v[176:179], v[88:91]
	v_mfma_f32_16x16x32_bf16 v[76:79], v[120:123], v[196:199], v[76:79]
	v_mfma_f32_16x16x32_bf16 v[72:75], v[136:139], v[196:199], v[72:75]
	v_mfma_f32_16x16x32_bf16 v[128:131], v[132:135], v[164:167], v[128:131]
	v_mfma_f32_16x16x32_bf16 v[124:127], v[140:143], v[164:167], v[124:127]
	v_mfma_f32_16x16x32_bf16 v[108:111], v[132:135], v[172:175], v[108:111]
	v_mfma_f32_16x16x32_bf16 v[104:107], v[140:143], v[172:175], v[104:107]
	v_mfma_f32_16x16x32_bf16 v[92:95], v[132:135], v[180:183], v[92:95]
	v_mfma_f32_16x16x32_bf16 v[88:91], v[140:143], v[180:183], v[88:91]
	v_mfma_f32_16x16x32_bf16 v[76:79], v[132:135], v[200:203], v[76:79]
	v_mfma_f32_16x16x32_bf16 v[72:75], v[140:143], v[200:203], v[72:75]
	v_mfma_f32_16x16x32_bf16 v[116:119], v[144:147], v[160:163], v[116:119]
	v_mfma_f32_16x16x32_bf16 v[112:115], v[152:155], v[160:163], v[112:115]
	v_mfma_f32_16x16x32_bf16 v[100:103], v[144:147], v[168:171], v[100:103]
	v_mfma_f32_16x16x32_bf16 v[96:99], v[152:155], v[168:171], v[96:99]
	v_mfma_f32_16x16x32_bf16 v[84:87], v[144:147], v[176:179], v[84:87]
	v_mfma_f32_16x16x32_bf16 v[80:83], v[152:155], v[176:179], v[80:83]
	v_mfma_f32_16x16x32_bf16 v[68:71], v[144:147], v[196:199], v[68:71]
	v_mfma_f32_16x16x32_bf16 v[64:67], v[152:155], v[196:199], v[64:67]
	v_mfma_f32_16x16x32_bf16 v[116:119], v[148:151], v[164:167], v[116:119]
	v_mfma_f32_16x16x32_bf16 v[112:115], v[156:159], v[164:167], v[112:115]
	v_mfma_f32_16x16x32_bf16 v[100:103], v[148:151], v[172:175], v[100:103]
	v_mfma_f32_16x16x32_bf16 v[96:99], v[156:159], v[172:175], v[96:99]
	v_mfma_f32_16x16x32_bf16 v[84:87], v[148:151], v[180:183], v[84:87]
	v_mfma_f32_16x16x32_bf16 v[80:83], v[156:159], v[180:183], v[80:83]
	v_mfma_f32_16x16x32_bf16 v[68:71], v[148:151], v[200:203], v[68:71]
	v_mfma_f32_16x16x32_bf16 v[64:67], v[156:159], v[200:203], v[64:67]
	s_barrier
	s_mov_b32 m0, s50
	v_lshl_add_u64 v[204:205], s[28:29], 0, v[188:189]
	s_add_u32 s60, s28, 0x80000
	ds_read_b128 v[160:163], v232 offset:16384
	ds_read_b128 v[164:167], v232 offset:17408
	ds_read_b128 v[168:171], v232 offset:18432
	ds_read_b128 v[172:175], v232 offset:19456
	ds_read_b128 v[176:179], v232 offset:20480
	ds_read_b128 v[180:183], v232 offset:21504
	ds_read_b128 v[196:199], v232 offset:22528
	ds_read_b128 v[200:203], v232 offset:23552
	global_load_lds_dwordx4 v[204:205], off
	v_lshl_add_u64 v[206:207], s[28:29], 0, v[184:185]
	s_mov_b32 m0, s51
	s_addc_u32 s61, s29, 0
	global_load_lds_dwordx4 v[206:207], off
	v_lshl_add_u64 v[208:209], s[60:61], 0, v[188:189]
	s_mov_b32 m0, s52
	global_load_lds_dwordx4 v[208:209], off
	v_lshl_add_u64 v[208:209], s[60:61], 0, v[184:185]
	s_mov_b32 m0, s53
	s_nop 0
	global_load_lds_dwordx4 v[208:209], off
	s_waitcnt vmcnt(8)
	s_waitcnt lgkmcnt(0)
	s_barrier
	s_waitcnt lgkmcnt(0)
	v_mfma_f32_16x16x32_bf16 v[60:63], v[120:123], v[160:163], v[60:63]
	v_mfma_f32_16x16x32_bf16 v[56:59], v[136:139], v[160:163], v[56:59]
	v_mfma_f32_16x16x32_bf16 v[44:47], v[120:123], v[168:171], v[44:47]
	v_mfma_f32_16x16x32_bf16 v[40:43], v[136:139], v[168:171], v[40:43]
	v_mfma_f32_16x16x32_bf16 v[28:31], v[120:123], v[176:179], v[28:31]
	v_mfma_f32_16x16x32_bf16 v[24:27], v[136:139], v[176:179], v[24:27]
	v_mfma_f32_16x16x32_bf16 v[12:15], v[120:123], v[196:199], v[12:15]
	v_mfma_f32_16x16x32_bf16 v[8:11], v[136:139], v[196:199], v[8:11]
	v_mfma_f32_16x16x32_bf16 v[60:63], v[132:135], v[164:167], v[60:63]
	v_mfma_f32_16x16x32_bf16 v[56:59], v[140:143], v[164:167], v[56:59]
	v_mfma_f32_16x16x32_bf16 v[44:47], v[132:135], v[172:175], v[44:47]
	v_mfma_f32_16x16x32_bf16 v[40:43], v[140:143], v[172:175], v[40:43]
	v_mfma_f32_16x16x32_bf16 v[28:31], v[132:135], v[180:183], v[28:31]
	v_mfma_f32_16x16x32_bf16 v[24:27], v[140:143], v[180:183], v[24:27]
	v_mfma_f32_16x16x32_bf16 v[12:15], v[132:135], v[200:203], v[12:15]
	v_mfma_f32_16x16x32_bf16 v[8:11], v[140:143], v[200:203], v[8:11]
	v_mfma_f32_16x16x32_bf16 v[52:55], v[144:147], v[160:163], v[52:55]
	v_mfma_f32_16x16x32_bf16 v[48:51], v[152:155], v[160:163], v[48:51]
	v_mfma_f32_16x16x32_bf16 v[36:39], v[144:147], v[168:171], v[36:39]
	v_mfma_f32_16x16x32_bf16 v[32:35], v[152:155], v[168:171], v[32:35]
	v_mfma_f32_16x16x32_bf16 v[20:23], v[144:147], v[176:179], v[20:23]
	v_mfma_f32_16x16x32_bf16 v[16:19], v[152:155], v[176:179], v[16:19]
	v_mfma_f32_16x16x32_bf16 v[4:7], v[144:147], v[196:199], v[4:7]
	v_mfma_f32_16x16x32_bf16 v[0:3], v[152:155], v[196:199], v[0:3]
	v_mfma_f32_16x16x32_bf16 v[52:55], v[148:151], v[164:167], v[52:55]
	v_mfma_f32_16x16x32_bf16 v[48:51], v[156:159], v[164:167], v[48:51]
	v_mfma_f32_16x16x32_bf16 v[36:39], v[148:151], v[172:175], v[36:39]
	v_mfma_f32_16x16x32_bf16 v[32:35], v[156:159], v[172:175], v[32:35]
	v_mfma_f32_16x16x32_bf16 v[20:23], v[148:151], v[180:183], v[20:23]
	v_mfma_f32_16x16x32_bf16 v[16:19], v[156:159], v[180:183], v[16:19]
	v_mfma_f32_16x16x32_bf16 v[4:7], v[148:151], v[200:203], v[4:7]
	v_mfma_f32_16x16x32_bf16 v[0:3], v[156:159], v[200:203], v[0:3]
	s_waitcnt vmcnt(4)
	s_barrier
	ds_read_b128 v[120:123], v234
	ds_read_b128 v[132:135], v234 offset:1024
	ds_read_b128 v[136:139], v234 offset:2048
	ds_read_b128 v[140:143], v234 offset:3072
	ds_read_b128 v[144:147], v235
	ds_read_b128 v[148:151], v235 offset:1024
	ds_read_b128 v[152:155], v235 offset:2048
	ds_read_b128 v[156:159], v235 offset:3072
	s_add_u32 s98, s30, s96
	s_addc_u32 s99, s31, s97
	s_add_i32 m0, s85, 0
	v_lshl_add_u64 v[212:213], s[98:99], 0, v[190:191]
	ds_read_b128 v[160:163], v232 offset:32768
	ds_read_b128 v[164:167], v232 offset:33792
	ds_read_b128 v[168:171], v232 offset:34816
	ds_read_b128 v[172:175], v232 offset:35840
	ds_read_b128 v[176:179], v232 offset:36864
	ds_read_b128 v[180:183], v232 offset:37888
	ds_read_b128 v[196:199], v232 offset:38912
	ds_read_b128 v[200:203], v232 offset:39936
	global_load_lds_dwordx4 v[212:213], off
	s_add_u32 s98, s98, 0x20000
	s_addc_u32 s99, s99, 0
	s_add_i32 m0, s85, 0x1000
	v_lshl_add_u64 v[212:213], s[98:99], 0, v[190:191]
	global_load_lds_dwordx4 v[212:213], off
	s_add_u32 s98, s98, 0x20000
	s_addc_u32 s99, s99, 0
	s_add_i32 m0, s85, 0x2000
	v_lshl_add_u64 v[212:213], s[98:99], 0, v[190:191]
	global_load_lds_dwordx4 v[212:213], off
	s_add_u32 s98, s98, 0x20000
	s_addc_u32 s99, s99, 0
	s_add_i32 m0, s85, 0x3000
	v_lshl_add_u64 v[212:213], s[98:99], 0, v[190:191]
	global_load_lds_dwordx4 v[212:213], off
	s_waitcnt vmcnt(8)
	s_waitcnt lgkmcnt(0)
	s_barrier
	s_waitcnt lgkmcnt(0)
	v_mfma_f32_16x16x32_bf16 v[128:131], v[120:123], v[160:163], v[128:131]
	v_mfma_f32_16x16x32_bf16 v[124:127], v[136:139], v[160:163], v[124:127]
	v_mfma_f32_16x16x32_bf16 v[108:111], v[120:123], v[168:171], v[108:111]
	v_mfma_f32_16x16x32_bf16 v[104:107], v[136:139], v[168:171], v[104:107]
	v_mfma_f32_16x16x32_bf16 v[92:95], v[120:123], v[176:179], v[92:95]
	v_mfma_f32_16x16x32_bf16 v[88:91], v[136:139], v[176:179], v[88:91]
	v_mfma_f32_16x16x32_bf16 v[76:79], v[120:123], v[196:199], v[76:79]
	v_mfma_f32_16x16x32_bf16 v[72:75], v[136:139], v[196:199], v[72:75]
	v_mfma_f32_16x16x32_bf16 v[128:131], v[132:135], v[164:167], v[128:131]
	v_mfma_f32_16x16x32_bf16 v[124:127], v[140:143], v[164:167], v[124:127]
	v_mfma_f32_16x16x32_bf16 v[108:111], v[132:135], v[172:175], v[108:111]
	v_mfma_f32_16x16x32_bf16 v[104:107], v[140:143], v[172:175], v[104:107]
	v_mfma_f32_16x16x32_bf16 v[92:95], v[132:135], v[180:183], v[92:95]
	v_mfma_f32_16x16x32_bf16 v[88:91], v[140:143], v[180:183], v[88:91]
	v_mfma_f32_16x16x32_bf16 v[76:79], v[132:135], v[200:203], v[76:79]
	v_mfma_f32_16x16x32_bf16 v[72:75], v[140:143], v[200:203], v[72:75]
	v_mfma_f32_16x16x32_bf16 v[116:119], v[144:147], v[160:163], v[116:119]
	v_mfma_f32_16x16x32_bf16 v[112:115], v[152:155], v[160:163], v[112:115]
	v_mfma_f32_16x16x32_bf16 v[100:103], v[144:147], v[168:171], v[100:103]
	v_mfma_f32_16x16x32_bf16 v[96:99], v[152:155], v[168:171], v[96:99]
	v_mfma_f32_16x16x32_bf16 v[84:87], v[144:147], v[176:179], v[84:87]
	v_mfma_f32_16x16x32_bf16 v[80:83], v[152:155], v[176:179], v[80:83]
	v_mfma_f32_16x16x32_bf16 v[68:71], v[144:147], v[196:199], v[68:71]
	v_mfma_f32_16x16x32_bf16 v[64:67], v[152:155], v[196:199], v[64:67]
	v_mfma_f32_16x16x32_bf16 v[116:119], v[148:151], v[164:167], v[116:119]
	v_mfma_f32_16x16x32_bf16 v[112:115], v[156:159], v[164:167], v[112:115]
	v_mfma_f32_16x16x32_bf16 v[100:103], v[148:151], v[172:175], v[100:103]
	v_mfma_f32_16x16x32_bf16 v[96:99], v[156:159], v[172:175], v[96:99]
	v_mfma_f32_16x16x32_bf16 v[84:87], v[148:151], v[180:183], v[84:87]
	v_mfma_f32_16x16x32_bf16 v[80:83], v[156:159], v[180:183], v[80:83]
	v_mfma_f32_16x16x32_bf16 v[68:71], v[148:151], v[200:203], v[68:71]
	v_mfma_f32_16x16x32_bf16 v[64:67], v[156:159], v[200:203], v[64:67]
	s_barrier
	s_mov_b32 m0, s55
	v_lshl_add_u64 v[204:205], v[204:205], 0, s[18:19]
	ds_read_b128 v[160:163], v232 offset:49152
	ds_read_b128 v[164:167], v232 offset:50176
	ds_read_b128 v[168:171], v232 offset:51200
	ds_read_b128 v[172:175], v232 offset:52224
	ds_read_b128 v[176:179], v232 offset:53248
	ds_read_b128 v[180:183], v232 offset:54272
	ds_read_b128 v[196:199], v232 offset:55296
	ds_read_b128 v[200:203], v232 offset:56320
	global_load_lds_dwordx4 v[204:205], off
	s_add_i32 m0, s55, 0x2000
	s_add_u32 s28, s28, 0x80080
	v_lshl_add_u64 v[204:205], v[206:207], 0, s[18:19]
	s_addc_u32 s29, s29, 0
	s_add_i32 s30, s54, s37
	global_load_lds_dwordx4 v[204:205], off
	v_lshl_add_u64 v[204:205], s[28:29], 0, v[188:189]
	s_mov_b32 m0, s30
	s_nop 0
	global_load_lds_dwordx4 v[204:205], off
	v_lshl_add_u64 v[204:205], s[28:29], 0, v[184:185]
	s_add_i32 m0, s30, 0x2000
	s_nop 0
	global_load_lds_dwordx4 v[204:205], off
	s_waitcnt vmcnt(8)
	s_waitcnt lgkmcnt(0)
	s_barrier
	s_waitcnt lgkmcnt(0)
	v_mfma_f32_16x16x32_bf16 v[60:63], v[120:123], v[160:163], v[60:63]
	v_mfma_f32_16x16x32_bf16 v[56:59], v[136:139], v[160:163], v[56:59]
	v_mfma_f32_16x16x32_bf16 v[44:47], v[120:123], v[168:171], v[44:47]
	v_mfma_f32_16x16x32_bf16 v[40:43], v[136:139], v[168:171], v[40:43]
	v_mfma_f32_16x16x32_bf16 v[28:31], v[120:123], v[176:179], v[28:31]
	v_mfma_f32_16x16x32_bf16 v[24:27], v[136:139], v[176:179], v[24:27]
	v_mfma_f32_16x16x32_bf16 v[12:15], v[120:123], v[196:199], v[12:15]
	v_mfma_f32_16x16x32_bf16 v[8:11], v[136:139], v[196:199], v[8:11]
	v_mfma_f32_16x16x32_bf16 v[60:63], v[132:135], v[164:167], v[60:63]
	v_mfma_f32_16x16x32_bf16 v[56:59], v[140:143], v[164:167], v[56:59]
	v_mfma_f32_16x16x32_bf16 v[44:47], v[132:135], v[172:175], v[44:47]
	v_mfma_f32_16x16x32_bf16 v[40:43], v[140:143], v[172:175], v[40:43]
	v_mfma_f32_16x16x32_bf16 v[28:31], v[132:135], v[180:183], v[28:31]
	v_mfma_f32_16x16x32_bf16 v[24:27], v[140:143], v[180:183], v[24:27]
	v_mfma_f32_16x16x32_bf16 v[12:15], v[132:135], v[200:203], v[12:15]
	v_mfma_f32_16x16x32_bf16 v[8:11], v[140:143], v[200:203], v[8:11]
	v_mfma_f32_16x16x32_bf16 v[52:55], v[144:147], v[160:163], v[52:55]
	v_mfma_f32_16x16x32_bf16 v[48:51], v[152:155], v[160:163], v[48:51]
	v_mfma_f32_16x16x32_bf16 v[36:39], v[144:147], v[168:171], v[36:39]
	v_mfma_f32_16x16x32_bf16 v[32:35], v[152:155], v[168:171], v[32:35]
	v_mfma_f32_16x16x32_bf16 v[20:23], v[144:147], v[176:179], v[20:23]
	v_mfma_f32_16x16x32_bf16 v[16:19], v[152:155], v[176:179], v[16:19]
	v_mfma_f32_16x16x32_bf16 v[4:7], v[144:147], v[196:199], v[4:7]
	v_mfma_f32_16x16x32_bf16 v[0:3], v[152:155], v[196:199], v[0:3]
	v_mfma_f32_16x16x32_bf16 v[52:55], v[148:151], v[164:167], v[52:55]
	v_mfma_f32_16x16x32_bf16 v[48:51], v[156:159], v[164:167], v[48:51]
	v_mfma_f32_16x16x32_bf16 v[36:39], v[148:151], v[172:175], v[36:39]
	v_mfma_f32_16x16x32_bf16 v[32:35], v[156:159], v[172:175], v[32:35]
	v_mfma_f32_16x16x32_bf16 v[20:23], v[148:151], v[180:183], v[20:23]
	v_mfma_f32_16x16x32_bf16 v[16:19], v[156:159], v[180:183], v[16:19]
	v_mfma_f32_16x16x32_bf16 v[4:7], v[148:151], v[200:203], v[4:7]
	v_mfma_f32_16x16x32_bf16 v[0:3], v[156:159], v[200:203], v[0:3]
	s_waitcnt vmcnt(4)
	s_add_i32 s58, s58, 2
	s_add_u32 s2, s2, 0x100
	s_addc_u32 s3, s3, 0
	s_cmp_gt_u32 s58, 29
	s_barrier
	s_cbranch_scc0 .LBB0_1825
	s_setprio 0
	s_and_b64 vcc, exec, s[22:23]
	s_cbranch_vccz .LBB0_1828
	s_barrier

.Lprio_skip13:
.LBB0_1955:
	ds_read_b128 v[140:143], v150
	ds_read_b128 v[144:147], v150 offset:1024
	ds_read_b128 v[156:159], v150 offset:2048
	ds_read_b128 v[160:163], v150 offset:3072
	ds_read_b128 v[164:167], v151
	ds_read_b128 v[168:171], v151 offset:1024
	ds_read_b128 v[172:175], v151 offset:2048
	ds_read_b128 v[176:179], v151 offset:3072
	s_add_u32 s36, s0, 0xfff80080
	s_addc_u32 s37, s1, -1
	s_cmp_eq_u32 s74, 28
	s_cselect_b32 s39, s68, s37
	s_cselect_b32 s38, s69, s36
	s_cselect_b32 s37, s70, s73
	s_cselect_b32 s36, s71, s72
	s_sub_u32 s98, s0, 0x80000
	s_subb_u32 s99, s1, 0
	s_add_i32 m0, s85, 0x8000
	ds_read_b128 v[180:183], v152
	ds_read_b128 v[184:187], v152 offset:1024
	ds_read_b128 v[188:191], v152 offset:2048
	ds_read_b128 v[192:195], v152 offset:3072
	ds_read_b128 v[196:199], v152 offset:4096
	ds_read_b128 v[200:203], v152 offset:5120
	ds_read_b128 v[204:207], v152 offset:6144
	ds_read_b128 v[208:211], v152 offset:7168
	global_load_lds_dwordx4 v222, s[98:99]
	s_add_u32 s98, s98, 0x20000
	s_addc_u32 s99, s99, 0
	s_add_i32 m0, s85, 0x9000
	s_nop 0
	global_load_lds_dwordx4 v222, s[98:99]
	s_add_u32 s98, s98, 0x20000
	s_addc_u32 s99, s99, 0
	s_add_i32 m0, s85, 0xa000
	s_nop 0
	global_load_lds_dwordx4 v222, s[98:99]
	s_add_u32 s98, s98, 0x20000
	s_addc_u32 s99, s99, 0
	s_add_i32 m0, s85, 0xb000
	s_nop 0
	global_load_lds_dwordx4 v222, s[98:99]
	s_waitcnt vmcnt(8)
	s_waitcnt lgkmcnt(0)
	s_barrier
	s_waitcnt lgkmcnt(0)
	v_mfma_f32_16x16x32_bf16 v[124:127], v[140:143], v[180:183], v[124:127]
	v_mfma_f32_16x16x32_bf16 v[120:123], v[156:159], v[180:183], v[120:123]
	v_mfma_f32_16x16x32_bf16 v[108:111], v[140:143], v[188:191], v[108:111]
	v_mfma_f32_16x16x32_bf16 v[104:107], v[156:159], v[188:191], v[104:107]
	v_mfma_f32_16x16x32_bf16 v[92:95], v[140:143], v[196:199], v[92:95]
	v_mfma_f32_16x16x32_bf16 v[88:91], v[156:159], v[196:199], v[88:91]
	v_mfma_f32_16x16x32_bf16 v[76:79], v[140:143], v[204:207], v[76:79]
	v_mfma_f32_16x16x32_bf16 v[72:75], v[156:159], v[204:207], v[72:75]
	v_mfma_f32_16x16x32_bf16 v[124:127], v[144:147], v[184:187], v[124:127]
	v_mfma_f32_16x16x32_bf16 v[120:123], v[160:163], v[184:187], v[120:123]
	v_mfma_f32_16x16x32_bf16 v[108:111], v[144:147], v[192:195], v[108:111]
	v_mfma_f32_16x16x32_bf16 v[104:107], v[160:163], v[192:195], v[104:107]
	v_mfma_f32_16x16x32_bf16 v[92:95], v[144:147], v[200:203], v[92:95]
	v_mfma_f32_16x16x32_bf16 v[88:91], v[160:163], v[200:203], v[88:91]
	v_mfma_f32_16x16x32_bf16 v[76:79], v[144:147], v[208:211], v[76:79]
	v_mfma_f32_16x16x32_bf16 v[72:75], v[160:163], v[208:211], v[72:75]
	v_mfma_f32_16x16x32_bf16 v[116:119], v[164:167], v[180:183], v[116:119]
	v_mfma_f32_16x16x32_bf16 v[112:115], v[172:175], v[180:183], v[112:115]
	v_mfma_f32_16x16x32_bf16 v[100:103], v[164:167], v[188:191], v[100:103]
	v_mfma_f32_16x16x32_bf16 v[96:99], v[172:175], v[188:191], v[96:99]
	v_mfma_f32_16x16x32_bf16 v[84:87], v[164:167], v[196:199], v[84:87]
	v_mfma_f32_16x16x32_bf16 v[80:83], v[172:175], v[196:199], v[80:83]
	v_mfma_f32_16x16x32_bf16 v[68:71], v[164:167], v[204:207], v[68:71]
	v_mfma_f32_16x16x32_bf16 v[64:67], v[172:175], v[204:207], v[64:67]
	v_mfma_f32_16x16x32_bf16 v[116:119], v[168:171], v[184:187], v[116:119]
	v_mfma_f32_16x16x32_bf16 v[112:115], v[176:179], v[184:187], v[112:115]
	v_mfma_f32_16x16x32_bf16 v[100:103], v[168:171], v[192:195], v[100:103]
	v_mfma_f32_16x16x32_bf16 v[96:99], v[176:179], v[192:195], v[96:99]
	v_mfma_f32_16x16x32_bf16 v[84:87], v[168:171], v[200:203], v[84:87]
	v_mfma_f32_16x16x32_bf16 v[80:83], v[176:179], v[200:203], v[80:83]
	v_mfma_f32_16x16x32_bf16 v[68:71], v[168:171], v[208:211], v[68:71]
	v_mfma_f32_16x16x32_bf16 v[64:67], v[176:179], v[208:211], v[64:67]
	s_barrier
	s_add_i32 s75, s56, s7
	v_lshl_add_u64 v[212:213], s[36:37], 0, v[130:131]
	s_mov_b32 m0, s75
	ds_read_b128 v[180:183], v152 offset:16384
	ds_read_b128 v[184:187], v152 offset:17408
	ds_read_b128 v[188:191], v152 offset:18432
	ds_read_b128 v[192:195], v152 offset:19456
	ds_read_b128 v[196:199], v152 offset:20480
	ds_read_b128 v[200:203], v152 offset:21504
	ds_read_b128 v[204:207], v152 offset:22528
	ds_read_b128 v[208:211], v152 offset:23552
	global_load_lds_dwordx4 v[212:213], off
	s_add_i32 m0, s75, 0x2000
	s_add_u32 s76, s36, 0x80000
	v_lshl_add_u64 v[214:215], s[36:37], 0, v[134:135]
	s_addc_u32 s77, s37, 0
	s_add_i32 s75, s57, s7
	global_load_lds_dwordx4 v[214:215], off
	v_lshl_add_u64 v[216:217], s[76:77], 0, v[130:131]
	s_mov_b32 m0, s75
	global_load_lds_dwordx4 v[216:217], off
	v_lshl_add_u64 v[216:217], s[76:77], 0, v[134:135]
	s_add_i32 m0, s75, 0x2000
	s_nop 0
	global_load_lds_dwordx4 v[216:217], off
	s_waitcnt vmcnt(8)
	s_waitcnt lgkmcnt(0)
	s_barrier
	s_waitcnt lgkmcnt(0)
	v_mfma_f32_16x16x32_bf16 v[60:63], v[140:143], v[180:183], v[60:63]
	v_mfma_f32_16x16x32_bf16 v[56:59], v[156:159], v[180:183], v[56:59]
	v_mfma_f32_16x16x32_bf16 v[44:47], v[140:143], v[188:191], v[44:47]
	v_mfma_f32_16x16x32_bf16 v[40:43], v[156:159], v[188:191], v[40:43]
	v_mfma_f32_16x16x32_bf16 v[28:31], v[140:143], v[196:199], v[28:31]
	v_mfma_f32_16x16x32_bf16 v[24:27], v[156:159], v[196:199], v[24:27]
	v_mfma_f32_16x16x32_bf16 v[12:15], v[140:143], v[204:207], v[12:15]
	v_mfma_f32_16x16x32_bf16 v[8:11], v[156:159], v[204:207], v[8:11]
	v_mfma_f32_16x16x32_bf16 v[60:63], v[144:147], v[184:187], v[60:63]
	v_mfma_f32_16x16x32_bf16 v[56:59], v[160:163], v[184:187], v[56:59]
	v_mfma_f32_16x16x32_bf16 v[44:47], v[144:147], v[192:195], v[44:47]
	v_mfma_f32_16x16x32_bf16 v[40:43], v[160:163], v[192:195], v[40:43]
	v_mfma_f32_16x16x32_bf16 v[28:31], v[144:147], v[200:203], v[28:31]
	v_mfma_f32_16x16x32_bf16 v[24:27], v[160:163], v[200:203], v[24:27]
	v_mfma_f32_16x16x32_bf16 v[12:15], v[144:147], v[208:211], v[12:15]
	v_mfma_f32_16x16x32_bf16 v[8:11], v[160:163], v[208:211], v[8:11]
	v_mfma_f32_16x16x32_bf16 v[52:55], v[164:167], v[180:183], v[52:55]
	v_mfma_f32_16x16x32_bf16 v[48:51], v[172:175], v[180:183], v[48:51]
	v_mfma_f32_16x16x32_bf16 v[36:39], v[164:167], v[188:191], v[36:39]
	v_mfma_f32_16x16x32_bf16 v[32:35], v[172:175], v[188:191], v[32:35]
	v_mfma_f32_16x16x32_bf16 v[20:23], v[164:167], v[196:199], v[20:23]
	v_mfma_f32_16x16x32_bf16 v[16:19], v[172:175], v[196:199], v[16:19]
	v_mfma_f32_16x16x32_bf16 v[4:7], v[164:167], v[204:207], v[4:7]
	v_mfma_f32_16x16x32_bf16 v[0:3], v[172:175], v[204:207], v[0:3]
	v_mfma_f32_16x16x32_bf16 v[52:55], v[168:171], v[184:187], v[52:55]
	v_mfma_f32_16x16x32_bf16 v[48:51], v[176:179], v[184:187], v[48:51]
	v_mfma_f32_16x16x32_bf16 v[36:39], v[168:171], v[192:195], v[36:39]
	v_mfma_f32_16x16x32_bf16 v[32:35], v[176:179], v[192:195], v[32:35]
	v_mfma_f32_16x16x32_bf16 v[20:23], v[168:171], v[200:203], v[20:23]
	v_mfma_f32_16x16x32_bf16 v[16:19], v[176:179], v[200:203], v[16:19]
	v_mfma_f32_16x16x32_bf16 v[4:7], v[168:171], v[208:211], v[4:7]
	v_mfma_f32_16x16x32_bf16 v[0:3], v[176:179], v[208:211], v[0:3]
	s_waitcnt vmcnt(4)
	s_barrier
	ds_read_b128 v[140:143], v153
	ds_read_b128 v[144:147], v153 offset:1024
	ds_read_b128 v[156:159], v153 offset:2048
	ds_read_b128 v[160:163], v153 offset:3072
	ds_read_b128 v[164:167], v154
	ds_read_b128 v[168:171], v154 offset:1024
	ds_read_b128 v[172:175], v154 offset:2048
	ds_read_b128 v[176:179], v154 offset:3072
	s_mov_b32 s98, s38
	s_mov_b32 s99, s39
	s_add_i32 m0, s85, 0
	ds_read_b128 v[180:183], v152 offset:32768
	ds_read_b128 v[184:187], v152 offset:33792
	ds_read_b128 v[188:191], v152 offset:34816
	ds_read_b128 v[192:195], v152 offset:35840
	ds_read_b128 v[196:199], v152 offset:36864
	ds_read_b128 v[200:203], v152 offset:37888
	ds_read_b128 v[204:207], v152 offset:38912
	ds_read_b128 v[208:211], v152 offset:39936
	global_load_lds_dwordx4 v222, s[98:99]
	s_add_u32 s98, s98, 0x20000
	s_addc_u32 s99, s99, 0
	s_add_i32 m0, s85, 0x1000
	s_nop 0
	global_load_lds_dwordx4 v222, s[98:99]
	s_add_u32 s98, s98, 0x20000
	s_addc_u32 s99, s99, 0
	s_add_i32 m0, s85, 0x2000
	s_nop 0
	global_load_lds_dwordx4 v222, s[98:99]
	s_add_u32 s98, s98, 0x20000
	s_addc_u32 s99, s99, 0
	s_add_i32 m0, s85, 0x3000
	s_nop 0
	global_load_lds_dwordx4 v222, s[98:99]
	s_waitcnt vmcnt(8)
	s_waitcnt lgkmcnt(0)
	s_barrier
	s_waitcnt lgkmcnt(0)
	v_mfma_f32_16x16x32_bf16 v[124:127], v[140:143], v[180:183], v[124:127]
	v_mfma_f32_16x16x32_bf16 v[120:123], v[156:159], v[180:183], v[120:123]
	v_mfma_f32_16x16x32_bf16 v[108:111], v[140:143], v[188:191], v[108:111]
	v_mfma_f32_16x16x32_bf16 v[104:107], v[156:159], v[188:191], v[104:107]
	v_mfma_f32_16x16x32_bf16 v[92:95], v[140:143], v[196:199], v[92:95]
	v_mfma_f32_16x16x32_bf16 v[88:91], v[156:159], v[196:199], v[88:91]
	v_mfma_f32_16x16x32_bf16 v[76:79], v[140:143], v[204:207], v[76:79]
	v_mfma_f32_16x16x32_bf16 v[72:75], v[156:159], v[204:207], v[72:75]
	v_mfma_f32_16x16x32_bf16 v[124:127], v[144:147], v[184:187], v[124:127]
	v_mfma_f32_16x16x32_bf16 v[120:123], v[160:163], v[184:187], v[120:123]
	v_mfma_f32_16x16x32_bf16 v[108:111], v[144:147], v[192:195], v[108:111]
	v_mfma_f32_16x16x32_bf16 v[104:107], v[160:163], v[192:195], v[104:107]
	v_mfma_f32_16x16x32_bf16 v[92:95], v[144:147], v[200:203], v[92:95]
	v_mfma_f32_16x16x32_bf16 v[88:91], v[160:163], v[200:203], v[88:91]
	v_mfma_f32_16x16x32_bf16 v[76:79], v[144:147], v[208:211], v[76:79]
	v_mfma_f32_16x16x32_bf16 v[72:75], v[160:163], v[208:211], v[72:75]
	v_mfma_f32_16x16x32_bf16 v[116:119], v[164:167], v[180:183], v[116:119]
	v_mfma_f32_16x16x32_bf16 v[112:115], v[172:175], v[180:183], v[112:115]
	v_mfma_f32_16x16x32_bf16 v[100:103], v[164:167], v[188:191], v[100:103]
	v_mfma_f32_16x16x32_bf16 v[96:99], v[172:175], v[188:191], v[96:99]
	v_mfma_f32_16x16x32_bf16 v[84:87], v[164:167], v[196:199], v[84:87]
	v_mfma_f32_16x16x32_bf16 v[80:83], v[172:175], v[196:199], v[80:83]
	v_mfma_f32_16x16x32_bf16 v[68:71], v[164:167], v[204:207], v[68:71]
	v_mfma_f32_16x16x32_bf16 v[64:67], v[172:175], v[204:207], v[64:67]
	v_mfma_f32_16x16x32_bf16 v[116:119], v[168:171], v[184:187], v[116:119]
	v_mfma_f32_16x16x32_bf16 v[112:115], v[176:179], v[184:187], v[112:115]
	v_mfma_f32_16x16x32_bf16 v[100:103], v[168:171], v[192:195], v[100:103]
	v_mfma_f32_16x16x32_bf16 v[96:99], v[176:179], v[192:195], v[96:99]
	v_mfma_f32_16x16x32_bf16 v[84:87], v[168:171], v[200:203], v[84:87]
	v_mfma_f32_16x16x32_bf16 v[80:83], v[176:179], v[200:203], v[80:83]
	v_mfma_f32_16x16x32_bf16 v[68:71], v[168:171], v[208:211], v[68:71]
	v_mfma_f32_16x16x32_bf16 v[64:67], v[176:179], v[208:211], v[64:67]
	s_barrier
	s_add_i32 s38, s58, s7
	v_lshl_add_u64 v[212:213], v[212:213], 0, s[14:15]
	s_mov_b32 m0, s38
	ds_read_b128 v[180:183], v152 offset:49152
	ds_read_b128 v[184:187], v152 offset:50176
	ds_read_b128 v[188:191], v152 offset:51200
	ds_read_b128 v[192:195], v152 offset:52224
	ds_read_b128 v[196:199], v152 offset:53248
	ds_read_b128 v[200:203], v152 offset:54272
	ds_read_b128 v[204:207], v152 offset:55296
	ds_read_b128 v[208:211], v152 offset:56320
	global_load_lds_dwordx4 v[212:213], off
	s_add_i32 m0, s38, 0x2000
	s_add_u32 s36, s36, 0x80080
	v_lshl_add_u64 v[212:213], v[214:215], 0, s[14:15]
	s_addc_u32 s37, s37, 0
	s_add_i32 s38, s59, s7
	global_load_lds_dwordx4 v[212:213], off
	v_lshl_add_u64 v[212:213], s[36:37], 0, v[130:131]
	s_mov_b32 m0, s38
	s_nop 0
	global_load_lds_dwordx4 v[212:213], off
	v_lshl_add_u64 v[212:213], s[36:37], 0, v[134:135]
	s_add_i32 m0, s38, 0x2000
	s_nop 0
	global_load_lds_dwordx4 v[212:213], off
	s_waitcnt vmcnt(8)
	s_waitcnt lgkmcnt(0)
	s_barrier
	s_waitcnt lgkmcnt(0)
	v_mfma_f32_16x16x32_bf16 v[60:63], v[140:143], v[180:183], v[60:63]
	v_mfma_f32_16x16x32_bf16 v[56:59], v[156:159], v[180:183], v[56:59]
	v_mfma_f32_16x16x32_bf16 v[44:47], v[140:143], v[188:191], v[44:47]
	v_mfma_f32_16x16x32_bf16 v[40:43], v[156:159], v[188:191], v[40:43]
	v_mfma_f32_16x16x32_bf16 v[28:31], v[140:143], v[196:199], v[28:31]
	v_mfma_f32_16x16x32_bf16 v[24:27], v[156:159], v[196:199], v[24:27]
	v_mfma_f32_16x16x32_bf16 v[12:15], v[140:143], v[204:207], v[12:15]
	v_mfma_f32_16x16x32_bf16 v[8:11], v[156:159], v[204:207], v[8:11]
	v_mfma_f32_16x16x32_bf16 v[60:63], v[144:147], v[184:187], v[60:63]
	v_mfma_f32_16x16x32_bf16 v[56:59], v[160:163], v[184:187], v[56:59]
	v_mfma_f32_16x16x32_bf16 v[44:47], v[144:147], v[192:195], v[44:47]
	v_mfma_f32_16x16x32_bf16 v[40:43], v[160:163], v[192:195], v[40:43]
	v_mfma_f32_16x16x32_bf16 v[28:31], v[144:147], v[200:203], v[28:31]
	v_mfma_f32_16x16x32_bf16 v[24:27], v[160:163], v[200:203], v[24:27]
	v_mfma_f32_16x16x32_bf16 v[12:15], v[144:147], v[208:211], v[12:15]
	v_mfma_f32_16x16x32_bf16 v[8:11], v[160:163], v[208:211], v[8:11]
	v_mfma_f32_16x16x32_bf16 v[52:55], v[164:167], v[180:183], v[52:55]
	v_mfma_f32_16x16x32_bf16 v[48:51], v[172:175], v[180:183], v[48:51]
	v_mfma_f32_16x16x32_bf16 v[36:39], v[164:167], v[188:191], v[36:39]
	v_mfma_f32_16x16x32_bf16 v[32:35], v[172:175], v[188:191], v[32:35]
	v_mfma_f32_16x16x32_bf16 v[20:23], v[164:167], v[196:199], v[20:23]
	v_mfma_f32_16x16x32_bf16 v[16:19], v[172:175], v[196:199], v[16:19]
	v_mfma_f32_16x16x32_bf16 v[4:7], v[164:167], v[204:207], v[4:7]
	v_mfma_f32_16x16x32_bf16 v[0:3], v[172:175], v[204:207], v[0:3]
	v_mfma_f32_16x16x32_bf16 v[52:55], v[168:171], v[184:187], v[52:55]
	v_mfma_f32_16x16x32_bf16 v[48:51], v[176:179], v[184:187], v[48:51]
	v_mfma_f32_16x16x32_bf16 v[36:39], v[168:171], v[192:195], v[36:39]
	v_mfma_f32_16x16x32_bf16 v[32:35], v[176:179], v[192:195], v[32:35]
	v_mfma_f32_16x16x32_bf16 v[20:23], v[168:171], v[200:203], v[20:23]
	v_mfma_f32_16x16x32_bf16 v[16:19], v[176:179], v[200:203], v[16:19]
	v_mfma_f32_16x16x32_bf16 v[4:7], v[168:171], v[208:211], v[4:7]
	v_mfma_f32_16x16x32_bf16 v[0:3], v[176:179], v[208:211], v[0:3]
	s_waitcnt vmcnt(4)
	s_add_i32 s74, s74, 2
	s_add_u32 s0, s0, 0x100
	s_addc_u32 s1, s1, 0
	s_add_u32 s72, s72, 0x100
	s_addc_u32 s73, s73, 0
	s_cmp_gt_u32 s74, 29
	s_barrier
	s_cbranch_scc0 .LBB0_1955
	s_setprio 0
	s_and_b64 vcc, exec, s[16:17]
	s_cbranch_vccz .LBB0_1958
	s_barrier

.Lprio_skip14:
.LBB0_2063:
	v_add_u32_e32 v147, s33, v145
	ds_read_b128 v[148:151], v147
	ds_read_b128 v[152:155], v147 offset:1024
	ds_read_b128 v[156:159], v147 offset:2048
	ds_read_b128 v[160:163], v147 offset:3072
	v_add_u32_e32 v147, s45, v145
	s_add_u32 s24, s18, s22
	ds_read_b128 v[164:167], v147
	ds_read_b128 v[168:171], v147 offset:1024
	ds_read_b128 v[172:175], v147 offset:2048
	ds_read_b128 v[176:179], v147 offset:3072
	s_addc_u32 s25, s19, s23
	s_add_u32 s24, s24, 0x100
	s_addc_u32 s25, s25, 0
	s_add_u32 s63, s56, s22
	s_addc_u32 s64, s57, s23
	s_cmpk_eq_i32 s22, 0x3f00
	s_cselect_b32 s27, s58, s25
	s_cselect_b32 s26, s59, s24
	s_cselect_b32 s25, s60, s64
	s_cselect_b32 s24, s61, s63
	s_add_u32 s98, s22, s86
	s_addc_u32 s99, s23, s87
	s_add_i32 m0, s85, 0x8000
	v_lshl_add_u64 v[214:215], v[140:141], 0, s[98:99]
	ds_read_b128 v[180:183], v146
	ds_read_b128 v[184:187], v146 offset:1024
	ds_read_b128 v[188:191], v146 offset:2048
	ds_read_b128 v[192:195], v146 offset:3072
	ds_read_b128 v[196:199], v146 offset:4096
	ds_read_b128 v[202:205], v146 offset:5120
	ds_read_b128 v[206:209], v146 offset:6144
	ds_read_b128 v[210:213], v146 offset:7168
	global_load_lds_dwordx4 v[214:215], off
	s_add_u32 s98, s98, 0x80000
	s_addc_u32 s99, s99, 0
	s_add_i32 m0, s85, 0x9000
	v_lshl_add_u64 v[214:215], v[140:141], 0, s[98:99]
	global_load_lds_dwordx4 v[214:215], off
	s_add_u32 s98, s98, 0x80000
	s_addc_u32 s99, s99, 0
	s_add_i32 m0, s85, 0xa000
	v_lshl_add_u64 v[214:215], v[140:141], 0, s[98:99]
	global_load_lds_dwordx4 v[214:215], off
	s_add_u32 s98, s98, 0x80000
	s_addc_u32 s99, s99, 0
	s_add_i32 m0, s85, 0xb000
	v_lshl_add_u64 v[214:215], v[140:141], 0, s[98:99]
	global_load_lds_dwordx4 v[214:215], off
	s_waitcnt vmcnt(8)
	s_waitcnt lgkmcnt(0)
	s_barrier
	s_waitcnt lgkmcnt(0)
	v_mfma_f32_16x16x32_bf16 v[124:127], v[148:151], v[180:183], v[124:127]
	v_mfma_f32_16x16x32_bf16 v[120:123], v[156:159], v[180:183], v[120:123]
	v_mfma_f32_16x16x32_bf16 v[108:111], v[148:151], v[188:191], v[108:111]
	v_mfma_f32_16x16x32_bf16 v[104:107], v[156:159], v[188:191], v[104:107]
	v_mfma_f32_16x16x32_bf16 v[92:95], v[148:151], v[196:199], v[92:95]
	v_mfma_f32_16x16x32_bf16 v[88:91], v[156:159], v[196:199], v[88:91]
	v_mfma_f32_16x16x32_bf16 v[76:79], v[148:151], v[206:209], v[76:79]
	v_mfma_f32_16x16x32_bf16 v[72:75], v[156:159], v[206:209], v[72:75]
	v_mfma_f32_16x16x32_bf16 v[124:127], v[152:155], v[184:187], v[124:127]
	v_mfma_f32_16x16x32_bf16 v[120:123], v[160:163], v[184:187], v[120:123]
	v_mfma_f32_16x16x32_bf16 v[108:111], v[152:155], v[192:195], v[108:111]
	v_mfma_f32_16x16x32_bf16 v[104:107], v[160:163], v[192:195], v[104:107]
	v_mfma_f32_16x16x32_bf16 v[92:95], v[152:155], v[202:205], v[92:95]
	v_mfma_f32_16x16x32_bf16 v[88:91], v[160:163], v[202:205], v[88:91]
	v_mfma_f32_16x16x32_bf16 v[76:79], v[152:155], v[210:213], v[76:79]
	v_mfma_f32_16x16x32_bf16 v[72:75], v[160:163], v[210:213], v[72:75]
	v_mfma_f32_16x16x32_bf16 v[116:119], v[164:167], v[180:183], v[116:119]
	v_mfma_f32_16x16x32_bf16 v[112:115], v[172:175], v[180:183], v[112:115]
	v_mfma_f32_16x16x32_bf16 v[100:103], v[164:167], v[188:191], v[100:103]
	v_mfma_f32_16x16x32_bf16 v[96:99], v[172:175], v[188:191], v[96:99]
	v_mfma_f32_16x16x32_bf16 v[84:87], v[164:167], v[196:199], v[84:87]
	v_mfma_f32_16x16x32_bf16 v[80:83], v[172:175], v[196:199], v[80:83]
	v_mfma_f32_16x16x32_bf16 v[68:71], v[164:167], v[206:209], v[68:71]
	v_mfma_f32_16x16x32_bf16 v[64:67], v[172:175], v[206:209], v[64:67]
	v_mfma_f32_16x16x32_bf16 v[116:119], v[168:171], v[184:187], v[116:119]
	v_mfma_f32_16x16x32_bf16 v[112:115], v[176:179], v[184:187], v[112:115]
	v_mfma_f32_16x16x32_bf16 v[100:103], v[168:171], v[192:195], v[100:103]
	v_mfma_f32_16x16x32_bf16 v[96:99], v[176:179], v[192:195], v[96:99]
	v_mfma_f32_16x16x32_bf16 v[84:87], v[168:171], v[202:205], v[84:87]
	v_mfma_f32_16x16x32_bf16 v[80:83], v[176:179], v[202:205], v[80:83]
	v_mfma_f32_16x16x32_bf16 v[68:71], v[168:171], v[210:213], v[68:71]
	v_mfma_f32_16x16x32_bf16 v[64:67], v[176:179], v[210:213], v[64:67]
	s_barrier
	s_mov_b32 m0, s48
	v_lshl_add_u64 v[214:215], s[24:25], 0, v[132:133]
	s_add_u32 s64, s24, 0x200000
	ds_read_b128 v[180:183], v146 offset:16384
	ds_read_b128 v[184:187], v146 offset:17408
	ds_read_b128 v[188:191], v146 offset:18432
	ds_read_b128 v[192:195], v146 offset:19456
	ds_read_b128 v[196:199], v146 offset:20480
	ds_read_b128 v[202:205], v146 offset:21504
	ds_read_b128 v[206:209], v146 offset:22528
	ds_read_b128 v[210:213], v146 offset:23552
	global_load_lds_dwordx4 v[214:215], off
	v_lshl_add_u64 v[216:217], s[24:25], 0, v[128:129]
	s_mov_b32 m0, s49
	s_addc_u32 s65, s25, 0
	global_load_lds_dwordx4 v[216:217], off
	v_lshl_add_u64 v[218:219], s[64:65], 0, v[132:133]
	s_mov_b32 m0, s50
	global_load_lds_dwordx4 v[218:219], off
	v_lshl_add_u64 v[218:219], s[64:65], 0, v[128:129]
	s_mov_b32 m0, s51
	s_nop 0
	global_load_lds_dwordx4 v[218:219], off
	s_waitcnt vmcnt(8)
	s_waitcnt lgkmcnt(0)
	s_barrier
	s_waitcnt lgkmcnt(0)
	v_mfma_f32_16x16x32_bf16 v[60:63], v[148:151], v[180:183], v[60:63]
	v_mfma_f32_16x16x32_bf16 v[56:59], v[156:159], v[180:183], v[56:59]
	v_mfma_f32_16x16x32_bf16 v[44:47], v[148:151], v[188:191], v[44:47]
	v_mfma_f32_16x16x32_bf16 v[40:43], v[156:159], v[188:191], v[40:43]
	v_mfma_f32_16x16x32_bf16 v[28:31], v[148:151], v[196:199], v[28:31]
	v_mfma_f32_16x16x32_bf16 v[24:27], v[156:159], v[196:199], v[24:27]
	v_mfma_f32_16x16x32_bf16 v[12:15], v[148:151], v[206:209], v[12:15]
	v_mfma_f32_16x16x32_bf16 v[8:11], v[156:159], v[206:209], v[8:11]
	v_mfma_f32_16x16x32_bf16 v[60:63], v[152:155], v[184:187], v[60:63]
	v_mfma_f32_16x16x32_bf16 v[56:59], v[160:163], v[184:187], v[56:59]
	v_mfma_f32_16x16x32_bf16 v[44:47], v[152:155], v[192:195], v[44:47]
	v_mfma_f32_16x16x32_bf16 v[40:43], v[160:163], v[192:195], v[40:43]
	v_mfma_f32_16x16x32_bf16 v[28:31], v[152:155], v[202:205], v[28:31]
	v_mfma_f32_16x16x32_bf16 v[24:27], v[160:163], v[202:205], v[24:27]
	v_mfma_f32_16x16x32_bf16 v[12:15], v[152:155], v[210:213], v[12:15]
	v_mfma_f32_16x16x32_bf16 v[8:11], v[160:163], v[210:213], v[8:11]
	v_mfma_f32_16x16x32_bf16 v[52:55], v[164:167], v[180:183], v[52:55]
	v_mfma_f32_16x16x32_bf16 v[48:51], v[172:175], v[180:183], v[48:51]
	v_mfma_f32_16x16x32_bf16 v[36:39], v[164:167], v[188:191], v[36:39]
	v_mfma_f32_16x16x32_bf16 v[32:35], v[172:175], v[188:191], v[32:35]
	v_mfma_f32_16x16x32_bf16 v[20:23], v[164:167], v[196:199], v[20:23]
	v_mfma_f32_16x16x32_bf16 v[16:19], v[172:175], v[196:199], v[16:19]
	v_mfma_f32_16x16x32_bf16 v[4:7], v[164:167], v[206:209], v[4:7]
	v_mfma_f32_16x16x32_bf16 v[0:3], v[172:175], v[206:209], v[0:3]
	v_mfma_f32_16x16x32_bf16 v[52:55], v[168:171], v[184:187], v[52:55]
	v_mfma_f32_16x16x32_bf16 v[48:51], v[176:179], v[184:187], v[48:51]
	v_mfma_f32_16x16x32_bf16 v[36:39], v[168:171], v[192:195], v[36:39]
	v_mfma_f32_16x16x32_bf16 v[32:35], v[176:179], v[192:195], v[32:35]
	v_mfma_f32_16x16x32_bf16 v[20:23], v[168:171], v[202:205], v[20:23]
	v_mfma_f32_16x16x32_bf16 v[16:19], v[176:179], v[202:205], v[16:19]
	v_mfma_f32_16x16x32_bf16 v[4:7], v[168:171], v[210:213], v[4:7]
	v_mfma_f32_16x16x32_bf16 v[0:3], v[176:179], v[210:213], v[0:3]
	s_waitcnt vmcnt(4)
	s_barrier
	v_add_u32_e32 v147, s52, v145
	s_add_i32 s63, 0, 0x1c000
	ds_read_b128 v[148:151], v147
	ds_read_b128 v[152:155], v147 offset:1024
	ds_read_b128 v[156:159], v147 offset:2048
	ds_read_b128 v[160:163], v147 offset:3072
	v_add_u32_e32 v147, s63, v145
	ds_read_b128 v[164:167], v147
	ds_read_b128 v[168:171], v147 offset:1024
	ds_read_b128 v[172:175], v147 offset:2048
	ds_read_b128 v[176:179], v147 offset:3072
	s_add_u32 s98, s26, s96
	s_addc_u32 s99, s27, s97
	s_add_i32 m0, s85, 0
	v_lshl_add_u64 v[222:223], s[98:99], 0, v[134:135]
	ds_read_b128 v[180:183], v146 offset:32768
	ds_read_b128 v[184:187], v146 offset:33792
	ds_read_b128 v[188:191], v146 offset:34816
	ds_read_b128 v[192:195], v146 offset:35840
	ds_read_b128 v[196:199], v146 offset:36864
	ds_read_b128 v[202:205], v146 offset:37888
	ds_read_b128 v[206:209], v146 offset:38912
	ds_read_b128 v[210:213], v146 offset:39936
	global_load_lds_dwordx4 v[222:223], off
	s_add_u32 s98, s98, 0x80000
	s_addc_u32 s99, s99, 0
	s_add_i32 m0, s85, 0x1000
	v_lshl_add_u64 v[222:223], s[98:99], 0, v[134:135]
	global_load_lds_dwordx4 v[222:223], off
	s_add_u32 s98, s98, 0x80000
	s_addc_u32 s99, s99, 0
	s_add_i32 m0, s85, 0x2000
	v_lshl_add_u64 v[222:223], s[98:99], 0, v[134:135]
	global_load_lds_dwordx4 v[222:223], off
	s_add_u32 s98, s98, 0x80000
	s_addc_u32 s99, s99, 0
	s_add_i32 m0, s85, 0x3000
	v_lshl_add_u64 v[222:223], s[98:99], 0, v[134:135]
	global_load_lds_dwordx4 v[222:223], off
	s_waitcnt vmcnt(8)
	s_waitcnt lgkmcnt(0)
	s_barrier
	s_waitcnt lgkmcnt(0)
	v_mfma_f32_16x16x32_bf16 v[124:127], v[148:151], v[180:183], v[124:127]
	v_mfma_f32_16x16x32_bf16 v[120:123], v[156:159], v[180:183], v[120:123]
	v_mfma_f32_16x16x32_bf16 v[108:111], v[148:151], v[188:191], v[108:111]
	v_mfma_f32_16x16x32_bf16 v[104:107], v[156:159], v[188:191], v[104:107]
	v_mfma_f32_16x16x32_bf16 v[92:95], v[148:151], v[196:199], v[92:95]
	v_mfma_f32_16x16x32_bf16 v[88:91], v[156:159], v[196:199], v[88:91]
	v_mfma_f32_16x16x32_bf16 v[76:79], v[148:151], v[206:209], v[76:79]
	v_mfma_f32_16x16x32_bf16 v[72:75], v[156:159], v[206:209], v[72:75]
	v_mfma_f32_16x16x32_bf16 v[124:127], v[152:155], v[184:187], v[124:127]
	v_mfma_f32_16x16x32_bf16 v[120:123], v[160:163], v[184:187], v[120:123]
	v_mfma_f32_16x16x32_bf16 v[108:111], v[152:155], v[192:195], v[108:111]
	v_mfma_f32_16x16x32_bf16 v[104:107], v[160:163], v[192:195], v[104:107]
	v_mfma_f32_16x16x32_bf16 v[92:95], v[152:155], v[202:205], v[92:95]
	v_mfma_f32_16x16x32_bf16 v[88:91], v[160:163], v[202:205], v[88:91]
	v_mfma_f32_16x16x32_bf16 v[76:79], v[152:155], v[210:213], v[76:79]
	v_mfma_f32_16x16x32_bf16 v[72:75], v[160:163], v[210:213], v[72:75]
	v_mfma_f32_16x16x32_bf16 v[116:119], v[164:167], v[180:183], v[116:119]
	v_mfma_f32_16x16x32_bf16 v[112:115], v[172:175], v[180:183], v[112:115]
	v_mfma_f32_16x16x32_bf16 v[100:103], v[164:167], v[188:191], v[100:103]
	v_mfma_f32_16x16x32_bf16 v[96:99], v[172:175], v[188:191], v[96:99]
	v_mfma_f32_16x16x32_bf16 v[84:87], v[164:167], v[196:199], v[84:87]
	v_mfma_f32_16x16x32_bf16 v[80:83], v[172:175], v[196:199], v[80:83]
	v_mfma_f32_16x16x32_bf16 v[68:71], v[164:167], v[206:209], v[68:71]
	v_mfma_f32_16x16x32_bf16 v[64:67], v[172:175], v[206:209], v[64:67]
	v_mfma_f32_16x16x32_bf16 v[116:119], v[168:171], v[184:187], v[116:119]
	v_mfma_f32_16x16x32_bf16 v[112:115], v[176:179], v[184:187], v[112:115]
	v_mfma_f32_16x16x32_bf16 v[100:103], v[168:171], v[192:195], v[100:103]
	v_mfma_f32_16x16x32_bf16 v[96:99], v[176:179], v[192:195], v[96:99]
	v_mfma_f32_16x16x32_bf16 v[84:87], v[168:171], v[202:205], v[84:87]
	v_mfma_f32_16x16x32_bf16 v[80:83], v[176:179], v[202:205], v[80:83]
	v_mfma_f32_16x16x32_bf16 v[68:71], v[168:171], v[210:213], v[68:71]
	v_mfma_f32_16x16x32_bf16 v[64:67], v[176:179], v[210:213], v[64:67]
	s_barrier
	s_add_i32 s26, s52, s38
	v_lshl_add_u64 v[214:215], v[214:215], 0, s[8:9]
	s_mov_b32 m0, s26
	ds_read_b128 v[180:183], v146 offset:49152
	ds_read_b128 v[184:187], v146 offset:50176
	ds_read_b128 v[188:191], v146 offset:51200
	ds_read_b128 v[192:195], v146 offset:52224
	ds_read_b128 v[196:199], v146 offset:53248
	ds_read_b128 v[202:205], v146 offset:54272
	ds_read_b128 v[206:209], v146 offset:55296
	ds_read_b128 v[210:213], v146 offset:56320
	global_load_lds_dwordx4 v[214:215], off
	s_add_i32 m0, s26, 0x2000
	s_add_u32 s24, s24, 0x200080
	v_lshl_add_u64 v[214:215], v[216:217], 0, s[8:9]
	s_addc_u32 s25, s25, 0
	s_add_i32 s26, s63, s38
	global_load_lds_dwordx4 v[214:215], off
	v_lshl_add_u64 v[214:215], s[24:25], 0, v[132:133]
	s_mov_b32 m0, s26
	s_nop 0
	global_load_lds_dwordx4 v[214:215], off
	v_lshl_add_u64 v[214:215], s[24:25], 0, v[128:129]
	s_add_i32 m0, s26, 0x2000
	s_nop 0
	global_load_lds_dwordx4 v[214:215], off
	s_waitcnt vmcnt(8)
	s_waitcnt lgkmcnt(0)
	s_barrier
	s_waitcnt lgkmcnt(0)
	v_mfma_f32_16x16x32_bf16 v[60:63], v[148:151], v[180:183], v[60:63]
	v_mfma_f32_16x16x32_bf16 v[56:59], v[156:159], v[180:183], v[56:59]
	v_mfma_f32_16x16x32_bf16 v[44:47], v[148:151], v[188:191], v[44:47]
	v_mfma_f32_16x16x32_bf16 v[40:43], v[156:159], v[188:191], v[40:43]
	v_mfma_f32_16x16x32_bf16 v[28:31], v[148:151], v[196:199], v[28:31]
	v_mfma_f32_16x16x32_bf16 v[24:27], v[156:159], v[196:199], v[24:27]
	v_mfma_f32_16x16x32_bf16 v[12:15], v[148:151], v[206:209], v[12:15]
	v_mfma_f32_16x16x32_bf16 v[8:11], v[156:159], v[206:209], v[8:11]
	v_mfma_f32_16x16x32_bf16 v[60:63], v[152:155], v[184:187], v[60:63]
	v_mfma_f32_16x16x32_bf16 v[56:59], v[160:163], v[184:187], v[56:59]
	v_mfma_f32_16x16x32_bf16 v[44:47], v[152:155], v[192:195], v[44:47]
	v_mfma_f32_16x16x32_bf16 v[40:43], v[160:163], v[192:195], v[40:43]
	v_mfma_f32_16x16x32_bf16 v[28:31], v[152:155], v[202:205], v[28:31]
	v_mfma_f32_16x16x32_bf16 v[24:27], v[160:163], v[202:205], v[24:27]
	v_mfma_f32_16x16x32_bf16 v[12:15], v[152:155], v[210:213], v[12:15]
	v_mfma_f32_16x16x32_bf16 v[8:11], v[160:163], v[210:213], v[8:11]
	v_mfma_f32_16x16x32_bf16 v[52:55], v[164:167], v[180:183], v[52:55]
	v_mfma_f32_16x16x32_bf16 v[48:51], v[172:175], v[180:183], v[48:51]
	v_mfma_f32_16x16x32_bf16 v[36:39], v[164:167], v[188:191], v[36:39]
	v_mfma_f32_16x16x32_bf16 v[32:35], v[172:175], v[188:191], v[32:35]
	v_mfma_f32_16x16x32_bf16 v[20:23], v[164:167], v[196:199], v[20:23]
	v_mfma_f32_16x16x32_bf16 v[16:19], v[172:175], v[196:199], v[16:19]
	v_mfma_f32_16x16x32_bf16 v[4:7], v[164:167], v[206:209], v[4:7]
	v_mfma_f32_16x16x32_bf16 v[0:3], v[172:175], v[206:209], v[0:3]
	v_mfma_f32_16x16x32_bf16 v[52:55], v[168:171], v[184:187], v[52:55]
	v_mfma_f32_16x16x32_bf16 v[48:51], v[176:179], v[184:187], v[48:51]
	v_mfma_f32_16x16x32_bf16 v[36:39], v[168:171], v[192:195], v[36:39]
	v_mfma_f32_16x16x32_bf16 v[32:35], v[176:179], v[192:195], v[32:35]
	v_mfma_f32_16x16x32_bf16 v[20:23], v[168:171], v[202:205], v[20:23]
	v_mfma_f32_16x16x32_bf16 v[16:19], v[176:179], v[202:205], v[16:19]
	v_mfma_f32_16x16x32_bf16 v[4:7], v[168:171], v[210:213], v[4:7]
	v_mfma_f32_16x16x32_bf16 v[0:3], v[176:179], v[210:213], v[0:3]
	s_waitcnt vmcnt(4)
	s_add_i32 s62, s62, 2
	s_add_u32 s22, s22, 0x100
	s_addc_u32 s23, s23, 0
	s_cmpk_gt_u32 s62, 0x7d
	s_barrier
	s_cbranch_scc0 .LBB0_2063
	s_setprio 0
	s_and_b64 vcc, exec, s[10:11]
	s_cbranch_vccz .LBB0_2066
	s_barrier
